# gdn_prep: batched X init + software-pipelined forward-substitution rows (7-deep L prefetch ring); GEMM K-loops: fragment reads reordered by first use with counted lgkmcnt waits
# speedup vs baseline: 1.0523x; 1.0088x over previous
; #define G3_LDA(buf, kt, i) __builtin_amdgcn_global_load_lds((const unsigned*)(ga + (size_t)((i) * 64) * lda + (kt) * 64), (lds_u32*)(sdst + (buf) * STAGE + (i) * 8192), 16, 0, 0)
; #define G3_LDB(buf, kt, i) __builtin_amdgcn_global_load_lds((const unsigned*)(gb + (size_t)((i) * 64) * ldb + (kt) * 64), (lds_u32*)(sdst + (buf) * STAGE + B_OFF + (i) * 8192), 16, 0, 0)
; DI void gemm3_mainloop(const int wave8, const int lane, const bf16_t* __restrict__ A, int lda, const bf16_t* __restrict__ Bt, int ldb, int K,
;                        unsigned char* smem, f32x4 (&acc)[8][4]) {
;     ...
;     asm volatile("s_waitcnt vmcnt(0)" ::: "memory");
;     G3_LDA(0, 0, 0); G3_LDA(0, 0, 1); G3_LDA(0, 0, 2); G3_LDA(0, 0, 3); G3_LDB(0, 0, 0); G3_LDB(0, 0, 1); G3_LDB(0, 0, 2); G3_LDB(0, 0, 3);
;     asm volatile("s_waitcnt vmcnt(0)" ::: "memory");
;     __builtin_amdgcn_s_barrier();
;     for (int kt = 0; kt < nk; kt += 2) { G3_STEP(0, 1, kt); G3_STEP(1, 0, kt + 1); }
.LBB0_90:
	ds_read_b128 v[128:131], v148 offset:32768
	ds_read_b128 v[168:171], v149
	ds_read_b128 v[156:159], v148 offset:34816
	ds_read_b128 v[160:163], v148 offset:36864
	ds_read_b128 v[164:167], v148 offset:38912
	ds_read_b128 v[172:175], v149 offset:2048
	ds_read_b128 v[176:179], v149 offset:4096
	ds_read_b128 v[180:183], v149 offset:6144
	ds_read_b128 v[184:187], v149 offset:8192
	ds_read_b128 v[188:191], v149 offset:10240
	ds_read_b128 v[192:195], v149 offset:12288
	ds_read_b128 v[196:199], v149 offset:14336
	s_waitcnt lgkmcnt(10)
	v_mfma_f32_16x16x32_bf16 v[112:115], v[128:131], v[168:171], v[112:115]
	s_mov_b64 s[8:9], 0x19dc5080
	s_mov_b32 m0, s88
	s_add_i32 s18, s6, 1
	s_waitcnt lgkmcnt(9)
	v_mfma_f32_16x16x32_bf16 v[124:127], v[156:159], v[168:171], v[124:127]
	s_add_i32 s7, s6, 2
	s_cmp_lt_u32 s6, 30
	s_waitcnt lgkmcnt(8)
	v_mfma_f32_16x16x32_bf16 v[120:123], v[160:163], v[168:171], v[120:123]
	s_waitcnt lgkmcnt(7)
	v_mfma_f32_16x16x32_bf16 v[116:119], v[164:167], v[168:171], v[116:119]
	v_lshl_add_u64 v[168:169], v[138:139], 0, v[132:133]
	v_lshl_add_u64 v[170:171], v[168:169], 0, s[8:9]
	s_mov_b64 s[8:9], 0x19e07080
	global_load_lds_dwordx4 v[170:171], off
	v_lshl_add_u64 v[170:171], v[168:169], 0, s[8:9]
	s_mov_b32 m0, s92
	s_mov_b64 s[8:9], 0x19e49080
	s_waitcnt lgkmcnt(6)
	v_mfma_f32_16x16x32_bf16 v[96:99], v[128:131], v[172:175], v[96:99]
	v_lshl_add_u64 v[138:139], v[138:139], 0, s[34:35]
	v_mfma_f32_16x16x32_bf16 v[108:111], v[156:159], v[172:175], v[108:111]
	v_mfma_f32_16x16x32_bf16 v[104:107], v[160:163], v[172:175], v[104:107]
	v_mfma_f32_16x16x32_bf16 v[100:103], v[164:167], v[172:175], v[100:103]
	global_load_lds_dwordx4 v[170:171], off
	v_lshl_add_u64 v[170:171], v[168:169], 0, s[8:9]
	s_mov_b32 m0, s93
	s_mov_b64 s[8:9], 0x19e8b080
	s_waitcnt lgkmcnt(5)
	v_mfma_f32_16x16x32_bf16 v[80:83], v[128:131], v[176:179], v[80:83]
	v_lshl_add_u64 v[168:169], v[168:169], 0, s[8:9]
	s_mov_b64 s[8:9], 0x245080
	v_mfma_f32_16x16x32_bf16 v[92:95], v[156:159], v[176:179], v[92:95]
	v_mfma_f32_16x16x32_bf16 v[88:91], v[160:163], v[176:179], v[88:91]
	v_mfma_f32_16x16x32_bf16 v[84:87], v[164:167], v[176:179], v[84:87]
	global_load_lds_dwordx4 v[170:171], off
	s_mov_b32 m0, s94
	s_waitcnt lgkmcnt(4)
	v_mfma_f32_16x16x32_bf16 v[64:67], v[128:131], v[180:183], v[64:67]
	v_mfma_f32_16x16x32_bf16 v[76:79], v[156:159], v[180:183], v[76:79]
	v_mfma_f32_16x16x32_bf16 v[72:75], v[160:163], v[180:183], v[72:75]
	v_mfma_f32_16x16x32_bf16 v[68:71], v[164:167], v[180:183], v[68:71]
	global_load_lds_dwordx4 v[168:169], off
	s_mov_b32 m0, s89
	s_waitcnt lgkmcnt(3)
	v_mfma_f32_16x16x32_bf16 v[48:51], v[128:131], v[184:187], v[48:51]
	v_mfma_f32_16x16x32_bf16 v[60:63], v[156:159], v[184:187], v[60:63]
	v_mfma_f32_16x16x32_bf16 v[56:59], v[160:163], v[184:187], v[56:59]
	v_mfma_f32_16x16x32_bf16 v[52:55], v[164:167], v[184:187], v[52:55]
	s_waitcnt lgkmcnt(2)
	v_mfma_f32_16x16x32_bf16 v[32:35], v[128:131], v[188:191], v[32:35]
	v_mfma_f32_16x16x32_bf16 v[44:47], v[156:159], v[188:191], v[44:47]
	v_mfma_f32_16x16x32_bf16 v[40:43], v[160:163], v[188:191], v[40:43]
	v_mfma_f32_16x16x32_bf16 v[36:39], v[164:167], v[188:191], v[36:39]
	s_waitcnt lgkmcnt(1)
	v_mfma_f32_16x16x32_bf16 v[12:15], v[128:131], v[192:195], v[12:15]
	v_mfma_f32_16x16x32_bf16 v[24:27], v[156:159], v[192:195], v[24:27]
	v_mfma_f32_16x16x32_bf16 v[20:23], v[160:163], v[192:195], v[20:23]
	v_mfma_f32_16x16x32_bf16 v[16:19], v[164:167], v[192:195], v[16:19]
	s_waitcnt lgkmcnt(0)
	v_mfma_f32_16x16x32_bf16 v[0:3], v[128:131], v[196:199], v[0:3]
	v_mfma_f32_16x16x32_bf16 v[8:11], v[156:159], v[196:199], v[8:11]
	v_mfma_f32_16x16x32_bf16 v[4:7], v[160:163], v[196:199], v[4:7]
	v_mfma_f32_16x16x32_bf16 v[28:31], v[164:167], v[196:199], v[28:31]
	ds_read_b128 v[128:131], v150 offset:32768
	ds_read_b128 v[168:171], v151
	ds_read_b128 v[156:159], v150 offset:34816
	ds_read_b128 v[160:163], v150 offset:36864
	ds_read_b128 v[164:167], v150 offset:38912
	ds_read_b128 v[172:175], v151 offset:2048
	ds_read_b128 v[176:179], v151 offset:4096
	ds_read_b128 v[180:183], v151 offset:6144
	ds_read_b128 v[184:187], v151 offset:8192
	ds_read_b128 v[188:191], v151 offset:10240
	ds_read_b128 v[192:195], v151 offset:12288
	ds_read_b128 v[196:199], v151 offset:14336
	s_waitcnt lgkmcnt(10)
	v_mfma_f32_16x16x32_bf16 v[112:115], v[128:131], v[168:171], v[112:115]
	s_waitcnt lgkmcnt(9)
	v_mfma_f32_16x16x32_bf16 v[124:127], v[156:159], v[168:171], v[124:127]
	s_waitcnt lgkmcnt(8)
	v_mfma_f32_16x16x32_bf16 v[120:123], v[160:163], v[168:171], v[120:123]
	s_waitcnt lgkmcnt(7)
	v_mfma_f32_16x16x32_bf16 v[116:119], v[164:167], v[168:171], v[116:119]
	v_lshl_add_u64 v[168:169], v[140:141], 0, v[132:133]
	v_lshl_add_u64 v[170:171], v[168:169], 0, s[8:9]
	s_mov_b64 s[8:9], 0x287080
	global_load_lds_dwordx4 v[170:171], off
	v_lshl_add_u64 v[170:171], v[168:169], 0, s[8:9]
	s_mov_b32 m0, s95
	s_waitcnt lgkmcnt(6)
	v_mfma_f32_16x16x32_bf16 v[96:99], v[128:131], v[172:175], v[96:99]
	s_cselect_b64 s[8:9], -1, 0
	s_and_b64 vcc, s[8:9], exec
	s_cselect_b32 s6, s7, s18
	v_mfma_f32_16x16x32_bf16 v[108:111], v[156:159], v[172:175], v[108:111]
	s_lshl_b32 s18, s6, 7
	v_lshl_add_u64 v[140:141], v[140:141], 0, s[34:35]
	s_mov_b32 s6, s7
	v_mfma_f32_16x16x32_bf16 v[104:107], v[160:163], v[172:175], v[104:107]
	v_mfma_f32_16x16x32_bf16 v[100:103], v[164:167], v[172:175], v[100:103]
	global_load_lds_dwordx4 v[170:171], off
	v_lshl_add_u64 v[170:171], v[168:169], 0, s[28:29]
	s_mov_b32 m0, s96
	s_waitcnt lgkmcnt(5)
	v_mfma_f32_16x16x32_bf16 v[80:83], v[128:131], v[176:179], v[80:83]
	v_lshl_add_u64 v[168:169], v[168:169], 0, s[30:31]
	v_mfma_f32_16x16x32_bf16 v[92:95], v[156:159], v[176:179], v[92:95]
	v_mfma_f32_16x16x32_bf16 v[88:91], v[160:163], v[176:179], v[88:91]
	v_mfma_f32_16x16x32_bf16 v[84:87], v[164:167], v[176:179], v[84:87]
	global_load_lds_dwordx4 v[170:171], off
	s_mov_b32 m0, s97
	s_waitcnt lgkmcnt(4)
	v_mfma_f32_16x16x32_bf16 v[64:67], v[128:131], v[180:183], v[64:67]
	v_mfma_f32_16x16x32_bf16 v[76:79], v[156:159], v[180:183], v[76:79]
	v_mfma_f32_16x16x32_bf16 v[72:75], v[160:163], v[180:183], v[72:75]
	v_mfma_f32_16x16x32_bf16 v[68:71], v[164:167], v[180:183], v[68:71]
	global_load_lds_dwordx4 v[168:169], off
	s_waitcnt vmcnt(0)
	s_waitcnt lgkmcnt(3)
	v_mfma_f32_16x16x32_bf16 v[48:51], v[128:131], v[184:187], v[48:51]
	s_barrier
; #define G3_LDA(buf, kt, i) __builtin_amdgcn_global_load_lds((const unsigned*)(ga + (size_t)((i) * 64) * lda + (kt) * 64), (lds_u32*)(sdst + (buf) * STAGE + (i) * 8192), 16, 0, 0)
; #define G3_LDB(buf, kt, i) __builtin_amdgcn_global_load_lds((const unsigned*)(gb + (size_t)((i) * 64) * ldb + (kt) * 64), (lds_u32*)(sdst + (buf) * STAGE + B_OFF + (i) * 8192), 16, 0, 0)
; DI void gemm3_mainloop(const int wave8, const int lane, const bf16_t* __restrict__ A, int lda, const bf16_t* __restrict__ Bt, int ldb, int K,
;                        unsigned char* smem, f32x4 (&acc)[8][4]) {
;     ...
;     asm volatile("s_waitcnt vmcnt(0)" ::: "memory");
;     G3_LDA(0, 0, 0); G3_LDA(0, 0, 1); G3_LDA(0, 0, 2); G3_LDA(0, 0, 3); G3_LDB(0, 0, 0); G3_LDB(0, 0, 1); G3_LDB(0, 0, 2); G3_LDB(0, 0, 3);
;     asm volatile("s_waitcnt vmcnt(0)" ::: "memory");
;     __builtin_amdgcn_s_barrier();
;     for (int kt = 0; kt < nk; kt += 2) { G3_STEP(0, 1, kt); G3_STEP(1, 0, kt + 1); }
	s_mov_b32 m0, s0
	v_mfma_f32_16x16x32_bf16 v[60:63], v[156:159], v[184:187], v[60:63]
	v_mfma_f32_16x16x32_bf16 v[56:59], v[160:163], v[184:187], v[56:59]
	v_mfma_f32_16x16x32_bf16 v[52:55], v[164:167], v[184:187], v[52:55]
	s_waitcnt lgkmcnt(2)
	v_mfma_f32_16x16x32_bf16 v[32:35], v[128:131], v[188:191], v[32:35]
	v_mfma_f32_16x16x32_bf16 v[44:47], v[156:159], v[188:191], v[44:47]
	v_mfma_f32_16x16x32_bf16 v[40:43], v[160:163], v[188:191], v[40:43]
	v_mfma_f32_16x16x32_bf16 v[36:39], v[164:167], v[188:191], v[36:39]
	s_waitcnt lgkmcnt(1)
	v_mfma_f32_16x16x32_bf16 v[12:15], v[128:131], v[192:195], v[12:15]
	v_mfma_f32_16x16x32_bf16 v[24:27], v[156:159], v[192:195], v[24:27]
	v_mfma_f32_16x16x32_bf16 v[20:23], v[160:163], v[192:195], v[20:23]
	v_mfma_f32_16x16x32_bf16 v[16:19], v[164:167], v[192:195], v[16:19]
	s_waitcnt lgkmcnt(0)
	v_mfma_f32_16x16x32_bf16 v[0:3], v[128:131], v[196:199], v[0:3]
	v_mfma_f32_16x16x32_bf16 v[8:11], v[156:159], v[196:199], v[8:11]
	v_mfma_f32_16x16x32_bf16 v[4:7], v[160:163], v[196:199], v[4:7]
	v_mfma_f32_16x16x32_bf16 v[28:31], v[164:167], v[196:199], v[28:31]
	ds_read_b128 v[128:131], v152
	ds_read_b128 v[168:171], v153
	ds_read_b128 v[156:159], v152 offset:2048
	ds_read_b128 v[160:163], v152 offset:4096
	ds_read_b128 v[164:167], v152 offset:6144
	ds_read_b128 v[172:175], v153 offset:2048
	ds_read_b128 v[176:179], v153 offset:4096
	ds_read_b128 v[180:183], v153 offset:6144
	ds_read_b128 v[184:187], v153 offset:8192
	ds_read_b128 v[188:191], v153 offset:10240
	ds_read_b128 v[192:195], v153 offset:12288
	ds_read_b128 v[196:199], v153 offset:14336
	s_waitcnt lgkmcnt(10)
	v_mfma_f32_16x16x32_bf16 v[112:115], v[128:131], v[168:171], v[112:115]
	s_waitcnt lgkmcnt(9)
	v_mfma_f32_16x16x32_bf16 v[124:127], v[156:159], v[168:171], v[124:127]
	s_waitcnt lgkmcnt(8)
	v_mfma_f32_16x16x32_bf16 v[120:123], v[160:163], v[168:171], v[120:123]
	s_waitcnt lgkmcnt(7)
	v_mfma_f32_16x16x32_bf16 v[116:119], v[164:167], v[168:171], v[116:119]
	v_lshl_add_u64 v[168:169], v[134:135], 0, s[18:19]
	global_load_lds_dwordx4 v[168:169], off
	v_lshl_add_u64 v[170:171], v[168:169], 0, s[22:23]
	s_mov_b32 m0, s55
	s_waitcnt lgkmcnt(6)
	v_mfma_f32_16x16x32_bf16 v[96:99], v[128:131], v[172:175], v[96:99]
	v_mfma_f32_16x16x32_bf16 v[108:111], v[156:159], v[172:175], v[108:111]
	v_mfma_f32_16x16x32_bf16 v[104:107], v[160:163], v[172:175], v[104:107]
	v_mfma_f32_16x16x32_bf16 v[100:103], v[164:167], v[172:175], v[100:103]
	global_load_lds_dwordx4 v[170:171], off
	v_lshl_add_u64 v[170:171], v[168:169], 0, s[24:25]
	s_mov_b32 m0, s87
	s_waitcnt lgkmcnt(5)
	v_mfma_f32_16x16x32_bf16 v[80:83], v[128:131], v[176:179], v[80:83]
	v_lshl_add_u64 v[168:169], v[168:169], 0, s[26:27]
	v_mfma_f32_16x16x32_bf16 v[92:95], v[156:159], v[176:179], v[92:95]
	v_mfma_f32_16x16x32_bf16 v[88:91], v[160:163], v[176:179], v[88:91]
	v_mfma_f32_16x16x32_bf16 v[84:87], v[164:167], v[176:179], v[84:87]
	global_load_lds_dwordx4 v[170:171], off
	s_mov_b32 m0, s69
	s_waitcnt lgkmcnt(4)
	v_mfma_f32_16x16x32_bf16 v[64:67], v[128:131], v[180:183], v[64:67]
	v_mfma_f32_16x16x32_bf16 v[76:79], v[156:159], v[180:183], v[76:79]
	v_mfma_f32_16x16x32_bf16 v[72:75], v[160:163], v[180:183], v[72:75]
	v_mfma_f32_16x16x32_bf16 v[68:71], v[164:167], v[180:183], v[68:71]
	global_load_lds_dwordx4 v[168:169], off
	s_mov_b32 m0, s68
	s_waitcnt lgkmcnt(3)
	v_mfma_f32_16x16x32_bf16 v[48:51], v[128:131], v[184:187], v[48:51]
	v_mfma_f32_16x16x32_bf16 v[60:63], v[156:159], v[184:187], v[60:63]
	v_mfma_f32_16x16x32_bf16 v[56:59], v[160:163], v[184:187], v[56:59]
	v_mfma_f32_16x16x32_bf16 v[52:55], v[164:167], v[184:187], v[52:55]
	s_waitcnt lgkmcnt(2)
	v_mfma_f32_16x16x32_bf16 v[32:35], v[128:131], v[188:191], v[32:35]
	v_mfma_f32_16x16x32_bf16 v[44:47], v[156:159], v[188:191], v[44:47]
	v_mfma_f32_16x16x32_bf16 v[40:43], v[160:163], v[188:191], v[40:43]
	v_mfma_f32_16x16x32_bf16 v[36:39], v[164:167], v[188:191], v[36:39]
	s_waitcnt lgkmcnt(1)
	v_mfma_f32_16x16x32_bf16 v[12:15], v[128:131], v[192:195], v[12:15]
	v_mfma_f32_16x16x32_bf16 v[24:27], v[156:159], v[192:195], v[24:27]
	v_mfma_f32_16x16x32_bf16 v[20:23], v[160:163], v[192:195], v[20:23]
	v_mfma_f32_16x16x32_bf16 v[16:19], v[164:167], v[192:195], v[16:19]
	s_waitcnt lgkmcnt(0)
	v_mfma_f32_16x16x32_bf16 v[0:3], v[128:131], v[196:199], v[0:3]
	v_mfma_f32_16x16x32_bf16 v[8:11], v[156:159], v[196:199], v[8:11]
	v_mfma_f32_16x16x32_bf16 v[4:7], v[160:163], v[196:199], v[4:7]
	v_mfma_f32_16x16x32_bf16 v[28:31], v[164:167], v[196:199], v[28:31]
	ds_read_b128 v[156:159], v154
	ds_read_b128 v[168:171], v155
	ds_read_b128 v[160:163], v154 offset:2048
	ds_read_b128 v[164:167], v154 offset:4096
	ds_read_b128 v[128:131], v154 offset:6144
	ds_read_b128 v[172:175], v155 offset:2048
	ds_read_b128 v[176:179], v155 offset:4096
	ds_read_b128 v[180:183], v155 offset:6144
	ds_read_b128 v[184:187], v155 offset:8192
	ds_read_b128 v[188:191], v155 offset:10240
	ds_read_b128 v[192:195], v155 offset:12288
	ds_read_b128 v[196:199], v155 offset:14336
	s_waitcnt lgkmcnt(10)
	v_mfma_f32_16x16x32_bf16 v[112:115], v[156:159], v[168:171], v[112:115]
	s_waitcnt lgkmcnt(9)
	v_mfma_f32_16x16x32_bf16 v[124:127], v[160:163], v[168:171], v[124:127]
	s_waitcnt lgkmcnt(8)
	v_mfma_f32_16x16x32_bf16 v[120:123], v[164:167], v[168:171], v[120:123]
	s_waitcnt lgkmcnt(7)
	v_mfma_f32_16x16x32_bf16 v[116:119], v[128:131], v[168:171], v[116:119]
	v_lshl_add_u64 v[168:169], v[136:137], 0, s[18:19]
	global_load_lds_dwordx4 v[168:169], off
	v_lshl_add_u64 v[170:171], v[168:169], 0, s[22:23]
	s_mov_b32 m0, s39
	s_waitcnt lgkmcnt(6)
	v_mfma_f32_16x16x32_bf16 v[96:99], v[156:159], v[172:175], v[96:99]
	v_mfma_f32_16x16x32_bf16 v[108:111], v[160:163], v[172:175], v[108:111]
	v_mfma_f32_16x16x32_bf16 v[104:107], v[164:167], v[172:175], v[104:107]
	v_mfma_f32_16x16x32_bf16 v[100:103], v[128:131], v[172:175], v[100:103]
	global_load_lds_dwordx4 v[170:171], off
	v_lshl_add_u64 v[170:171], v[168:169], 0, s[24:25]
	s_mov_b32 m0, s38
	s_waitcnt lgkmcnt(5)
	v_mfma_f32_16x16x32_bf16 v[80:83], v[156:159], v[176:179], v[80:83]
	v_lshl_add_u64 v[168:169], v[168:169], 0, s[26:27]
	v_mfma_f32_16x16x32_bf16 v[92:95], v[160:163], v[176:179], v[92:95]
	v_mfma_f32_16x16x32_bf16 v[88:91], v[164:167], v[176:179], v[88:91]
	v_mfma_f32_16x16x32_bf16 v[84:87], v[128:131], v[176:179], v[84:87]
	global_load_lds_dwordx4 v[170:171], off
	s_mov_b32 m0, s1
	s_waitcnt lgkmcnt(4)
	v_mfma_f32_16x16x32_bf16 v[64:67], v[156:159], v[180:183], v[64:67]
	v_mfma_f32_16x16x32_bf16 v[76:79], v[160:163], v[180:183], v[76:79]
	v_mfma_f32_16x16x32_bf16 v[72:75], v[164:167], v[180:183], v[72:75]
	v_mfma_f32_16x16x32_bf16 v[68:71], v[128:131], v[180:183], v[68:71]
	global_load_lds_dwordx4 v[168:169], off
	s_waitcnt vmcnt(0)
	s_waitcnt lgkmcnt(3)
	v_mfma_f32_16x16x32_bf16 v[48:51], v[156:159], v[184:187], v[48:51]
	s_barrier
; DI unsigned pk2(float a, float b) { f2_t v = {a, b}; bf2_t r = __builtin_convertvector(v, bf2_t); return __builtin_bit_cast(unsigned, r); }
; #define G3_LDA(buf, kt, i) __builtin_amdgcn_global_load_lds((const unsigned*)(ga + (size_t)((i) * 64) * lda + (kt) * 64), (lds_u32*)(sdst + (buf) * STAGE + (i) * 8192), 16, 0, 0)
; #define G3_LDB(buf, kt, i) __builtin_amdgcn_global_load_lds((const unsigned*)(gb + (size_t)((i) * 64) * ldb + (kt) * 64), (lds_u32*)(sdst + (buf) * STAGE + B_OFF + (i) * 8192), 16, 0, 0)
; DI void gemm3_mainloop(const int wave8, const int lane, const bf16_t* __restrict__ A, int lda, const bf16_t* __restrict__ Bt, int ldb, int K,
;                        unsigned char* smem, f32x4 (&acc)[8][4]) {
;     ...
;     asm volatile("s_waitcnt vmcnt(0)" ::: "memory");
;     G3_LDA(0, 0, 0); G3_LDA(0, 0, 1); G3_LDA(0, 0, 2); G3_LDA(0, 0, 3); G3_LDB(0, 0, 0); G3_LDB(0, 0, 1); G3_LDB(0, 0, 2); G3_LDB(0, 0, 3);
;     asm volatile("s_waitcnt vmcnt(0)" ::: "memory");
;     __builtin_amdgcn_s_barrier();
;     for (int kt = 0; kt < nk; kt += 2) { G3_STEP(0, 1, kt); G3_STEP(1, 0, kt + 1); }
; DI void phase1(const Params& p, unsigned char* smem) {
;     ...
;         const int c128 = nt * 2 + (wn >> 1);
;         if (c128 >= 47) return;
;         bf16_t* dst; int ld, c0;
;         if (c128 < 23) { dst = pa; ld = LDPA; c0 = c128 * 128; } else { dst = pb; ld = LDPB; c0 = (c128 - 23) * 128; }
; #pragma unroll
;         for (int i = 0; i < 8; ++i) {
;             const int m = mt * 256 + wm * 128 + i * 16 + fr;
;             float ss = 0.f;
; #pragma unroll
;             for (int j = 0; j < 4; ++j) {
;                 const f32x4 v = acc[i][j];
;                 ss += v.x * v.x + v.y * v.y + v.z * v.z + v.w * v.w;
;                 u32x2 o; o.x = pk2(v.x, v.y); o.y = pk2(v.z, v.w);
;                 *(u32x2*)(dst + (size_t)m * ld + c0 + (wn & 1) * 64 + j * 16 + fq * 4) = o;
;             }
;             if (c128 < 6) {
;                 ss += __shfl_xor(ss, 16); ss += __shfl_xor(ss, 32);
;                 if (fq == 0) atomicAdd(ssq + (c128 < 4 ? 0 : T_) + m, ss);
	v_mfma_f32_16x16x32_bf16 v[60:63], v[160:163], v[184:187], v[60:63]
	v_mfma_f32_16x16x32_bf16 v[56:59], v[164:167], v[184:187], v[56:59]
	v_mfma_f32_16x16x32_bf16 v[52:55], v[128:131], v[184:187], v[52:55]
	s_waitcnt lgkmcnt(2)
	v_mfma_f32_16x16x32_bf16 v[32:35], v[156:159], v[188:191], v[32:35]
	v_mfma_f32_16x16x32_bf16 v[44:47], v[160:163], v[188:191], v[44:47]
	v_mfma_f32_16x16x32_bf16 v[40:43], v[164:167], v[188:191], v[40:43]
	v_mfma_f32_16x16x32_bf16 v[36:39], v[128:131], v[188:191], v[36:39]
	s_waitcnt lgkmcnt(1)
	v_mfma_f32_16x16x32_bf16 v[12:15], v[156:159], v[192:195], v[12:15]
	v_mfma_f32_16x16x32_bf16 v[24:27], v[160:163], v[192:195], v[24:27]
	v_mfma_f32_16x16x32_bf16 v[20:23], v[164:167], v[192:195], v[20:23]
	v_mfma_f32_16x16x32_bf16 v[16:19], v[128:131], v[192:195], v[16:19]
	s_waitcnt lgkmcnt(0)
	v_mfma_f32_16x16x32_bf16 v[0:3], v[156:159], v[196:199], v[0:3]
	v_mfma_f32_16x16x32_bf16 v[8:11], v[160:163], v[196:199], v[8:11]
	v_mfma_f32_16x16x32_bf16 v[4:7], v[164:167], v[196:199], v[4:7]
	v_mfma_f32_16x16x32_bf16 v[28:31], v[128:131], v[196:199], v[28:31]
	s_cbranch_vccnz .LBB0_90
	s_lshl_b32 s5, s5, 1
	s_or_b32 s36, s5, s44
	s_cmp_gt_i32 s36, 46
	s_cbranch_scc1 .LBB0_88
	s_lshl_b32 s5, s36, 7
	s_add_i32 s6, s5, 0xfffff480
	s_cmp_lt_i32 s36, 23
	s_cselect_b32 s6, s5, s6
	s_cselect_b32 s5, s48, 0xddc5000
	s_cselect_b32 s75, s46, 0xc00
	s_add_u32 s8, s72, s5
	s_addc_u32 s9, s73, 0
	s_lshl_b32 s4, s4, 8
	s_add_i32 s4, s4, s54
	s_ashr_i32 s7, s6, 31
	v_and_or_b32 v130, v147, 15, s4
	s_lshl_b64 s[4:5], s[6:7], 1
	s_add_u32 s4, s8, s4
	s_addc_u32 s5, s9, s5
	s_add_u32 s4, s4, s49
	s_addc_u32 s5, s5, 0
	v_lshlrev_b32_e32 v132, 3, v145
	v_lshl_add_u64 v[128:129], s[4:5], 0, v[132:133]
	v_mov_b32_e32 v132, v130
	v_mad_u64_u32 v[130:131], s[4:5], s75, v130, 0
	v_lshl_add_u64 v[130:131], v[130:131], 1, v[128:129]
	v_cvt_pk_bf16_f32 v134, v112, v113
	v_cvt_pk_bf16_f32 v135, v114, v115
	s_cmp_lt_i32 s36, 6
	global_store_dwordx2 v[130:131], v[134:135], off
	v_cvt_pk_bf16_f32 v134, v124, v125
	v_cvt_pk_bf16_f32 v135, v126, v127
	s_cselect_b64 s[6:7], -1, 0
	s_cmp_lt_i32 s36, 4
	global_store_dwordx2 v[130:131], v[134:135], off offset:32
	v_cvt_pk_bf16_f32 v134, v120, v121
	v_cvt_pk_bf16_f32 v135, v122, v123
	s_cselect_b32 s18, 0, 0x8000
	s_cmp_gt_i32 s36, 5
	v_cmp_gt_u32_e64 s[8:9], 16, v146
	global_store_dwordx2 v[130:131], v[134:135], off offset:64
	v_cvt_pk_bf16_f32 v134, v116, v117
	v_cvt_pk_bf16_f32 v135, v118, v119
	global_store_dwordx2 v[130:131], v[134:135], off offset:96
	s_cbranch_scc1 .LBB0_96
	v_mul_f32_e32 v130, v113, v113
	v_mul_f32_e32 v125, v125, v125
	v_fmac_f32_e32 v130, v112, v112
	v_fmac_f32_e32 v125, v124, v124
	v_mul_f32_e32 v121, v121, v121
	v_fmac_f32_e32 v130, v114, v114
	v_fmac_f32_e32 v125, v126, v126
	v_fmac_f32_e32 v121, v120, v120
	v_mul_f32_e32 v117, v117, v117
	v_fmac_f32_e32 v130, v115, v115
	v_fmac_f32_e32 v125, v127, v127
	v_fmac_f32_e32 v121, v122, v122
	v_fmac_f32_e32 v117, v116, v116
	v_add_f32_e32 v124, v130, v125
	v_fmac_f32_e32 v121, v123, v123
	v_fmac_f32_e32 v117, v118, v118
	v_add_f32_e32 v120, v124, v121
	v_fmac_f32_e32 v117, v119, v119
	v_add_f32_e32 v116, v120, v117
	ds_bpermute_b32 v117, v144, v116
	s_waitcnt lgkmcnt(0)
	v_add_f32_e32 v116, v116, v117
	ds_bpermute_b32 v117, v241, v116
	s_and_saveexec_b64 s[4:5], s[8:9]
	s_cbranch_execz .LBB0_95
	s_lshl_b32 s37, s18, 2
	s_add_u32 s76, s12, s37
	s_addc_u32 s77, s13, 0
	s_waitcnt lgkmcnt(0)
	v_add_f32_e32 v118, v116, v117
	v_lshl_add_u64 v[116:117], v[132:133], 2, s[76:77]
	v_add_f32_e32 v118, 0x45400000, v118
	v_subrev_f32_e32 v118, 0x45400000, v118
	global_atomic_add_f32 v[116:117], v118, off

; DI bf16_t f2bf(float a) { return (bf16_t)(pk2(a, 0.f) & 0xffffu); }
; DI float bf2f(bf16_t v) { return __uint_as_float(((unsigned)v) << 16); }
; DI int crow(int e, int h) { return (e & 3) + 8 * (e >> 2) + 4 * h; }
; DI void gdn_prep(const Params& p, int item, unsigned char* smem) {
;     ...
;         const int j = tj * 32 + r; const float gcj = sgc[j];
; #pragma unroll
;         for (int e = 0; e < 16; ++e) {
;             const int c = ti * 32 + crow(e, h);
;             const float dec = c >= j ? expf(sgc[c] - gcj) : 0.f;
;             sL[c * 68 + j] = c > j ? sbeta[c] * akk[e] * dec : 0.f;
;             ag[c * 64 + j] = f2bf(aqk[e] * dec);
;         }
;     }
;     __syncthreads();
;     {
;         float X[64];
;         const bf16_t* src = tid < 128 ? (sv + tid) : (sk + tid - 128);
; #pragma unroll
;         for (int i = 0; i < 64; ++i) { float a = bf2f(src[i * 136]) * sbeta[i]; if (tid >= 128) a *= segc[i]; X[i] = a; }
.LBB0_279:
	s_or_b64 exec, exec, s[4:5]
	ds_write_b32 v0, v2 offset:52496
	v_mul_f32_e32 v0, v15, v3
	v_cvt_pk_bf16_f32 v2, v0, s0
	v_lshl_add_u32 v0, v1, 6, v33
	s_add_u32 s4, s72, s36
	v_ashrrev_i32_e32 v1, 31, v0
	s_addc_u32 s5, s73, s37
	v_lshl_add_u64 v[0:1], v[0:1], 1, s[4:5]
	s_mov_b32 s4, 0x3a1c5000
	v_add_co_u32_e32 v0, vcc, s4, v0
	s_movk_i32 s4, 0x80
	s_nop 0
	v_addc_co_u32_e32 v1, vcc, 0, v1, vcc
	v_cmp_gt_i32_e32 vcc, s4, v46
	global_store_short v[0:1], v2, off
	v_lshl_add_u32 v0, v46, 1, s10
	v_cndmask_b32_e32 v1, v205, v206, vcc
	v_add_u32_e32 v0, v0, v1
	v_mov_b32_e32 v1, s49
	s_waitcnt lgkmcnt(0)
	s_barrier
	s_movk_i32 s4, 0x7f
	v_cmp_lt_i32_e32 vcc, s4, v46
	v_mov_b32_e32 v84, s49
	ds_read_u16 v2, v0
	ds_read_u16 v3, v0 offset:272
	ds_read_u16 v5, v0 offset:544
	ds_read_u16 v6, v0 offset:816
	ds_read_u16 v7, v0 offset:1088
	ds_read_u16 v8, v0 offset:1360
	ds_read_u16 v9, v0 offset:1632
	ds_read_u16 v10, v0 offset:1904
	ds_read_b128 v[88:91], v84 offset:0
	ds_read_b128 v[92:95], v84 offset:16
	ds_read_b128 v[96:99], v84 offset:256
	ds_read_b128 v[100:103], v84 offset:272
	s_waitcnt lgkmcnt(0)
	v_lshlrev_b32_e32 v2, 16, v2
	v_cndmask_b32_e32 v104, 1.0, v96, vcc
	v_lshlrev_b32_e32 v3, 16, v3
	v_cndmask_b32_e32 v105, 1.0, v97, vcc
	v_lshlrev_b32_e32 v5, 16, v5
	v_cndmask_b32_e32 v106, 1.0, v98, vcc
	v_lshlrev_b32_e32 v6, 16, v6
	v_cndmask_b32_e32 v107, 1.0, v99, vcc
	v_lshlrev_b32_e32 v7, 16, v7
	v_cndmask_b32_e32 v108, 1.0, v100, vcc
	v_lshlrev_b32_e32 v8, 16, v8
	v_cndmask_b32_e32 v109, 1.0, v101, vcc
	v_lshlrev_b32_e32 v9, 16, v9
	v_cndmask_b32_e32 v110, 1.0, v102, vcc
	v_lshlrev_b32_e32 v10, 16, v10
	v_cndmask_b32_e32 v111, 1.0, v103, vcc
	v_mul_f32_e32 v2, v88, v2
	v_mul_f32_e32 v3, v89, v3
	v_mul_f32_e32 v5, v90, v5
	v_mul_f32_e32 v6, v91, v6
	v_mul_f32_e32 v7, v92, v7
	v_mul_f32_e32 v8, v93, v8
	v_mul_f32_e32 v9, v94, v9
	v_mul_f32_e32 v10, v95, v10
	v_mul_f32_e32 v2, v2, v104
	v_mul_f32_e32 v3, v3, v105
	v_mul_f32_e32 v5, v5, v106
	v_mul_f32_e32 v6, v6, v107
	v_mul_f32_e32 v7, v7, v108
	v_mul_f32_e32 v8, v8, v109
	v_mul_f32_e32 v9, v9, v110
	v_mul_f32_e32 v10, v10, v111
	ds_read_u16 v11, v0 offset:2176
	ds_read_u16 v12, v0 offset:2448
	ds_read_u16 v13, v0 offset:2720
	ds_read_u16 v14, v0 offset:2992
	ds_read_u16 v15, v0 offset:3264
	ds_read_u16 v16, v0 offset:3536
	ds_read_u16 v66, v0 offset:3808
	ds_read_u16 v17, v0 offset:4080
	ds_read_b128 v[88:91], v84 offset:32
	ds_read_b128 v[92:95], v84 offset:48
	ds_read_b128 v[96:99], v84 offset:288
	ds_read_b128 v[100:103], v84 offset:304
	s_waitcnt lgkmcnt(0)
	v_lshlrev_b32_e32 v11, 16, v11
	v_cndmask_b32_e32 v104, 1.0, v96, vcc
	v_lshlrev_b32_e32 v12, 16, v12
	v_cndmask_b32_e32 v105, 1.0, v97, vcc
	v_lshlrev_b32_e32 v13, 16, v13
	v_cndmask_b32_e32 v106, 1.0, v98, vcc
	v_lshlrev_b32_e32 v14, 16, v14
	v_cndmask_b32_e32 v107, 1.0, v99, vcc
	v_lshlrev_b32_e32 v15, 16, v15
	v_cndmask_b32_e32 v108, 1.0, v100, vcc
	v_lshlrev_b32_e32 v16, 16, v16
	v_cndmask_b32_e32 v109, 1.0, v101, vcc
	v_lshlrev_b32_e32 v66, 16, v66
	v_cndmask_b32_e32 v110, 1.0, v102, vcc
	v_lshlrev_b32_e32 v17, 16, v17
	v_cndmask_b32_e32 v111, 1.0, v103, vcc
	v_mul_f32_e32 v11, v88, v11
	v_mul_f32_e32 v12, v89, v12
	v_mul_f32_e32 v13, v90, v13
	v_mul_f32_e32 v14, v91, v14
	v_mul_f32_e32 v15, v92, v15
	v_mul_f32_e32 v16, v93, v16
	v_mul_f32_e32 v66, v94, v66
	v_mul_f32_e32 v17, v95, v17
	v_mul_f32_e32 v11, v11, v104
	v_mul_f32_e32 v12, v12, v105
	v_mul_f32_e32 v13, v13, v106
	v_mul_f32_e32 v14, v14, v107
	v_mul_f32_e32 v15, v15, v108
	v_mul_f32_e32 v16, v16, v109
	v_mul_f32_e32 v66, v66, v110
	v_mul_f32_e32 v17, v17, v111
	ds_read_u16 v18, v0 offset:4352
	ds_read_u16 v19, v0 offset:4624
	ds_read_u16 v20, v0 offset:4896
	ds_read_u16 v21, v0 offset:5168
	ds_read_u16 v22, v0 offset:5440
	ds_read_u16 v23, v0 offset:5712
	ds_read_u16 v24, v0 offset:5984
	ds_read_u16 v25, v0 offset:6256
	ds_read_b128 v[88:91], v84 offset:64
	ds_read_b128 v[92:95], v84 offset:80
	ds_read_b128 v[96:99], v84 offset:320
	ds_read_b128 v[100:103], v84 offset:336
	s_waitcnt lgkmcnt(0)
	v_lshlrev_b32_e32 v18, 16, v18
	v_cndmask_b32_e32 v104, 1.0, v96, vcc
	v_lshlrev_b32_e32 v19, 16, v19
	v_cndmask_b32_e32 v105, 1.0, v97, vcc
	v_lshlrev_b32_e32 v20, 16, v20
	v_cndmask_b32_e32 v106, 1.0, v98, vcc
	v_lshlrev_b32_e32 v21, 16, v21
	v_cndmask_b32_e32 v107, 1.0, v99, vcc
	v_lshlrev_b32_e32 v22, 16, v22
	v_cndmask_b32_e32 v108, 1.0, v100, vcc
	v_lshlrev_b32_e32 v23, 16, v23
	v_cndmask_b32_e32 v109, 1.0, v101, vcc
	v_lshlrev_b32_e32 v24, 16, v24
	v_cndmask_b32_e32 v110, 1.0, v102, vcc
	v_lshlrev_b32_e32 v25, 16, v25
	v_cndmask_b32_e32 v111, 1.0, v103, vcc
	v_mul_f32_e32 v18, v88, v18
	v_mul_f32_e32 v19, v89, v19
	v_mul_f32_e32 v20, v90, v20
	v_mul_f32_e32 v21, v91, v21
	v_mul_f32_e32 v22, v92, v22
	v_mul_f32_e32 v23, v93, v23
	v_mul_f32_e32 v24, v94, v24
	v_mul_f32_e32 v25, v95, v25
	v_mul_f32_e32 v18, v18, v104
	v_mul_f32_e32 v19, v19, v105
	v_mul_f32_e32 v20, v20, v106
	v_mul_f32_e32 v21, v21, v107
	v_mul_f32_e32 v22, v22, v108
	v_mul_f32_e32 v23, v23, v109
	v_mul_f32_e32 v24, v24, v110
	v_mul_f32_e32 v25, v25, v111
	ds_read_u16 v26, v0 offset:6528
	ds_read_u16 v27, v0 offset:6800
	ds_read_u16 v29, v0 offset:7072
	ds_read_u16 v30, v0 offset:7344
	ds_read_u16 v33, v0 offset:7616
	ds_read_u16 v34, v0 offset:7888
	ds_read_u16 v36, v0 offset:8160
	ds_read_u16 v37, v0 offset:8432
	ds_read_b128 v[88:91], v84 offset:96
	ds_read_b128 v[92:95], v84 offset:112
	ds_read_b128 v[96:99], v84 offset:352
	ds_read_b128 v[100:103], v84 offset:368
	s_waitcnt lgkmcnt(0)
; DI float bf2f(bf16_t v) { return __uint_as_float(((unsigned)v) << 16); }
; DI void gdn_prep(const Params& p, int item, unsigned char* smem) {
;     ...
;         float X[64];
;         const bf16_t* src = tid < 128 ? (sv + tid) : (sk + tid - 128);
; #pragma unroll
;         for (int i = 0; i < 64; ++i) { float a = bf2f(src[i * 136]) * sbeta[i]; if (tid >= 128) a *= segc[i]; X[i] = a; }
	v_lshlrev_b32_e32 v26, 16, v26
	v_cndmask_b32_e32 v104, 1.0, v96, vcc
	v_lshlrev_b32_e32 v27, 16, v27
	v_cndmask_b32_e32 v105, 1.0, v97, vcc
	v_lshlrev_b32_e32 v29, 16, v29
	v_cndmask_b32_e32 v106, 1.0, v98, vcc
	v_lshlrev_b32_e32 v30, 16, v30
	v_cndmask_b32_e32 v107, 1.0, v99, vcc
	v_lshlrev_b32_e32 v33, 16, v33
	v_cndmask_b32_e32 v108, 1.0, v100, vcc
	v_lshlrev_b32_e32 v34, 16, v34
	v_cndmask_b32_e32 v109, 1.0, v101, vcc
	v_lshlrev_b32_e32 v36, 16, v36
	v_cndmask_b32_e32 v110, 1.0, v102, vcc
	v_lshlrev_b32_e32 v37, 16, v37
	v_cndmask_b32_e32 v111, 1.0, v103, vcc
	v_mul_f32_e32 v26, v88, v26
	v_mul_f32_e32 v27, v89, v27
	v_mul_f32_e32 v29, v90, v29
	v_mul_f32_e32 v30, v91, v30
	v_mul_f32_e32 v33, v92, v33
	v_mul_f32_e32 v34, v93, v34
	v_mul_f32_e32 v36, v94, v36
	v_mul_f32_e32 v37, v95, v37
	v_mul_f32_e32 v26, v26, v104
	v_mul_f32_e32 v27, v27, v105
	v_mul_f32_e32 v29, v29, v106
	v_mul_f32_e32 v30, v30, v107
	v_mul_f32_e32 v33, v33, v108
	v_mul_f32_e32 v34, v34, v109
	v_mul_f32_e32 v36, v36, v110
	v_mul_f32_e32 v37, v37, v111
	ds_read_u16 v39, v0 offset:8704
	ds_read_u16 v41, v0 offset:8976
	ds_read_u16 v42, v0 offset:9248
	ds_read_u16 v44, v0 offset:9520
	ds_read_u16 v48, v0 offset:9792
	ds_read_u16 v49, v0 offset:10064
	ds_read_u16 v51, v0 offset:10336
	ds_read_u16 v53, v0 offset:10608
	ds_read_b128 v[88:91], v84 offset:128
	ds_read_b128 v[92:95], v84 offset:144
	ds_read_b128 v[96:99], v84 offset:384
	ds_read_b128 v[100:103], v84 offset:400
	s_waitcnt lgkmcnt(0)
	v_lshlrev_b32_e32 v39, 16, v39
	v_cndmask_b32_e32 v104, 1.0, v96, vcc
	v_lshlrev_b32_e32 v41, 16, v41
	v_cndmask_b32_e32 v105, 1.0, v97, vcc
	v_lshlrev_b32_e32 v42, 16, v42
	v_cndmask_b32_e32 v106, 1.0, v98, vcc
	v_lshlrev_b32_e32 v44, 16, v44
	v_cndmask_b32_e32 v107, 1.0, v99, vcc
	v_lshlrev_b32_e32 v48, 16, v48
	v_cndmask_b32_e32 v108, 1.0, v100, vcc
	v_lshlrev_b32_e32 v49, 16, v49
	v_cndmask_b32_e32 v109, 1.0, v101, vcc
	v_lshlrev_b32_e32 v51, 16, v51
	v_cndmask_b32_e32 v110, 1.0, v102, vcc
	v_lshlrev_b32_e32 v53, 16, v53
	v_cndmask_b32_e32 v111, 1.0, v103, vcc
	v_mul_f32_e32 v39, v88, v39
	v_mul_f32_e32 v41, v89, v41
	v_mul_f32_e32 v42, v90, v42
	v_mul_f32_e32 v44, v91, v44
	v_mul_f32_e32 v48, v92, v48
	v_mul_f32_e32 v49, v93, v49
	v_mul_f32_e32 v51, v94, v51
	v_mul_f32_e32 v53, v95, v53
	v_mul_f32_e32 v39, v39, v104
	v_mul_f32_e32 v41, v41, v105
	v_mul_f32_e32 v42, v42, v106
	v_mul_f32_e32 v44, v44, v107
	v_mul_f32_e32 v48, v48, v108
	v_mul_f32_e32 v49, v49, v109
	v_mul_f32_e32 v51, v51, v110
	v_mul_f32_e32 v53, v53, v111
	ds_read_u16 v54, v0 offset:10880
	ds_read_u16 v56, v0 offset:11152
	ds_read_u16 v58, v0 offset:11424
	ds_read_u16 v61, v0 offset:11696
	ds_read_u16 v63, v0 offset:11968
	ds_read_u16 v65, v0 offset:12240
	ds_read_u16 v64, v0 offset:12512
	ds_read_u16 v62, v0 offset:12784
	ds_read_b128 v[88:91], v84 offset:160
	ds_read_b128 v[92:95], v84 offset:176
	ds_read_b128 v[96:99], v84 offset:416
	ds_read_b128 v[100:103], v84 offset:432
	s_waitcnt lgkmcnt(0)
	v_lshlrev_b32_e32 v54, 16, v54
	v_cndmask_b32_e32 v104, 1.0, v96, vcc
	v_lshlrev_b32_e32 v56, 16, v56
	v_cndmask_b32_e32 v105, 1.0, v97, vcc
	v_lshlrev_b32_e32 v58, 16, v58
	v_cndmask_b32_e32 v106, 1.0, v98, vcc
	v_lshlrev_b32_e32 v61, 16, v61
	v_cndmask_b32_e32 v107, 1.0, v99, vcc
	v_lshlrev_b32_e32 v63, 16, v63
	v_cndmask_b32_e32 v108, 1.0, v100, vcc
	v_lshlrev_b32_e32 v65, 16, v65
	v_cndmask_b32_e32 v109, 1.0, v101, vcc
	v_lshlrev_b32_e32 v64, 16, v64
	v_cndmask_b32_e32 v110, 1.0, v102, vcc
	v_lshlrev_b32_e32 v62, 16, v62
	v_cndmask_b32_e32 v111, 1.0, v103, vcc
	v_mul_f32_e32 v54, v88, v54
	v_mul_f32_e32 v56, v89, v56
	v_mul_f32_e32 v58, v90, v58
	v_mul_f32_e32 v61, v91, v61
	v_mul_f32_e32 v63, v92, v63
	v_mul_f32_e32 v65, v93, v65
	v_mul_f32_e32 v64, v94, v64
	v_mul_f32_e32 v62, v95, v62
	v_mul_f32_e32 v54, v54, v104
	v_mul_f32_e32 v56, v56, v105
	v_mul_f32_e32 v58, v58, v106
	v_mul_f32_e32 v61, v61, v107
	v_mul_f32_e32 v63, v63, v108
	v_mul_f32_e32 v65, v65, v109
	v_mul_f32_e32 v64, v64, v110
	v_mul_f32_e32 v62, v62, v111
	ds_read_u16 v60, v0 offset:13056
	ds_read_u16 v59, v0 offset:13328
	ds_read_u16 v57, v0 offset:13600
	ds_read_u16 v55, v0 offset:13872
	ds_read_u16 v52, v0 offset:14144
	ds_read_u16 v50, v0 offset:14416
	ds_read_u16 v47, v0 offset:14688
	ds_read_u16 v45, v0 offset:14960
	ds_read_b128 v[88:91], v84 offset:192
	ds_read_b128 v[92:95], v84 offset:208
	ds_read_b128 v[96:99], v84 offset:448
	ds_read_b128 v[100:103], v84 offset:464
	s_waitcnt lgkmcnt(0)
	v_lshlrev_b32_e32 v60, 16, v60
	v_cndmask_b32_e32 v104, 1.0, v96, vcc
	v_lshlrev_b32_e32 v59, 16, v59
	v_cndmask_b32_e32 v105, 1.0, v97, vcc
	v_lshlrev_b32_e32 v57, 16, v57
	v_cndmask_b32_e32 v106, 1.0, v98, vcc
	v_lshlrev_b32_e32 v55, 16, v55
	v_cndmask_b32_e32 v107, 1.0, v99, vcc
	v_lshlrev_b32_e32 v52, 16, v52
	v_cndmask_b32_e32 v108, 1.0, v100, vcc
	v_lshlrev_b32_e32 v50, 16, v50
	v_cndmask_b32_e32 v109, 1.0, v101, vcc
	v_lshlrev_b32_e32 v47, 16, v47
	v_cndmask_b32_e32 v110, 1.0, v102, vcc
	v_lshlrev_b32_e32 v45, 16, v45
	v_cndmask_b32_e32 v111, 1.0, v103, vcc
	v_mul_f32_e32 v60, v88, v60
	v_mul_f32_e32 v59, v89, v59
	v_mul_f32_e32 v57, v90, v57
	v_mul_f32_e32 v55, v91, v55
	v_mul_f32_e32 v52, v92, v52
	v_mul_f32_e32 v50, v93, v50
	v_mul_f32_e32 v47, v94, v47
	v_mul_f32_e32 v45, v95, v45
	v_mul_f32_e32 v60, v60, v104
	v_mul_f32_e32 v59, v59, v105
	v_mul_f32_e32 v57, v57, v106
	v_mul_f32_e32 v55, v55, v107
	v_mul_f32_e32 v52, v52, v108
	v_mul_f32_e32 v50, v50, v109
	v_mul_f32_e32 v47, v47, v110
	v_mul_f32_e32 v45, v45, v111
	ds_read_u16 v43, v0 offset:15232
	ds_read_u16 v40, v0 offset:15504
	ds_read_u16 v38, v0 offset:15776
	ds_read_u16 v35, v0 offset:16048
	ds_read_u16 v31, v0 offset:16320
	ds_read_u16 v28, v0 offset:16592
	ds_read_u16 v1, v0 offset:16864
	ds_read_u16 v0, v0 offset:17136
	ds_read_b128 v[88:91], v84 offset:224
	ds_read_b128 v[92:95], v84 offset:240
	ds_read_b128 v[96:99], v84 offset:480
	ds_read_b128 v[100:103], v84 offset:496
	s_waitcnt lgkmcnt(0)
; DI float bf2f(bf16_t v) { return __uint_as_float(((unsigned)v) << 16); }
; DI void gdn_prep(const Params& p, int item, unsigned char* smem) {
;     ...
;         for (int i = 0; i < 64; ++i) { float a = bf2f(src[i * 136]) * sbeta[i]; if (tid >= 128) a *= segc[i]; X[i] = a; }
; #pragma unroll
;         for (int i = 1; i < 64; ++i) {
;             float a = X[i];
;             int dep; asm volatile("v_and_b32 %0, 0, %1" : "=v"(dep) : "v"(X[i - 1]));
;             const float* Lr = sL + i * 68 + dep;
;             float b0 = 0.f, b1 = 0.f, b2 = 0.f;
; #pragma unroll
;             for (int j4 = 0; j4 < (i + 3) / 4; ++j4) {
;                 const f32x4 l = *(const f32x4*)(Lr + 4 * j4);
;                 if (4 * j4 + 0 < i) a -= l.x * X[4 * j4 + 0];
;                 if (4 * j4 + 1 < i) b0 -= l.y * X[4 * j4 + 1];
;                 if (4 * j4 + 2 < i) b1 -= l.z * X[4 * j4 + 2];
;                 if (4 * j4 + 3 < i) b2 -= l.w * X[4 * j4 + 3];
;             }
;             X[i] = (a + b0) + (b1 + b2);
;         }
	v_lshlrev_b32_e32 v43, 16, v43
	v_cndmask_b32_e32 v104, 1.0, v96, vcc
	v_lshlrev_b32_e32 v40, 16, v40
	v_cndmask_b32_e32 v105, 1.0, v97, vcc
	v_lshlrev_b32_e32 v38, 16, v38
	v_cndmask_b32_e32 v106, 1.0, v98, vcc
	v_lshlrev_b32_e32 v35, 16, v35
	v_cndmask_b32_e32 v107, 1.0, v99, vcc
	v_lshlrev_b32_e32 v31, 16, v31
	v_cndmask_b32_e32 v108, 1.0, v100, vcc
	v_lshlrev_b32_e32 v28, 16, v28
	v_cndmask_b32_e32 v109, 1.0, v101, vcc
	v_lshlrev_b32_e32 v1, 16, v1
	v_cndmask_b32_e32 v110, 1.0, v102, vcc
	v_lshlrev_b32_e32 v0, 16, v0
	v_cndmask_b32_e32 v111, 1.0, v103, vcc
	v_mul_f32_e32 v43, v88, v43
	v_mul_f32_e32 v40, v89, v40
	v_mul_f32_e32 v38, v90, v38
	v_mul_f32_e32 v35, v91, v35
	v_mul_f32_e32 v31, v92, v31
	v_mul_f32_e32 v28, v93, v28
	v_mul_f32_e32 v1, v94, v1
	v_mul_f32_e32 v0, v95, v0
	v_mul_f32_e32 v43, v43, v104
	v_mul_f32_e32 v40, v40, v105
	v_mul_f32_e32 v38, v38, v106
	v_mul_f32_e32 v35, v35, v107
	v_mul_f32_e32 v31, v31, v108
	v_mul_f32_e32 v28, v28, v109
	v_mul_f32_e32 v1, v1, v110
	v_mul_f32_e32 v0, v0, v111
	v_mov_b32_e32 v78, s10
	v_add_u32_e32 v78, 0xcc00, v78
	ds_read_b128 v[84:87], v78 offset:272
	ds_read_b128 v[88:91], v78 offset:544
	ds_read_b128 v[92:95], v78 offset:816
	ds_read_b128 v[96:99], v78 offset:1088
	ds_read_b128 v[100:103], v78 offset:1360
	ds_read_b128 v[104:107], v78 offset:1376
	ds_read_b128 v[108:111], v78 offset:1632
	s_waitcnt lgkmcnt(6)
	v_mov_b32_e32 v76, v84
	ds_read_b128 v[84:87], v78 offset:1648
	s_waitcnt lgkmcnt(6)
	v_fma_f32 v5, -v2, v88, v5
	v_mov_b32_e32 v75, v89
	ds_read_b128 v[88:91], v78 offset:1904
	v_fma_f32 v3, -v2, v76, v3
	s_waitcnt lgkmcnt(6)
	v_fma_f32 v6, -v2, v92, v6
	v_fma_f32 v72, -v3, v93, 0
	v_mov_b32_e32 v76, v94
	v_fma_f32 v69, -v3, v75, 0
	ds_read_b128 v[92:95], v78 offset:1920
	v_add_f32_e32 v5, v5, v69
	s_waitcnt lgkmcnt(6)
	v_fma_f32 v7, -v2, v96, v7
	v_fma_f32 v69, -v3, v97, 0
	v_fma_f32 v70, -v5, v98, 0
	v_fma_f32 v73, -v5, v76, 0
	v_mov_b32_e32 v75, v99
	ds_read_b128 v[96:99], v78 offset:2176
	v_add_f32_e32 v72, v6, v72
	v_add_f32_e32 v6, v72, v73
	s_waitcnt lgkmcnt(6)
	v_fma_f32 v8, -v2, v100, v8
	v_fma_f32 v72, -v3, v101, 0
	v_fma_f32 v73, -v5, v102, 0
	v_fma_f32 v71, -v6, v75, 0
	v_fma_f32 v74, -v6, v103, 0
	ds_read_b128 v[100:103], v78 offset:2192
	s_waitcnt lgkmcnt(6)
	v_mov_b32_e32 v76, v104
	ds_read_b128 v[104:107], v78 offset:2448
	v_add_f32_e32 v69, v7, v69
	v_add_f32_e32 v70, v70, v71
	v_add_f32_e32 v7, v69, v70
	s_waitcnt lgkmcnt(6)
	v_fma_f32 v9, -v2, v108, v9
	v_fma_f32 v69, -v3, v109, 0
	v_fma_f32 v70, -v5, v110, 0
	v_fma_f32 v8, -v7, v76, v8
	v_fma_f32 v71, -v6, v111, 0
	ds_read_b128 v[108:111], v78 offset:2464
	s_waitcnt lgkmcnt(6)
	v_fma_f32 v9, -v7, v84, v9
	v_mov_b32_e32 v75, v85
	v_add_f32_e32 v72, v8, v72
	ds_read_b128 v[84:87], v78 offset:2480
	v_add_f32_e32 v73, v73, v74
	v_add_f32_e32 v8, v72, v73
	s_waitcnt lgkmcnt(6)
	v_fma_f32 v10, -v2, v88, v10
	v_fma_f32 v72, -v3, v89, 0
	v_fma_f32 v73, -v5, v90, 0
	v_fma_f32 v69, -v8, v75, v69
	v_fma_f32 v74, -v6, v91, 0
	ds_read_b128 v[88:91], v78 offset:2720
	s_waitcnt lgkmcnt(6)
	v_fma_f32 v10, -v7, v92, v10
	v_fma_f32 v72, -v8, v93, v72
	v_add_f32_e32 v69, v9, v69
	v_mov_b32_e32 v76, v94
	ds_read_b128 v[92:95], v78 offset:2736
	v_add_f32_e32 v70, v70, v71
	v_add_f32_e32 v9, v69, v70
	s_waitcnt lgkmcnt(6)
	v_fma_f32 v11, -v2, v96, v11
	v_fma_f32 v69, -v3, v97, 0
	v_fma_f32 v70, -v5, v98, 0
	v_fma_f32 v73, -v9, v76, v73
	v_fma_f32 v71, -v6, v99, 0
	ds_read_b128 v[96:99], v78 offset:2752
	s_waitcnt lgkmcnt(6)
	v_fma_f32 v11, -v7, v100, v11
	v_fma_f32 v69, -v8, v101, v69
	v_add_f32_e32 v72, v10, v72
	v_fma_f32 v70, -v9, v102, v70
	v_mov_b32_e32 v75, v103
	ds_read_b128 v[100:103], v78 offset:2992
	v_add_f32_e32 v73, v73, v74
	v_add_f32_e32 v10, v72, v73
	s_waitcnt lgkmcnt(6)
	v_fma_f32 v12, -v2, v104, v12
	v_fma_f32 v72, -v3, v105, 0
	v_fma_f32 v73, -v5, v106, 0
	v_fma_f32 v71, -v10, v75, v71
	v_fma_f32 v74, -v6, v107, 0
	ds_read_b128 v[104:107], v78 offset:3008
	s_waitcnt lgkmcnt(6)
	v_fma_f32 v12, -v7, v108, v12
	v_fma_f32 v72, -v8, v109, v72
	v_add_f32_e32 v69, v11, v69
	v_fma_f32 v73, -v9, v110, v73
	v_fma_f32 v74, -v10, v111, v74
	ds_read_b128 v[108:111], v78 offset:3024
	s_waitcnt lgkmcnt(6)
	v_mov_b32_e32 v76, v84
	v_add_f32_e32 v70, v70, v71
	ds_read_b128 v[84:87], v78 offset:3264
	v_add_f32_e32 v11, v69, v70
	s_waitcnt lgkmcnt(6)
	v_fma_f32 v13, -v2, v88, v13
	v_fma_f32 v69, -v3, v89, 0
	v_fma_f32 v70, -v5, v90, 0
	v_fma_f32 v12, -v11, v76, v12
	v_fma_f32 v71, -v6, v91, 0
	ds_read_b128 v[88:91], v78 offset:3280
	s_waitcnt lgkmcnt(6)
	v_fma_f32 v13, -v7, v92, v13
	v_fma_f32 v69, -v8, v93, v69
	v_add_f32_e32 v72, v12, v72
	v_fma_f32 v70, -v9, v94, v70
	v_fma_f32 v71, -v10, v95, v71
	ds_read_b128 v[92:95], v78 offset:3296
	s_waitcnt lgkmcnt(6)
	v_fma_f32 v13, -v11, v96, v13
	v_add_f32_e32 v73, v73, v74
	v_mov_b32_e32 v75, v97
	ds_read_b128 v[96:99], v78 offset:3536
	v_add_f32_e32 v12, v72, v73
	s_waitcnt lgkmcnt(6)
	v_fma_f32 v14, -v2, v100, v14
	v_fma_f32 v72, -v3, v101, 0
	v_fma_f32 v73, -v5, v102, 0
	v_fma_f32 v69, -v12, v75, v69
	v_fma_f32 v74, -v6, v103, 0
	ds_read_b128 v[100:103], v78 offset:3552
	s_waitcnt lgkmcnt(6)
	v_fma_f32 v14, -v7, v104, v14
	v_fma_f32 v72, -v8, v105, v72
	v_add_f32_e32 v69, v13, v69
	v_fma_f32 v73, -v9, v106, v73
	v_fma_f32 v74, -v10, v107, v74
	ds_read_b128 v[104:107], v78 offset:3568
	s_waitcnt lgkmcnt(6)
	v_fma_f32 v14, -v11, v108, v14
	v_add_f32_e32 v70, v70, v71
	v_fma_f32 v72, -v12, v109, v72
	v_mov_b32_e32 v76, v110
	ds_read_b128 v[108:111], v78 offset:3584
	v_add_f32_e32 v13, v69, v70
	s_waitcnt lgkmcnt(6)
; DI void gdn_prep(const Params& p, int item, unsigned char* smem) {
;     ...
; #pragma unroll
;         for (int i = 1; i < 64; ++i) {
;             float a = X[i];
;             int dep; asm volatile("v_and_b32 %0, 0, %1" : "=v"(dep) : "v"(X[i - 1]));
;             const float* Lr = sL + i * 68 + dep;
;             float b0 = 0.f, b1 = 0.f, b2 = 0.f;
; #pragma unroll
;             for (int j4 = 0; j4 < (i + 3) / 4; ++j4) {
;                 const f32x4 l = *(const f32x4*)(Lr + 4 * j4);
;                 if (4 * j4 + 0 < i) a -= l.x * X[4 * j4 + 0];
;                 if (4 * j4 + 1 < i) b0 -= l.y * X[4 * j4 + 1];
;                 if (4 * j4 + 2 < i) b1 -= l.z * X[4 * j4 + 2];
;                 if (4 * j4 + 3 < i) b2 -= l.w * X[4 * j4 + 3];
;             }
;             X[i] = (a + b0) + (b1 + b2);
;         }
	v_fma_f32 v15, -v2, v84, v15
	v_fma_f32 v69, -v3, v85, 0
	v_fma_f32 v70, -v5, v86, 0
	v_fma_f32 v73, -v13, v76, v73
	v_fma_f32 v71, -v6, v87, 0
	ds_read_b128 v[84:87], v78 offset:3808
	s_waitcnt lgkmcnt(6)
	v_fma_f32 v15, -v7, v88, v15
	v_fma_f32 v69, -v8, v89, v69
	v_add_f32_e32 v72, v14, v72
	v_fma_f32 v70, -v9, v90, v70
	v_fma_f32 v71, -v10, v91, v71
	ds_read_b128 v[88:91], v78 offset:3824
	s_waitcnt lgkmcnt(6)
	v_fma_f32 v15, -v11, v92, v15
	v_add_f32_e32 v73, v73, v74
	v_fma_f32 v69, -v12, v93, v69
	v_fma_f32 v70, -v13, v94, v70
	v_mov_b32_e32 v75, v95
	v_add_f32_e32 v14, v72, v73
	ds_read_b128 v[92:95], v78 offset:3840
	s_waitcnt lgkmcnt(6)
	v_fma_f32 v16, -v2, v96, v16
	v_fma_f32 v72, -v3, v97, 0
	v_fma_f32 v73, -v5, v98, 0
	v_fma_f32 v71, -v14, v75, v71
	v_fma_f32 v74, -v6, v99, 0
	ds_read_b128 v[96:99], v78 offset:3856
	s_waitcnt lgkmcnt(6)
	v_fma_f32 v16, -v7, v100, v16
	v_fma_f32 v72, -v8, v101, v72
	v_add_f32_e32 v69, v15, v69
	v_fma_f32 v73, -v9, v102, v73
	v_fma_f32 v74, -v10, v103, v74
	ds_read_b128 v[100:103], v78 offset:4080
	s_waitcnt lgkmcnt(6)
	v_fma_f32 v16, -v11, v104, v16
	v_add_f32_e32 v70, v70, v71
	v_fma_f32 v72, -v12, v105, v72
	v_fma_f32 v73, -v13, v106, v73
	v_fma_f32 v74, -v14, v107, v74
	v_add_f32_e32 v15, v69, v70
	ds_read_b128 v[104:107], v78 offset:4096
	s_waitcnt lgkmcnt(6)
	v_mov_b32_e32 v76, v108
	ds_read_b128 v[108:111], v78 offset:4112
	s_waitcnt lgkmcnt(6)
	v_fma_f32 v66, -v2, v84, v66
	v_fma_f32 v69, -v3, v85, 0
	v_fma_f32 v70, -v5, v86, 0
	v_fma_f32 v16, -v15, v76, v16
	v_fma_f32 v71, -v6, v87, 0
	ds_read_b128 v[84:87], v78 offset:4128
	s_waitcnt lgkmcnt(6)
	v_fma_f32 v66, -v7, v88, v66
	v_fma_f32 v69, -v8, v89, v69
	v_add_f32_e32 v72, v16, v72
	v_fma_f32 v70, -v9, v90, v70
	v_fma_f32 v71, -v10, v91, v71
	ds_read_b128 v[88:91], v78 offset:4352
	s_waitcnt lgkmcnt(6)
	v_fma_f32 v66, -v11, v92, v66
	v_add_f32_e32 v73, v73, v74
	v_fma_f32 v69, -v12, v93, v69
	v_fma_f32 v70, -v13, v94, v70
	v_fma_f32 v71, -v14, v95, v71
	v_add_f32_e32 v16, v72, v73
	ds_read_b128 v[92:95], v78 offset:4368
	s_waitcnt lgkmcnt(6)
	v_fma_f32 v66, -v15, v96, v66
	v_mov_b32_e32 v75, v97
	ds_read_b128 v[96:99], v78 offset:4384
	s_waitcnt lgkmcnt(6)
	v_fma_f32 v17, -v2, v100, v17
	v_fma_f32 v72, -v3, v101, 0
	v_fma_f32 v73, -v5, v102, 0
	v_fma_f32 v69, -v16, v75, v69
	v_fma_f32 v74, -v6, v103, 0
	ds_read_b128 v[100:103], v78 offset:4400
	s_waitcnt lgkmcnt(6)
	v_fma_f32 v17, -v7, v104, v17
	v_fma_f32 v72, -v8, v105, v72
	v_add_f32_e32 v69, v66, v69
	v_fma_f32 v73, -v9, v106, v73
	v_fma_f32 v74, -v10, v107, v74
	ds_read_b128 v[104:107], v78 offset:4624
	s_waitcnt lgkmcnt(6)
	v_fma_f32 v17, -v11, v108, v17
	v_add_f32_e32 v70, v70, v71
	v_fma_f32 v72, -v12, v109, v72
	v_fma_f32 v73, -v13, v110, v73
	v_fma_f32 v74, -v14, v111, v74
	v_add_f32_e32 v66, v69, v70
	ds_read_b128 v[108:111], v78 offset:4640
	s_waitcnt lgkmcnt(6)
	v_fma_f32 v17, -v15, v84, v17
	v_fma_f32 v72, -v16, v85, v72
	v_mov_b32_e32 v76, v86
	ds_read_b128 v[84:87], v78 offset:4656
	s_waitcnt lgkmcnt(6)
	v_fma_f32 v18, -v2, v88, v18
	v_fma_f32 v69, -v3, v89, 0
	v_fma_f32 v70, -v5, v90, 0
	v_fma_f32 v73, -v66, v76, v73
	v_fma_f32 v71, -v6, v91, 0
	ds_read_b128 v[88:91], v78 offset:4672
	s_waitcnt lgkmcnt(6)
	v_fma_f32 v18, -v7, v92, v18
	v_fma_f32 v69, -v8, v93, v69
	v_add_f32_e32 v72, v17, v72
	v_fma_f32 v70, -v9, v94, v70
	v_fma_f32 v71, -v10, v95, v71
	ds_read_b128 v[92:95], v78 offset:4688
	s_waitcnt lgkmcnt(6)
	v_fma_f32 v18, -v11, v96, v18
	v_add_f32_e32 v73, v73, v74
	v_fma_f32 v69, -v12, v97, v69
	v_fma_f32 v70, -v13, v98, v70
	v_fma_f32 v71, -v14, v99, v71
	v_add_f32_e32 v17, v72, v73
	ds_read_b128 v[96:99], v78 offset:4896
	s_waitcnt lgkmcnt(6)
	v_fma_f32 v18, -v15, v100, v18
	v_fma_f32 v69, -v16, v101, v69
	v_fma_f32 v70, -v66, v102, v70
	v_mov_b32_e32 v75, v103
	ds_read_b128 v[100:103], v78 offset:4912
	s_waitcnt lgkmcnt(6)
	v_fma_f32 v19, -v2, v104, v19
	v_fma_f32 v72, -v3, v105, 0
	v_fma_f32 v73, -v5, v106, 0
	v_fma_f32 v71, -v17, v75, v71
	v_fma_f32 v74, -v6, v107, 0
	ds_read_b128 v[104:107], v78 offset:4928
	s_waitcnt lgkmcnt(6)
	v_fma_f32 v19, -v7, v108, v19
	v_fma_f32 v72, -v8, v109, v72
	v_add_f32_e32 v69, v18, v69
	v_fma_f32 v73, -v9, v110, v73
	v_fma_f32 v74, -v10, v111, v74
	ds_read_b128 v[108:111], v78 offset:4944
	s_waitcnt lgkmcnt(6)
	v_fma_f32 v19, -v11, v84, v19
	v_add_f32_e32 v70, v70, v71
	v_fma_f32 v72, -v12, v85, v72
	v_fma_f32 v73, -v13, v86, v73
	v_fma_f32 v74, -v14, v87, v74
	v_add_f32_e32 v18, v69, v70
	ds_read_b128 v[84:87], v78 offset:4960
	s_waitcnt lgkmcnt(6)
	v_fma_f32 v19, -v15, v88, v19
	v_fma_f32 v72, -v16, v89, v72
	v_fma_f32 v73, -v66, v90, v73
	v_fma_f32 v74, -v17, v91, v74
	ds_read_b128 v[88:91], v78 offset:5168
	s_waitcnt lgkmcnt(6)
	v_mov_b32_e32 v76, v92
	ds_read_b128 v[92:95], v78 offset:5184
	s_waitcnt lgkmcnt(6)
	v_fma_f32 v20, -v2, v96, v20
	v_fma_f32 v69, -v3, v97, 0
	v_fma_f32 v70, -v5, v98, 0
	v_fma_f32 v19, -v18, v76, v19
	v_fma_f32 v71, -v6, v99, 0
	ds_read_b128 v[96:99], v78 offset:5200
	s_waitcnt lgkmcnt(6)
	v_fma_f32 v20, -v7, v100, v20
	v_fma_f32 v69, -v8, v101, v69
	v_add_f32_e32 v72, v19, v72
	v_fma_f32 v70, -v9, v102, v70
	v_fma_f32 v71, -v10, v103, v71
	ds_read_b128 v[100:103], v78 offset:5216
	s_waitcnt lgkmcnt(6)
	v_fma_f32 v20, -v11, v104, v20
	v_add_f32_e32 v73, v73, v74
	v_fma_f32 v69, -v12, v105, v69
	v_fma_f32 v70, -v13, v106, v70
	v_fma_f32 v71, -v14, v107, v71
	v_add_f32_e32 v19, v72, v73
	ds_read_b128 v[104:107], v78 offset:5232
	s_waitcnt lgkmcnt(6)
	v_fma_f32 v20, -v15, v108, v20
	v_fma_f32 v69, -v16, v109, v69
	v_fma_f32 v70, -v66, v110, v70
	v_fma_f32 v71, -v17, v111, v71
	ds_read_b128 v[108:111], v78 offset:5440
	s_waitcnt lgkmcnt(6)
; DI void gdn_prep(const Params& p, int item, unsigned char* smem) {
;     ...
; #pragma unroll
;         for (int i = 1; i < 64; ++i) {
;             float a = X[i];
;             int dep; asm volatile("v_and_b32 %0, 0, %1" : "=v"(dep) : "v"(X[i - 1]));
;             const float* Lr = sL + i * 68 + dep;
;             float b0 = 0.f, b1 = 0.f, b2 = 0.f;
; #pragma unroll
;             for (int j4 = 0; j4 < (i + 3) / 4; ++j4) {
;                 const f32x4 l = *(const f32x4*)(Lr + 4 * j4);
;                 if (4 * j4 + 0 < i) a -= l.x * X[4 * j4 + 0];
;                 if (4 * j4 + 1 < i) b0 -= l.y * X[4 * j4 + 1];
;                 if (4 * j4 + 2 < i) b1 -= l.z * X[4 * j4 + 2];
;                 if (4 * j4 + 3 < i) b2 -= l.w * X[4 * j4 + 3];
;             }
;             X[i] = (a + b0) + (b1 + b2);
;         }
	v_fma_f32 v20, -v18, v84, v20
	v_mov_b32_e32 v75, v85
	ds_read_b128 v[84:87], v78 offset:5456
	s_waitcnt lgkmcnt(6)
	v_fma_f32 v21, -v2, v88, v21
	v_fma_f32 v72, -v3, v89, 0
	v_fma_f32 v73, -v5, v90, 0
	v_fma_f32 v69, -v19, v75, v69
	v_fma_f32 v74, -v6, v91, 0
	ds_read_b128 v[88:91], v78 offset:5472
	s_waitcnt lgkmcnt(6)
	v_fma_f32 v21, -v7, v92, v21
	v_fma_f32 v72, -v8, v93, v72
	v_add_f32_e32 v69, v20, v69
	v_fma_f32 v73, -v9, v94, v73
	v_fma_f32 v74, -v10, v95, v74
	ds_read_b128 v[92:95], v78 offset:5488
	s_waitcnt lgkmcnt(6)
	v_fma_f32 v21, -v11, v96, v21
	v_add_f32_e32 v70, v70, v71
	v_fma_f32 v72, -v12, v97, v72
	v_fma_f32 v73, -v13, v98, v73
	v_fma_f32 v74, -v14, v99, v74
	v_add_f32_e32 v20, v69, v70
	ds_read_b128 v[96:99], v78 offset:5504
	s_waitcnt lgkmcnt(6)
	v_fma_f32 v21, -v15, v100, v21
	v_fma_f32 v72, -v16, v101, v72
	v_fma_f32 v73, -v66, v102, v73
	v_fma_f32 v74, -v17, v103, v74
	ds_read_b128 v[100:103], v78 offset:5712
	s_waitcnt lgkmcnt(6)
	v_fma_f32 v21, -v18, v104, v21
	v_fma_f32 v72, -v19, v105, v72
	v_mov_b32_e32 v76, v106
	ds_read_b128 v[104:107], v78 offset:5728
	s_waitcnt lgkmcnt(6)
	v_fma_f32 v22, -v2, v108, v22
	v_fma_f32 v69, -v3, v109, 0
	v_fma_f32 v70, -v5, v110, 0
	v_fma_f32 v73, -v20, v76, v73
	v_fma_f32 v71, -v6, v111, 0
	ds_read_b128 v[108:111], v78 offset:5744
	s_waitcnt lgkmcnt(6)
	v_fma_f32 v22, -v7, v84, v22
	v_fma_f32 v69, -v8, v85, v69
	v_add_f32_e32 v72, v21, v72
	v_fma_f32 v70, -v9, v86, v70
	v_fma_f32 v71, -v10, v87, v71
	ds_read_b128 v[84:87], v78 offset:5760
	s_waitcnt lgkmcnt(6)
	v_fma_f32 v22, -v11, v88, v22
	v_add_f32_e32 v73, v73, v74
	v_fma_f32 v69, -v12, v89, v69
	v_fma_f32 v70, -v13, v90, v70
	v_fma_f32 v71, -v14, v91, v71
	v_add_f32_e32 v21, v72, v73
	ds_read_b128 v[88:91], v78 offset:5776
	s_waitcnt lgkmcnt(6)
	v_fma_f32 v22, -v15, v92, v22
	v_fma_f32 v69, -v16, v93, v69
	v_fma_f32 v70, -v66, v94, v70
	v_fma_f32 v71, -v17, v95, v71
	ds_read_b128 v[92:95], v78 offset:5792
	s_waitcnt lgkmcnt(6)
	v_fma_f32 v22, -v18, v96, v22
	v_fma_f32 v69, -v19, v97, v69
	v_fma_f32 v70, -v20, v98, v70
	v_mov_b32_e32 v75, v99
	ds_read_b128 v[96:99], v78 offset:5984
	s_waitcnt lgkmcnt(6)
	v_fma_f32 v23, -v2, v100, v23
	v_fma_f32 v72, -v3, v101, 0
	v_fma_f32 v73, -v5, v102, 0
	v_fma_f32 v71, -v21, v75, v71
	v_fma_f32 v74, -v6, v103, 0
	ds_read_b128 v[100:103], v78 offset:6000
	s_waitcnt lgkmcnt(6)
	v_fma_f32 v23, -v7, v104, v23
	v_fma_f32 v72, -v8, v105, v72
	v_add_f32_e32 v69, v22, v69
	v_fma_f32 v73, -v9, v106, v73
	v_fma_f32 v74, -v10, v107, v74
	ds_read_b128 v[104:107], v78 offset:6016
	s_waitcnt lgkmcnt(6)
	v_fma_f32 v23, -v11, v108, v23
	v_add_f32_e32 v70, v70, v71
	v_fma_f32 v72, -v12, v109, v72
	v_fma_f32 v73, -v13, v110, v73
	v_fma_f32 v74, -v14, v111, v74
	v_add_f32_e32 v22, v69, v70
	ds_read_b128 v[108:111], v78 offset:6032
	s_waitcnt lgkmcnt(6)
	v_fma_f32 v23, -v15, v84, v23
	v_fma_f32 v72, -v16, v85, v72
	v_fma_f32 v73, -v66, v86, v73
	v_fma_f32 v74, -v17, v87, v74
	ds_read_b128 v[84:87], v78 offset:6048
	s_waitcnt lgkmcnt(6)
	v_fma_f32 v23, -v18, v88, v23
	v_fma_f32 v72, -v19, v89, v72
	v_fma_f32 v73, -v20, v90, v73
	v_fma_f32 v74, -v21, v91, v74
	ds_read_b128 v[88:91], v78 offset:6064
	s_waitcnt lgkmcnt(6)
	v_mov_b32_e32 v76, v92
	ds_read_b128 v[92:95], v78 offset:6256
	s_waitcnt lgkmcnt(6)
	v_fma_f32 v24, -v2, v96, v24
	v_fma_f32 v69, -v3, v97, 0
	v_fma_f32 v70, -v5, v98, 0
	v_fma_f32 v23, -v22, v76, v23
	v_fma_f32 v71, -v6, v99, 0
	ds_read_b128 v[96:99], v78 offset:6272
	s_waitcnt lgkmcnt(6)
	v_fma_f32 v24, -v7, v100, v24
	v_fma_f32 v69, -v8, v101, v69
	v_add_f32_e32 v72, v23, v72
	v_fma_f32 v70, -v9, v102, v70
	v_fma_f32 v71, -v10, v103, v71
	ds_read_b128 v[100:103], v78 offset:6288
	s_waitcnt lgkmcnt(6)
	v_fma_f32 v24, -v11, v104, v24
	v_add_f32_e32 v73, v73, v74
	v_fma_f32 v69, -v12, v105, v69
	v_fma_f32 v70, -v13, v106, v70
	v_fma_f32 v71, -v14, v107, v71
	v_add_f32_e32 v23, v72, v73
	ds_read_b128 v[104:107], v78 offset:6304
	s_waitcnt lgkmcnt(6)
	v_fma_f32 v24, -v15, v108, v24
	v_fma_f32 v69, -v16, v109, v69
	v_fma_f32 v70, -v66, v110, v70
	v_fma_f32 v71, -v17, v111, v71
	ds_read_b128 v[108:111], v78 offset:6320
	s_waitcnt lgkmcnt(6)
	v_fma_f32 v24, -v18, v84, v24
	v_fma_f32 v69, -v19, v85, v69
	v_fma_f32 v70, -v20, v86, v70
	v_fma_f32 v71, -v21, v87, v71
	ds_read_b128 v[84:87], v78 offset:6336
	s_waitcnt lgkmcnt(6)
	v_fma_f32 v24, -v22, v88, v24
	v_mov_b32_e32 v75, v89
	ds_read_b128 v[88:91], v78 offset:6528
	s_waitcnt lgkmcnt(6)
	v_fma_f32 v25, -v2, v92, v25
	v_fma_f32 v72, -v3, v93, 0
	v_fma_f32 v73, -v5, v94, 0
	v_fma_f32 v69, -v23, v75, v69
	v_fma_f32 v74, -v6, v95, 0
	ds_read_b128 v[92:95], v78 offset:6544
	s_waitcnt lgkmcnt(6)
	v_fma_f32 v25, -v7, v96, v25
	v_fma_f32 v72, -v8, v97, v72
	v_add_f32_e32 v69, v24, v69
	v_fma_f32 v73, -v9, v98, v73
	v_fma_f32 v74, -v10, v99, v74
	ds_read_b128 v[96:99], v78 offset:6560
	s_waitcnt lgkmcnt(6)
	v_fma_f32 v25, -v11, v100, v25
	v_add_f32_e32 v70, v70, v71
	v_fma_f32 v72, -v12, v101, v72
	v_fma_f32 v73, -v13, v102, v73
	v_fma_f32 v74, -v14, v103, v74
	v_add_f32_e32 v24, v69, v70
	ds_read_b128 v[100:103], v78 offset:6576
	s_waitcnt lgkmcnt(6)
	v_fma_f32 v25, -v15, v104, v25
	v_fma_f32 v72, -v16, v105, v72
	v_fma_f32 v73, -v66, v106, v73
	v_fma_f32 v74, -v17, v107, v74
	ds_read_b128 v[104:107], v78 offset:6592
	s_waitcnt lgkmcnt(6)
	v_fma_f32 v25, -v18, v108, v25
	v_fma_f32 v72, -v19, v109, v72
	v_fma_f32 v73, -v20, v110, v73
	v_fma_f32 v74, -v21, v111, v74
	ds_read_b128 v[108:111], v78 offset:6608
	s_waitcnt lgkmcnt(6)
	v_fma_f32 v25, -v22, v84, v25
	v_fma_f32 v72, -v23, v85, v72
	v_mov_b32_e32 v76, v86
	ds_read_b128 v[84:87], v78 offset:6800
	s_waitcnt lgkmcnt(6)
; DI void gdn_prep(const Params& p, int item, unsigned char* smem) {
;     ...
;         for (int i = 1; i < 64; ++i) {
;             float a = X[i];
;             int dep; asm volatile("v_and_b32 %0, 0, %1" : "=v"(dep) : "v"(X[i - 1]));
;             const float* Lr = sL + i * 68 + dep;
;             float b0 = 0.f, b1 = 0.f, b2 = 0.f;
; #pragma unroll
;             for (int j4 = 0; j4 < (i + 3) / 4; ++j4) {
;                 const f32x4 l = *(const f32x4*)(Lr + 4 * j4);
;                 if (4 * j4 + 0 < i) a -= l.x * X[4 * j4 + 0];
;                 if (4 * j4 + 1 < i) b0 -= l.y * X[4 * j4 + 1];
;                 if (4 * j4 + 2 < i) b1 -= l.z * X[4 * j4 + 2];
;                 if (4 * j4 + 3 < i) b2 -= l.w * X[4 * j4 + 3];
;             }
;             X[i] = (a + b0) + (b1 + b2);
	v_fma_f32 v26, -v2, v88, v26
	v_fma_f32 v69, -v3, v89, 0
	v_fma_f32 v70, -v5, v90, 0
	v_fma_f32 v73, -v24, v76, v73
	v_fma_f32 v71, -v6, v91, 0
	ds_read_b128 v[88:91], v78 offset:6816
	s_waitcnt lgkmcnt(6)
	v_fma_f32 v26, -v7, v92, v26
	v_fma_f32 v69, -v8, v93, v69
	v_add_f32_e32 v72, v25, v72
	v_fma_f32 v70, -v9, v94, v70
	v_fma_f32 v71, -v10, v95, v71
	ds_read_b128 v[92:95], v78 offset:6832
	s_waitcnt lgkmcnt(6)
	v_fma_f32 v26, -v11, v96, v26
	v_add_f32_e32 v73, v73, v74
	v_fma_f32 v69, -v12, v97, v69
	v_fma_f32 v70, -v13, v98, v70
	v_fma_f32 v71, -v14, v99, v71
	v_add_f32_e32 v25, v72, v73
	ds_read_b128 v[96:99], v78 offset:6848
	s_waitcnt lgkmcnt(6)
	v_fma_f32 v26, -v15, v100, v26
	v_fma_f32 v69, -v16, v101, v69
	v_fma_f32 v70, -v66, v102, v70
	v_fma_f32 v71, -v17, v103, v71
	ds_read_b128 v[100:103], v78 offset:6864
	s_waitcnt lgkmcnt(6)
	v_fma_f32 v26, -v18, v104, v26
	v_fma_f32 v69, -v19, v105, v69
	v_fma_f32 v70, -v20, v106, v70
	v_fma_f32 v71, -v21, v107, v71
	ds_read_b128 v[104:107], v78 offset:6880
	s_waitcnt lgkmcnt(6)
	v_fma_f32 v26, -v22, v108, v26
	v_fma_f32 v69, -v23, v109, v69
	v_fma_f32 v70, -v24, v110, v70
	v_mov_b32_e32 v75, v111
	ds_read_b128 v[108:111], v78 offset:6896
	s_waitcnt lgkmcnt(6)
	v_fma_f32 v27, -v2, v84, v27
	v_fma_f32 v72, -v3, v85, 0
	v_fma_f32 v73, -v5, v86, 0
	v_fma_f32 v71, -v25, v75, v71
	v_fma_f32 v74, -v6, v87, 0
	ds_read_b128 v[84:87], v78 offset:7072
	s_waitcnt lgkmcnt(6)
	v_fma_f32 v27, -v7, v88, v27
	v_fma_f32 v72, -v8, v89, v72
	v_add_f32_e32 v69, v26, v69
	v_fma_f32 v73, -v9, v90, v73
	v_fma_f32 v74, -v10, v91, v74
	ds_read_b128 v[88:91], v78 offset:7088
	s_waitcnt lgkmcnt(6)
	v_fma_f32 v27, -v11, v92, v27
	v_add_f32_e32 v70, v70, v71
	v_fma_f32 v72, -v12, v93, v72
	v_fma_f32 v73, -v13, v94, v73
	v_fma_f32 v74, -v14, v95, v74
	v_add_f32_e32 v26, v69, v70
	ds_read_b128 v[92:95], v78 offset:7104
	s_waitcnt lgkmcnt(6)
	v_fma_f32 v27, -v15, v96, v27
	v_fma_f32 v72, -v16, v97, v72
	v_fma_f32 v73, -v66, v98, v73
	v_fma_f32 v74, -v17, v99, v74
	ds_read_b128 v[96:99], v78 offset:7120
	s_waitcnt lgkmcnt(6)
	v_fma_f32 v27, -v18, v100, v27
	v_fma_f32 v72, -v19, v101, v72
	v_fma_f32 v73, -v20, v102, v73
	v_fma_f32 v74, -v21, v103, v74
	ds_read_b128 v[100:103], v78 offset:7136
	s_waitcnt lgkmcnt(6)
	v_fma_f32 v27, -v22, v104, v27
	v_fma_f32 v72, -v23, v105, v72
	v_fma_f32 v73, -v24, v106, v73
	v_fma_f32 v74, -v25, v107, v74
	ds_read_b128 v[104:107], v78 offset:7152
	s_waitcnt lgkmcnt(6)
	v_mov_b32_e32 v76, v108
	ds_read_b128 v[108:111], v78 offset:7168
	s_waitcnt lgkmcnt(6)
	v_fma_f32 v29, -v2, v84, v29
	v_fma_f32 v69, -v3, v85, 0
	v_fma_f32 v70, -v5, v86, 0
	v_fma_f32 v27, -v26, v76, v27
	v_fma_f32 v71, -v6, v87, 0
	ds_read_b128 v[84:87], v78 offset:7344
	s_waitcnt lgkmcnt(6)
	v_fma_f32 v29, -v7, v88, v29
	v_fma_f32 v69, -v8, v89, v69
	v_add_f32_e32 v72, v27, v72
	v_fma_f32 v70, -v9, v90, v70
	v_fma_f32 v71, -v10, v91, v71
	ds_read_b128 v[88:91], v78 offset:7360
	s_waitcnt lgkmcnt(6)
	v_fma_f32 v29, -v11, v92, v29
	v_add_f32_e32 v73, v73, v74
	v_fma_f32 v69, -v12, v93, v69
	v_fma_f32 v70, -v13, v94, v70
	v_fma_f32 v71, -v14, v95, v71
	v_add_f32_e32 v27, v72, v73
	ds_read_b128 v[92:95], v78 offset:7376
	s_waitcnt lgkmcnt(6)
	v_fma_f32 v29, -v15, v96, v29
	v_fma_f32 v69, -v16, v97, v69
	v_fma_f32 v70, -v66, v98, v70
	v_fma_f32 v71, -v17, v99, v71
	ds_read_b128 v[96:99], v78 offset:7392
	s_waitcnt lgkmcnt(6)
	v_fma_f32 v29, -v18, v100, v29
	v_fma_f32 v69, -v19, v101, v69
	v_fma_f32 v70, -v20, v102, v70
	v_fma_f32 v71, -v21, v103, v71
	ds_read_b128 v[100:103], v78 offset:7408
	s_waitcnt lgkmcnt(6)
	v_fma_f32 v29, -v22, v104, v29
	v_fma_f32 v69, -v23, v105, v69
	v_fma_f32 v70, -v24, v106, v70
	v_fma_f32 v71, -v25, v107, v71
	ds_read_b128 v[104:107], v78 offset:7424
	s_waitcnt lgkmcnt(6)
	v_fma_f32 v29, -v26, v108, v29
	v_mov_b32_e32 v75, v109
	ds_read_b128 v[108:111], v78 offset:7440
	s_waitcnt lgkmcnt(6)
	v_fma_f32 v30, -v2, v84, v30
	v_fma_f32 v72, -v3, v85, 0
	v_fma_f32 v73, -v5, v86, 0
	v_fma_f32 v69, -v27, v75, v69
	v_fma_f32 v74, -v6, v87, 0
	ds_read_b128 v[84:87], v78 offset:7616
	s_waitcnt lgkmcnt(6)
	v_fma_f32 v30, -v7, v88, v30
	v_fma_f32 v72, -v8, v89, v72
	v_add_f32_e32 v69, v29, v69
	v_fma_f32 v73, -v9, v90, v73
	v_fma_f32 v74, -v10, v91, v74
	ds_read_b128 v[88:91], v78 offset:7632
	s_waitcnt lgkmcnt(6)
	v_fma_f32 v30, -v11, v92, v30
	v_add_f32_e32 v70, v70, v71
	v_fma_f32 v72, -v12, v93, v72
	v_fma_f32 v73, -v13, v94, v73
	v_fma_f32 v74, -v14, v95, v74
	v_add_f32_e32 v29, v69, v70
	ds_read_b128 v[92:95], v78 offset:7648
	s_waitcnt lgkmcnt(6)
	v_fma_f32 v30, -v15, v96, v30
	v_fma_f32 v72, -v16, v97, v72
	v_fma_f32 v73, -v66, v98, v73
	v_fma_f32 v74, -v17, v99, v74
	ds_read_b128 v[96:99], v78 offset:7664
	s_waitcnt lgkmcnt(6)
	v_fma_f32 v30, -v18, v100, v30
	v_fma_f32 v72, -v19, v101, v72
	v_fma_f32 v73, -v20, v102, v73
	v_fma_f32 v74, -v21, v103, v74
	ds_read_b128 v[100:103], v78 offset:7680
	s_waitcnt lgkmcnt(6)
	v_fma_f32 v30, -v22, v104, v30
	v_fma_f32 v72, -v23, v105, v72
	v_fma_f32 v73, -v24, v106, v73
	v_fma_f32 v74, -v25, v107, v74
	ds_read_b128 v[104:107], v78 offset:7696
	s_waitcnt lgkmcnt(6)
	v_fma_f32 v30, -v26, v108, v30
	v_fma_f32 v72, -v27, v109, v72
	v_mov_b32_e32 v76, v110
	ds_read_b128 v[108:111], v78 offset:7712
	s_waitcnt lgkmcnt(6)
	v_fma_f32 v33, -v2, v84, v33
	v_fma_f32 v69, -v3, v85, 0
	v_fma_f32 v70, -v5, v86, 0
	v_fma_f32 v73, -v29, v76, v73
	v_fma_f32 v71, -v6, v87, 0
	ds_read_b128 v[84:87], v78 offset:7888
	s_waitcnt lgkmcnt(6)
	v_fma_f32 v33, -v7, v88, v33
	v_fma_f32 v69, -v8, v89, v69
	v_add_f32_e32 v72, v30, v72
	v_fma_f32 v70, -v9, v90, v70
	v_fma_f32 v71, -v10, v91, v71
	ds_read_b128 v[88:91], v78 offset:7904
	s_waitcnt lgkmcnt(6)
; DI void gdn_prep(const Params& p, int item, unsigned char* smem) {
;     ...
;         for (int i = 1; i < 64; ++i) {
;             float a = X[i];
;             int dep; asm volatile("v_and_b32 %0, 0, %1" : "=v"(dep) : "v"(X[i - 1]));
;             const float* Lr = sL + i * 68 + dep;
;             float b0 = 0.f, b1 = 0.f, b2 = 0.f;
; #pragma unroll
;             for (int j4 = 0; j4 < (i + 3) / 4; ++j4) {
;                 const f32x4 l = *(const f32x4*)(Lr + 4 * j4);
;                 if (4 * j4 + 0 < i) a -= l.x * X[4 * j4 + 0];
;                 if (4 * j4 + 1 < i) b0 -= l.y * X[4 * j4 + 1];
;                 if (4 * j4 + 2 < i) b1 -= l.z * X[4 * j4 + 2];
;                 if (4 * j4 + 3 < i) b2 -= l.w * X[4 * j4 + 3];
;             }
;             X[i] = (a + b0) + (b1 + b2);
	v_fma_f32 v33, -v11, v92, v33
	v_add_f32_e32 v73, v73, v74
	v_fma_f32 v69, -v12, v93, v69
	v_fma_f32 v70, -v13, v94, v70
	v_fma_f32 v71, -v14, v95, v71
	v_add_f32_e32 v30, v72, v73
	ds_read_b128 v[92:95], v78 offset:7920
	s_waitcnt lgkmcnt(6)
	v_fma_f32 v33, -v15, v96, v33
	v_fma_f32 v69, -v16, v97, v69
	v_fma_f32 v70, -v66, v98, v70
	v_fma_f32 v71, -v17, v99, v71
	ds_read_b128 v[96:99], v78 offset:7936
	s_waitcnt lgkmcnt(6)
	v_fma_f32 v33, -v18, v100, v33
	v_fma_f32 v69, -v19, v101, v69
	v_fma_f32 v70, -v20, v102, v70
	v_fma_f32 v71, -v21, v103, v71
	ds_read_b128 v[100:103], v78 offset:7952
	s_waitcnt lgkmcnt(6)
	v_fma_f32 v33, -v22, v104, v33
	v_fma_f32 v69, -v23, v105, v69
	v_fma_f32 v70, -v24, v106, v70
	v_fma_f32 v71, -v25, v107, v71
	ds_read_b128 v[104:107], v78 offset:7968
	s_waitcnt lgkmcnt(6)
	v_fma_f32 v33, -v26, v108, v33
	v_fma_f32 v69, -v27, v109, v69
	v_fma_f32 v70, -v29, v110, v70
	v_mov_b32_e32 v75, v111
	ds_read_b128 v[108:111], v78 offset:7984
	s_waitcnt lgkmcnt(6)
	v_fma_f32 v34, -v2, v84, v34
	v_fma_f32 v72, -v3, v85, 0
	v_fma_f32 v73, -v5, v86, 0
	v_fma_f32 v71, -v30, v75, v71
	v_fma_f32 v74, -v6, v87, 0
	ds_read_b128 v[84:87], v78 offset:8000
	s_waitcnt lgkmcnt(6)
	v_fma_f32 v34, -v7, v88, v34
	v_fma_f32 v72, -v8, v89, v72
	v_add_f32_e32 v69, v33, v69
	v_fma_f32 v73, -v9, v90, v73
	v_fma_f32 v74, -v10, v91, v74
	ds_read_b128 v[88:91], v78 offset:8160
	s_waitcnt lgkmcnt(6)
	v_fma_f32 v34, -v11, v92, v34
	v_add_f32_e32 v70, v70, v71
	v_fma_f32 v72, -v12, v93, v72
	v_fma_f32 v73, -v13, v94, v73
	v_fma_f32 v74, -v14, v95, v74
	v_add_f32_e32 v33, v69, v70
	ds_read_b128 v[92:95], v78 offset:8176
	s_waitcnt lgkmcnt(6)
	v_fma_f32 v34, -v15, v96, v34
	v_fma_f32 v72, -v16, v97, v72
	v_fma_f32 v73, -v66, v98, v73
	v_fma_f32 v74, -v17, v99, v74
	ds_read_b128 v[96:99], v78 offset:8192
	s_waitcnt lgkmcnt(6)
	v_fma_f32 v34, -v18, v100, v34
	v_fma_f32 v72, -v19, v101, v72
	v_fma_f32 v73, -v20, v102, v73
	v_fma_f32 v74, -v21, v103, v74
	ds_read_b128 v[100:103], v78 offset:8208
	s_waitcnt lgkmcnt(6)
	v_fma_f32 v34, -v22, v104, v34
	v_fma_f32 v72, -v23, v105, v72
	v_fma_f32 v73, -v24, v106, v73
	v_fma_f32 v74, -v25, v107, v74
	ds_read_b128 v[104:107], v78 offset:8224
	s_waitcnt lgkmcnt(6)
	v_fma_f32 v34, -v26, v108, v34
	v_fma_f32 v72, -v27, v109, v72
	v_fma_f32 v73, -v29, v110, v73
	v_fma_f32 v74, -v30, v111, v74
	ds_read_b128 v[108:111], v78 offset:8240
	s_waitcnt lgkmcnt(6)
	v_mov_b32_e32 v76, v84
	ds_read_b128 v[84:87], v78 offset:8256
	s_waitcnt lgkmcnt(6)
	v_fma_f32 v36, -v2, v88, v36
	v_fma_f32 v69, -v3, v89, 0
	v_fma_f32 v70, -v5, v90, 0
	v_fma_f32 v34, -v33, v76, v34
	v_fma_f32 v71, -v6, v91, 0
	ds_read_b128 v[88:91], v78 offset:8272
	s_waitcnt lgkmcnt(6)
	v_fma_f32 v36, -v7, v92, v36
	v_fma_f32 v69, -v8, v93, v69
	v_add_f32_e32 v72, v34, v72
	v_fma_f32 v70, -v9, v94, v70
	v_fma_f32 v71, -v10, v95, v71
	ds_read_b128 v[92:95], v78 offset:8432
	s_waitcnt lgkmcnt(6)
	v_fma_f32 v36, -v11, v96, v36
	v_add_f32_e32 v73, v73, v74
	v_fma_f32 v69, -v12, v97, v69
	v_fma_f32 v70, -v13, v98, v70
	v_fma_f32 v71, -v14, v99, v71
	v_add_f32_e32 v34, v72, v73
	ds_read_b128 v[96:99], v78 offset:8448
	s_waitcnt lgkmcnt(6)
	v_fma_f32 v36, -v15, v100, v36
	v_fma_f32 v69, -v16, v101, v69
	v_fma_f32 v70, -v66, v102, v70
	v_fma_f32 v71, -v17, v103, v71
	ds_read_b128 v[100:103], v78 offset:8464
	s_waitcnt lgkmcnt(6)
	v_fma_f32 v36, -v18, v104, v36
	v_fma_f32 v69, -v19, v105, v69
	v_fma_f32 v70, -v20, v106, v70
	v_fma_f32 v71, -v21, v107, v71
	ds_read_b128 v[104:107], v78 offset:8480
	s_waitcnt lgkmcnt(6)
	v_fma_f32 v36, -v22, v108, v36
	v_fma_f32 v69, -v23, v109, v69
	v_fma_f32 v70, -v24, v110, v70
	v_fma_f32 v71, -v25, v111, v71
	ds_read_b128 v[108:111], v78 offset:8496
	s_waitcnt lgkmcnt(6)
	v_fma_f32 v36, -v26, v84, v36
	v_fma_f32 v69, -v27, v85, v69
	v_fma_f32 v70, -v29, v86, v70
	v_fma_f32 v71, -v30, v87, v71
	ds_read_b128 v[84:87], v78 offset:8512
	s_waitcnt lgkmcnt(6)
	v_fma_f32 v36, -v33, v88, v36
	v_mov_b32_e32 v75, v89
	ds_read_b128 v[88:91], v78 offset:8528
	s_waitcnt lgkmcnt(6)
	v_fma_f32 v37, -v2, v92, v37
	v_fma_f32 v72, -v3, v93, 0
	v_fma_f32 v73, -v5, v94, 0
	v_fma_f32 v69, -v34, v75, v69
	v_fma_f32 v74, -v6, v95, 0
	ds_read_b128 v[92:95], v78 offset:8544
	s_waitcnt lgkmcnt(6)
	v_fma_f32 v37, -v7, v96, v37
	v_fma_f32 v72, -v8, v97, v72
	v_add_f32_e32 v69, v36, v69
	v_fma_f32 v73, -v9, v98, v73
	v_fma_f32 v74, -v10, v99, v74
	ds_read_b128 v[96:99], v78 offset:8704
	s_waitcnt lgkmcnt(6)
	v_fma_f32 v37, -v11, v100, v37
	v_add_f32_e32 v70, v70, v71
	v_fma_f32 v72, -v12, v101, v72
	v_fma_f32 v73, -v13, v102, v73
	v_fma_f32 v74, -v14, v103, v74
	v_add_f32_e32 v36, v69, v70
	ds_read_b128 v[100:103], v78 offset:8720
	s_waitcnt lgkmcnt(6)
	v_fma_f32 v37, -v15, v104, v37
	v_fma_f32 v72, -v16, v105, v72
	v_fma_f32 v73, -v66, v106, v73
	v_fma_f32 v74, -v17, v107, v74
	ds_read_b128 v[104:107], v78 offset:8736
	s_waitcnt lgkmcnt(6)
	v_fma_f32 v37, -v18, v108, v37
	v_fma_f32 v72, -v19, v109, v72
	v_fma_f32 v73, -v20, v110, v73
	v_fma_f32 v74, -v21, v111, v74
	ds_read_b128 v[108:111], v78 offset:8752
	s_waitcnt lgkmcnt(6)
	v_fma_f32 v37, -v22, v84, v37
	v_fma_f32 v72, -v23, v85, v72
	v_fma_f32 v73, -v24, v86, v73
	v_fma_f32 v74, -v25, v87, v74
	ds_read_b128 v[84:87], v78 offset:8768
	s_waitcnt lgkmcnt(6)
	v_fma_f32 v37, -v26, v88, v37
	v_fma_f32 v72, -v27, v89, v72
	v_fma_f32 v73, -v29, v90, v73
	v_fma_f32 v74, -v30, v91, v74
	ds_read_b128 v[88:91], v78 offset:8784
	s_waitcnt lgkmcnt(6)
	v_fma_f32 v37, -v33, v92, v37
	v_fma_f32 v72, -v34, v93, v72
	v_mov_b32_e32 v76, v94
	ds_read_b128 v[92:95], v78 offset:8800
	s_waitcnt lgkmcnt(6)
; DI void gdn_prep(const Params& p, int item, unsigned char* smem) {
;     ...
;         for (int i = 1; i < 64; ++i) {
;             float a = X[i];
;             int dep; asm volatile("v_and_b32 %0, 0, %1" : "=v"(dep) : "v"(X[i - 1]));
;             const float* Lr = sL + i * 68 + dep;
;             float b0 = 0.f, b1 = 0.f, b2 = 0.f;
; #pragma unroll
;             for (int j4 = 0; j4 < (i + 3) / 4; ++j4) {
;                 const f32x4 l = *(const f32x4*)(Lr + 4 * j4);
;                 if (4 * j4 + 0 < i) a -= l.x * X[4 * j4 + 0];
;                 if (4 * j4 + 1 < i) b0 -= l.y * X[4 * j4 + 1];
;                 if (4 * j4 + 2 < i) b1 -= l.z * X[4 * j4 + 2];
;                 if (4 * j4 + 3 < i) b2 -= l.w * X[4 * j4 + 3];
;             }
;             X[i] = (a + b0) + (b1 + b2);
	v_fma_f32 v39, -v2, v96, v39
	v_fma_f32 v69, -v3, v97, 0
	v_fma_f32 v70, -v5, v98, 0
	v_fma_f32 v73, -v36, v76, v73
	v_fma_f32 v71, -v6, v99, 0
	ds_read_b128 v[96:99], v78 offset:8816
	s_waitcnt lgkmcnt(6)
	v_fma_f32 v39, -v7, v100, v39
	v_fma_f32 v69, -v8, v101, v69
	v_add_f32_e32 v72, v37, v72
	v_fma_f32 v70, -v9, v102, v70
	v_fma_f32 v71, -v10, v103, v71
	ds_read_b128 v[100:103], v78 offset:8976
	s_waitcnt lgkmcnt(6)
	v_fma_f32 v39, -v11, v104, v39
	v_add_f32_e32 v73, v73, v74
	v_fma_f32 v69, -v12, v105, v69
	v_fma_f32 v70, -v13, v106, v70
	v_fma_f32 v71, -v14, v107, v71
	v_add_f32_e32 v37, v72, v73
	ds_read_b128 v[104:107], v78 offset:8992
	s_waitcnt lgkmcnt(6)
	v_fma_f32 v39, -v15, v108, v39
	v_fma_f32 v69, -v16, v109, v69
	v_fma_f32 v70, -v66, v110, v70
	v_fma_f32 v71, -v17, v111, v71
	ds_read_b128 v[108:111], v78 offset:9008
	s_waitcnt lgkmcnt(6)
	v_fma_f32 v39, -v18, v84, v39
	v_fma_f32 v69, -v19, v85, v69
	v_fma_f32 v70, -v20, v86, v70
	v_fma_f32 v71, -v21, v87, v71
	ds_read_b128 v[84:87], v78 offset:9024
	s_waitcnt lgkmcnt(6)
	v_fma_f32 v39, -v22, v88, v39
	v_fma_f32 v69, -v23, v89, v69
	v_fma_f32 v70, -v24, v90, v70
	v_fma_f32 v71, -v25, v91, v71
	ds_read_b128 v[88:91], v78 offset:9040
	s_waitcnt lgkmcnt(6)
	v_fma_f32 v39, -v26, v92, v39
	v_fma_f32 v69, -v27, v93, v69
	v_fma_f32 v70, -v29, v94, v70
	v_fma_f32 v71, -v30, v95, v71
	ds_read_b128 v[92:95], v78 offset:9056
	s_waitcnt lgkmcnt(6)
	v_fma_f32 v39, -v33, v96, v39
	v_fma_f32 v69, -v34, v97, v69
	v_fma_f32 v70, -v36, v98, v70
	v_mov_b32_e32 v75, v99
	ds_read_b128 v[96:99], v78 offset:9072
	s_waitcnt lgkmcnt(6)
	v_fma_f32 v41, -v2, v100, v41
	v_fma_f32 v72, -v3, v101, 0
	v_fma_f32 v73, -v5, v102, 0
	v_fma_f32 v71, -v37, v75, v71
	v_fma_f32 v74, -v6, v103, 0
	ds_read_b128 v[100:103], v78 offset:9088
	s_waitcnt lgkmcnt(6)
	v_fma_f32 v41, -v7, v104, v41
	v_fma_f32 v72, -v8, v105, v72
	v_add_f32_e32 v69, v39, v69
	v_fma_f32 v73, -v9, v106, v73
	v_fma_f32 v74, -v10, v107, v74
	ds_read_b128 v[104:107], v78 offset:9104
	s_waitcnt lgkmcnt(6)
	v_fma_f32 v41, -v11, v108, v41
	v_add_f32_e32 v70, v70, v71
	v_fma_f32 v72, -v12, v109, v72
	v_fma_f32 v73, -v13, v110, v73
	v_fma_f32 v74, -v14, v111, v74
	v_add_f32_e32 v39, v69, v70
	ds_read_b128 v[108:111], v78 offset:9248
	s_waitcnt lgkmcnt(6)
	v_fma_f32 v41, -v15, v84, v41
	v_fma_f32 v72, -v16, v85, v72
	v_fma_f32 v73, -v66, v86, v73
	v_fma_f32 v74, -v17, v87, v74
	ds_read_b128 v[84:87], v78 offset:9264
	s_waitcnt lgkmcnt(6)
	v_fma_f32 v41, -v18, v88, v41
	v_fma_f32 v72, -v19, v89, v72
	v_fma_f32 v73, -v20, v90, v73
	v_fma_f32 v74, -v21, v91, v74
	ds_read_b128 v[88:91], v78 offset:9280
	s_waitcnt lgkmcnt(6)
	v_fma_f32 v41, -v22, v92, v41
	v_fma_f32 v72, -v23, v93, v72
	v_fma_f32 v73, -v24, v94, v73
	v_fma_f32 v74, -v25, v95, v74
	ds_read_b128 v[92:95], v78 offset:9296
	s_waitcnt lgkmcnt(6)
	v_fma_f32 v41, -v26, v96, v41
	v_fma_f32 v72, -v27, v97, v72
	v_fma_f32 v73, -v29, v98, v73
	v_fma_f32 v74, -v30, v99, v74
	ds_read_b128 v[96:99], v78 offset:9312
	s_waitcnt lgkmcnt(6)
	v_fma_f32 v41, -v33, v100, v41
	v_fma_f32 v72, -v34, v101, v72
	v_fma_f32 v73, -v36, v102, v73
	v_fma_f32 v74, -v37, v103, v74
	ds_read_b128 v[100:103], v78 offset:9328
	s_waitcnt lgkmcnt(6)
	v_mov_b32_e32 v76, v104
	ds_read_b128 v[104:107], v78 offset:9344
	s_waitcnt lgkmcnt(6)
	v_fma_f32 v42, -v2, v108, v42
	v_fma_f32 v69, -v3, v109, 0
	v_fma_f32 v70, -v5, v110, 0
	v_fma_f32 v41, -v39, v76, v41
	v_fma_f32 v71, -v6, v111, 0
	ds_read_b128 v[108:111], v78 offset:9360
	s_waitcnt lgkmcnt(6)
	v_fma_f32 v42, -v7, v84, v42
	v_fma_f32 v69, -v8, v85, v69
	v_add_f32_e32 v72, v41, v72
	v_fma_f32 v70, -v9, v86, v70
	v_fma_f32 v71, -v10, v87, v71
	ds_read_b128 v[84:87], v78 offset:9376
	s_waitcnt lgkmcnt(6)
	v_fma_f32 v42, -v11, v88, v42
	v_add_f32_e32 v73, v73, v74
	v_fma_f32 v69, -v12, v89, v69
	v_fma_f32 v70, -v13, v90, v70
	v_fma_f32 v71, -v14, v91, v71
	v_add_f32_e32 v41, v72, v73
	ds_read_b128 v[88:91], v78 offset:9520
	s_waitcnt lgkmcnt(6)
	v_fma_f32 v42, -v15, v92, v42
	v_fma_f32 v69, -v16, v93, v69
	v_fma_f32 v70, -v66, v94, v70
	v_fma_f32 v71, -v17, v95, v71
	ds_read_b128 v[92:95], v78 offset:9536
	s_waitcnt lgkmcnt(6)
	v_fma_f32 v42, -v18, v96, v42
	v_fma_f32 v69, -v19, v97, v69
	v_fma_f32 v70, -v20, v98, v70
	v_fma_f32 v71, -v21, v99, v71
	ds_read_b128 v[96:99], v78 offset:9552
	s_waitcnt lgkmcnt(6)
	v_fma_f32 v42, -v22, v100, v42
	v_fma_f32 v69, -v23, v101, v69
	v_fma_f32 v70, -v24, v102, v70
	v_fma_f32 v71, -v25, v103, v71
	ds_read_b128 v[100:103], v78 offset:9568
	s_waitcnt lgkmcnt(6)
	v_fma_f32 v42, -v26, v104, v42
	v_fma_f32 v69, -v27, v105, v69
	v_fma_f32 v70, -v29, v106, v70
	v_fma_f32 v71, -v30, v107, v71
	ds_read_b128 v[104:107], v78 offset:9584
	s_waitcnt lgkmcnt(6)
	v_fma_f32 v42, -v33, v108, v42
	v_fma_f32 v69, -v34, v109, v69
	v_fma_f32 v70, -v36, v110, v70
	v_fma_f32 v71, -v37, v111, v71
	ds_read_b128 v[108:111], v78 offset:9600
	s_waitcnt lgkmcnt(6)
	v_fma_f32 v42, -v39, v84, v42
	v_mov_b32_e32 v75, v85
	ds_read_b128 v[84:87], v78 offset:9616
	s_waitcnt lgkmcnt(6)
	v_fma_f32 v44, -v2, v88, v44
	v_fma_f32 v72, -v3, v89, 0
	v_fma_f32 v73, -v5, v90, 0
	v_fma_f32 v69, -v41, v75, v69
	v_fma_f32 v74, -v6, v91, 0
	ds_read_b128 v[88:91], v78 offset:9632
	s_waitcnt lgkmcnt(6)
	v_fma_f32 v44, -v7, v92, v44
	v_fma_f32 v72, -v8, v93, v72
	v_add_f32_e32 v69, v42, v69
	v_fma_f32 v73, -v9, v94, v73
	v_fma_f32 v74, -v10, v95, v74
	ds_read_b128 v[92:95], v78 offset:9648
	s_waitcnt lgkmcnt(6)
	v_fma_f32 v44, -v11, v96, v44
	v_add_f32_e32 v70, v70, v71
	v_fma_f32 v72, -v12, v97, v72
	v_fma_f32 v73, -v13, v98, v73
	v_fma_f32 v74, -v14, v99, v74
	v_add_f32_e32 v42, v69, v70
	ds_read_b128 v[96:99], v78 offset:9792
	s_waitcnt lgkmcnt(6)
; DI void gdn_prep(const Params& p, int item, unsigned char* smem) {
;     ...
;         for (int i = 1; i < 64; ++i) {
;             float a = X[i];
;             int dep; asm volatile("v_and_b32 %0, 0, %1" : "=v"(dep) : "v"(X[i - 1]));
;             const float* Lr = sL + i * 68 + dep;
;             float b0 = 0.f, b1 = 0.f, b2 = 0.f;
; #pragma unroll
;             for (int j4 = 0; j4 < (i + 3) / 4; ++j4) {
;                 const f32x4 l = *(const f32x4*)(Lr + 4 * j4);
;                 if (4 * j4 + 0 < i) a -= l.x * X[4 * j4 + 0];
;                 if (4 * j4 + 1 < i) b0 -= l.y * X[4 * j4 + 1];
;                 if (4 * j4 + 2 < i) b1 -= l.z * X[4 * j4 + 2];
;                 if (4 * j4 + 3 < i) b2 -= l.w * X[4 * j4 + 3];
;             }
;             X[i] = (a + b0) + (b1 + b2);
	v_fma_f32 v44, -v15, v100, v44
	v_fma_f32 v72, -v16, v101, v72
	v_fma_f32 v73, -v66, v102, v73
	v_fma_f32 v74, -v17, v103, v74
	ds_read_b128 v[100:103], v78 offset:9808
	s_waitcnt lgkmcnt(6)
	v_fma_f32 v44, -v18, v104, v44
	v_fma_f32 v72, -v19, v105, v72
	v_fma_f32 v73, -v20, v106, v73
	v_fma_f32 v74, -v21, v107, v74
	ds_read_b128 v[104:107], v78 offset:9824
	s_waitcnt lgkmcnt(6)
	v_fma_f32 v44, -v22, v108, v44
	v_fma_f32 v72, -v23, v109, v72
	v_fma_f32 v73, -v24, v110, v73
	v_fma_f32 v74, -v25, v111, v74
	ds_read_b128 v[108:111], v78 offset:9840
	s_waitcnt lgkmcnt(6)
	v_fma_f32 v44, -v26, v84, v44
	v_fma_f32 v72, -v27, v85, v72
	v_fma_f32 v73, -v29, v86, v73
	v_fma_f32 v74, -v30, v87, v74
	ds_read_b128 v[84:87], v78 offset:9856
	s_waitcnt lgkmcnt(6)
	v_fma_f32 v44, -v33, v88, v44
	v_fma_f32 v72, -v34, v89, v72
	v_fma_f32 v73, -v36, v90, v73
	v_fma_f32 v74, -v37, v91, v74
	ds_read_b128 v[88:91], v78 offset:9872
	s_waitcnt lgkmcnt(6)
	v_fma_f32 v44, -v39, v92, v44
	v_fma_f32 v72, -v41, v93, v72
	v_mov_b32_e32 v76, v94
	ds_read_b128 v[92:95], v78 offset:9888
	s_waitcnt lgkmcnt(6)
	v_fma_f32 v48, -v2, v96, v48
	v_fma_f32 v69, -v3, v97, 0
	v_fma_f32 v70, -v5, v98, 0
	v_fma_f32 v73, -v42, v76, v73
	v_fma_f32 v71, -v6, v99, 0
	ds_read_b128 v[96:99], v78 offset:9904
	s_waitcnt lgkmcnt(6)
	v_fma_f32 v48, -v7, v100, v48
	v_fma_f32 v69, -v8, v101, v69
	v_add_f32_e32 v72, v44, v72
	v_fma_f32 v70, -v9, v102, v70
	v_fma_f32 v71, -v10, v103, v71
	ds_read_b128 v[100:103], v78 offset:9920
	s_waitcnt lgkmcnt(6)
	v_fma_f32 v48, -v11, v104, v48
	v_add_f32_e32 v73, v73, v74
	v_fma_f32 v69, -v12, v105, v69
	v_fma_f32 v70, -v13, v106, v70
	v_fma_f32 v71, -v14, v107, v71
	v_add_f32_e32 v44, v72, v73
	ds_read_b128 v[104:107], v78 offset:10064
	s_waitcnt lgkmcnt(6)
	v_fma_f32 v48, -v15, v108, v48
	v_fma_f32 v69, -v16, v109, v69
	v_fma_f32 v70, -v66, v110, v70
	v_fma_f32 v71, -v17, v111, v71
	ds_read_b128 v[108:111], v78 offset:10080
	s_waitcnt lgkmcnt(6)
	v_fma_f32 v48, -v18, v84, v48
	v_fma_f32 v69, -v19, v85, v69
	v_fma_f32 v70, -v20, v86, v70
	v_fma_f32 v71, -v21, v87, v71
	ds_read_b128 v[84:87], v78 offset:10096
	s_waitcnt lgkmcnt(6)
	v_fma_f32 v48, -v22, v88, v48
	v_fma_f32 v69, -v23, v89, v69
	v_fma_f32 v70, -v24, v90, v70
	v_fma_f32 v71, -v25, v91, v71
	ds_read_b128 v[88:91], v78 offset:10112
	s_waitcnt lgkmcnt(6)
	v_fma_f32 v48, -v26, v92, v48
	v_fma_f32 v69, -v27, v93, v69
	v_fma_f32 v70, -v29, v94, v70
	v_fma_f32 v71, -v30, v95, v71
	ds_read_b128 v[92:95], v78 offset:10128
	s_waitcnt lgkmcnt(6)
	v_fma_f32 v48, -v33, v96, v48
	v_fma_f32 v69, -v34, v97, v69
	v_fma_f32 v70, -v36, v98, v70
	v_fma_f32 v71, -v37, v99, v71
	ds_read_b128 v[96:99], v78 offset:10144
	s_waitcnt lgkmcnt(6)
	v_fma_f32 v48, -v39, v100, v48
	v_fma_f32 v69, -v41, v101, v69
	v_fma_f32 v70, -v42, v102, v70
	v_mov_b32_e32 v75, v103
	ds_read_b128 v[100:103], v78 offset:10160
	s_waitcnt lgkmcnt(6)
	v_fma_f32 v49, -v2, v104, v49
	v_fma_f32 v72, -v3, v105, 0
	v_fma_f32 v73, -v5, v106, 0
	v_fma_f32 v71, -v44, v75, v71
	v_fma_f32 v74, -v6, v107, 0
	ds_read_b128 v[104:107], v78 offset:10176
	s_waitcnt lgkmcnt(6)
	v_fma_f32 v49, -v7, v108, v49
	v_fma_f32 v72, -v8, v109, v72
	v_add_f32_e32 v69, v48, v69
	v_fma_f32 v73, -v9, v110, v73
	v_fma_f32 v74, -v10, v111, v74
	ds_read_b128 v[108:111], v78 offset:10192
	s_waitcnt lgkmcnt(6)
	v_fma_f32 v49, -v11, v84, v49
	v_add_f32_e32 v70, v70, v71
	v_fma_f32 v72, -v12, v85, v72
	v_fma_f32 v73, -v13, v86, v73
	v_fma_f32 v74, -v14, v87, v74
	v_add_f32_e32 v48, v69, v70
	ds_read_b128 v[84:87], v78 offset:10208
	s_waitcnt lgkmcnt(6)
	v_fma_f32 v49, -v15, v88, v49
	v_fma_f32 v72, -v16, v89, v72
	v_fma_f32 v73, -v66, v90, v73
	v_fma_f32 v74, -v17, v91, v74
	ds_read_b128 v[88:91], v78 offset:10336
	s_waitcnt lgkmcnt(6)
	v_fma_f32 v49, -v18, v92, v49
	v_fma_f32 v72, -v19, v93, v72
	v_fma_f32 v73, -v20, v94, v73
	v_fma_f32 v74, -v21, v95, v74
	ds_read_b128 v[92:95], v78 offset:10352
	s_waitcnt lgkmcnt(6)
	v_fma_f32 v49, -v22, v96, v49
	v_fma_f32 v72, -v23, v97, v72
	v_fma_f32 v73, -v24, v98, v73
	v_fma_f32 v74, -v25, v99, v74
	ds_read_b128 v[96:99], v78 offset:10368
	s_waitcnt lgkmcnt(6)
	v_fma_f32 v49, -v26, v100, v49
	v_fma_f32 v72, -v27, v101, v72
	v_fma_f32 v73, -v29, v102, v73
	v_fma_f32 v74, -v30, v103, v74
	ds_read_b128 v[100:103], v78 offset:10384
	s_waitcnt lgkmcnt(6)
	v_fma_f32 v49, -v33, v104, v49
	v_fma_f32 v72, -v34, v105, v72
	v_fma_f32 v73, -v36, v106, v73
	v_fma_f32 v74, -v37, v107, v74
	ds_read_b128 v[104:107], v78 offset:10400
	s_waitcnt lgkmcnt(6)
	v_fma_f32 v49, -v39, v108, v49
	v_fma_f32 v72, -v41, v109, v72
	v_fma_f32 v73, -v42, v110, v73
	v_fma_f32 v74, -v44, v111, v74
	ds_read_b128 v[108:111], v78 offset:10416
	s_waitcnt lgkmcnt(6)
	v_mov_b32_e32 v76, v84
	ds_read_b128 v[84:87], v78 offset:10432
	s_waitcnt lgkmcnt(6)
	v_fma_f32 v51, -v2, v88, v51
	v_fma_f32 v69, -v3, v89, 0
	v_fma_f32 v70, -v5, v90, 0
	v_fma_f32 v49, -v48, v76, v49
	v_fma_f32 v71, -v6, v91, 0
	ds_read_b128 v[88:91], v78 offset:10448
	s_waitcnt lgkmcnt(6)
	v_fma_f32 v51, -v7, v92, v51
	v_fma_f32 v69, -v8, v93, v69
	v_add_f32_e32 v72, v49, v72
	v_fma_f32 v70, -v9, v94, v70
	v_fma_f32 v71, -v10, v95, v71
	ds_read_b128 v[92:95], v78 offset:10464
	s_waitcnt lgkmcnt(6)
	v_fma_f32 v51, -v11, v96, v51
	v_add_f32_e32 v73, v73, v74
	v_fma_f32 v69, -v12, v97, v69
	v_fma_f32 v70, -v13, v98, v70
	v_fma_f32 v71, -v14, v99, v71
	v_add_f32_e32 v49, v72, v73
	ds_read_b128 v[96:99], v78 offset:10480
	s_waitcnt lgkmcnt(6)
	v_fma_f32 v51, -v15, v100, v51
	v_fma_f32 v69, -v16, v101, v69
	v_fma_f32 v70, -v66, v102, v70
	v_fma_f32 v71, -v17, v103, v71
	ds_read_b128 v[100:103], v78 offset:10608
	s_waitcnt lgkmcnt(6)
; DI void gdn_prep(const Params& p, int item, unsigned char* smem) {
;     ...
;         for (int i = 1; i < 64; ++i) {
;             float a = X[i];
;             int dep; asm volatile("v_and_b32 %0, 0, %1" : "=v"(dep) : "v"(X[i - 1]));
;             const float* Lr = sL + i * 68 + dep;
;             float b0 = 0.f, b1 = 0.f, b2 = 0.f;
; #pragma unroll
;             for (int j4 = 0; j4 < (i + 3) / 4; ++j4) {
;                 const f32x4 l = *(const f32x4*)(Lr + 4 * j4);
;                 if (4 * j4 + 0 < i) a -= l.x * X[4 * j4 + 0];
;                 if (4 * j4 + 1 < i) b0 -= l.y * X[4 * j4 + 1];
;                 if (4 * j4 + 2 < i) b1 -= l.z * X[4 * j4 + 2];
;                 if (4 * j4 + 3 < i) b2 -= l.w * X[4 * j4 + 3];
;             }
;             X[i] = (a + b0) + (b1 + b2);
	v_fma_f32 v51, -v18, v104, v51
	v_fma_f32 v69, -v19, v105, v69
	v_fma_f32 v70, -v20, v106, v70
	v_fma_f32 v71, -v21, v107, v71
	ds_read_b128 v[104:107], v78 offset:10624
	s_waitcnt lgkmcnt(6)
	v_fma_f32 v51, -v22, v108, v51
	v_fma_f32 v69, -v23, v109, v69
	v_fma_f32 v70, -v24, v110, v70
	v_fma_f32 v71, -v25, v111, v71
	ds_read_b128 v[108:111], v78 offset:10640
	s_waitcnt lgkmcnt(6)
	v_fma_f32 v51, -v26, v84, v51
	v_fma_f32 v69, -v27, v85, v69
	v_fma_f32 v70, -v29, v86, v70
	v_fma_f32 v71, -v30, v87, v71
	ds_read_b128 v[84:87], v78 offset:10656
	s_waitcnt lgkmcnt(6)
	v_fma_f32 v51, -v33, v88, v51
	v_fma_f32 v69, -v34, v89, v69
	v_fma_f32 v70, -v36, v90, v70
	v_fma_f32 v71, -v37, v91, v71
	ds_read_b128 v[88:91], v78 offset:10672
	s_waitcnt lgkmcnt(6)
	v_fma_f32 v51, -v39, v92, v51
	v_fma_f32 v69, -v41, v93, v69
	v_fma_f32 v70, -v42, v94, v70
	v_fma_f32 v71, -v44, v95, v71
	ds_read_b128 v[92:95], v78 offset:10688
	s_waitcnt lgkmcnt(6)
	v_fma_f32 v51, -v48, v96, v51
	v_mov_b32_e32 v75, v97
	ds_read_b128 v[96:99], v78 offset:10704
	s_waitcnt lgkmcnt(6)
	v_fma_f32 v53, -v2, v100, v53
	v_fma_f32 v72, -v3, v101, 0
	v_fma_f32 v73, -v5, v102, 0
	v_fma_f32 v69, -v49, v75, v69
	v_fma_f32 v74, -v6, v103, 0
	ds_read_b128 v[100:103], v78 offset:10720
	s_waitcnt lgkmcnt(6)
	v_fma_f32 v53, -v7, v104, v53
	v_fma_f32 v72, -v8, v105, v72
	v_add_f32_e32 v69, v51, v69
	v_fma_f32 v73, -v9, v106, v73
	v_fma_f32 v74, -v10, v107, v74
	ds_read_b128 v[104:107], v78 offset:10736
	s_waitcnt lgkmcnt(6)
	v_fma_f32 v53, -v11, v108, v53
	v_add_f32_e32 v70, v70, v71
	v_fma_f32 v72, -v12, v109, v72
	v_fma_f32 v73, -v13, v110, v73
	v_fma_f32 v74, -v14, v111, v74
	v_add_f32_e32 v51, v69, v70
	ds_read_b128 v[108:111], v78 offset:10752
	s_waitcnt lgkmcnt(6)
	v_fma_f32 v53, -v15, v84, v53
	v_fma_f32 v72, -v16, v85, v72
	v_fma_f32 v73, -v66, v86, v73
	v_fma_f32 v74, -v17, v87, v74
	ds_read_b128 v[84:87], v78 offset:10880
	s_waitcnt lgkmcnt(6)
	v_fma_f32 v53, -v18, v88, v53
	v_fma_f32 v72, -v19, v89, v72
	v_fma_f32 v73, -v20, v90, v73
	v_fma_f32 v74, -v21, v91, v74
	ds_read_b128 v[88:91], v78 offset:10896
	s_waitcnt lgkmcnt(6)
	v_fma_f32 v53, -v22, v92, v53
	v_fma_f32 v72, -v23, v93, v72
	v_fma_f32 v73, -v24, v94, v73
	v_fma_f32 v74, -v25, v95, v74
	ds_read_b128 v[92:95], v78 offset:10912
	s_waitcnt lgkmcnt(6)
	v_fma_f32 v53, -v26, v96, v53
	v_fma_f32 v72, -v27, v97, v72
	v_fma_f32 v73, -v29, v98, v73
	v_fma_f32 v74, -v30, v99, v74
	ds_read_b128 v[96:99], v78 offset:10928
	s_waitcnt lgkmcnt(6)
	v_fma_f32 v53, -v33, v100, v53
	v_fma_f32 v72, -v34, v101, v72
	v_fma_f32 v73, -v36, v102, v73
	v_fma_f32 v74, -v37, v103, v74
	ds_read_b128 v[100:103], v78 offset:10944
	s_waitcnt lgkmcnt(6)
	v_fma_f32 v53, -v39, v104, v53
	v_fma_f32 v72, -v41, v105, v72
	v_fma_f32 v73, -v42, v106, v73
	v_fma_f32 v74, -v44, v107, v74
	ds_read_b128 v[104:107], v78 offset:10960
	s_waitcnt lgkmcnt(6)
	v_fma_f32 v53, -v48, v108, v53
	v_fma_f32 v72, -v49, v109, v72
	v_mov_b32_e32 v76, v110
	ds_read_b128 v[108:111], v78 offset:10976
	s_waitcnt lgkmcnt(6)
	v_fma_f32 v54, -v2, v84, v54
	v_fma_f32 v69, -v3, v85, 0
	v_fma_f32 v70, -v5, v86, 0
	v_fma_f32 v73, -v51, v76, v73
	v_fma_f32 v71, -v6, v87, 0
	ds_read_b128 v[84:87], v78 offset:10992
	s_waitcnt lgkmcnt(6)
	v_fma_f32 v54, -v7, v88, v54
	v_fma_f32 v69, -v8, v89, v69
	v_add_f32_e32 v72, v53, v72
	v_fma_f32 v70, -v9, v90, v70
	v_fma_f32 v71, -v10, v91, v71
	ds_read_b128 v[88:91], v78 offset:11008
	s_waitcnt lgkmcnt(6)
	v_fma_f32 v54, -v11, v92, v54
	v_add_f32_e32 v73, v73, v74
	v_fma_f32 v69, -v12, v93, v69
	v_fma_f32 v70, -v13, v94, v70
	v_fma_f32 v71, -v14, v95, v71
	v_add_f32_e32 v53, v72, v73
	ds_read_b128 v[92:95], v78 offset:11024
	s_waitcnt lgkmcnt(6)
	v_fma_f32 v54, -v15, v96, v54
	v_fma_f32 v69, -v16, v97, v69
	v_fma_f32 v70, -v66, v98, v70
	v_fma_f32 v71, -v17, v99, v71
	ds_read_b128 v[96:99], v78 offset:11152
	s_waitcnt lgkmcnt(6)
	v_fma_f32 v54, -v18, v100, v54
	v_fma_f32 v69, -v19, v101, v69
	v_fma_f32 v70, -v20, v102, v70
	v_fma_f32 v71, -v21, v103, v71
	ds_read_b128 v[100:103], v78 offset:11168
	s_waitcnt lgkmcnt(6)
	v_fma_f32 v54, -v22, v104, v54
	v_fma_f32 v69, -v23, v105, v69
	v_fma_f32 v70, -v24, v106, v70
	v_fma_f32 v71, -v25, v107, v71
	ds_read_b128 v[104:107], v78 offset:11184
	s_waitcnt lgkmcnt(6)
	v_fma_f32 v54, -v26, v108, v54
	v_fma_f32 v69, -v27, v109, v69
	v_fma_f32 v70, -v29, v110, v70
	v_fma_f32 v71, -v30, v111, v71
	ds_read_b128 v[108:111], v78 offset:11200
	s_waitcnt lgkmcnt(6)
	v_fma_f32 v54, -v33, v84, v54
	v_fma_f32 v69, -v34, v85, v69
	v_fma_f32 v70, -v36, v86, v70
	v_fma_f32 v71, -v37, v87, v71
	ds_read_b128 v[84:87], v78 offset:11216
	s_waitcnt lgkmcnt(6)
	v_fma_f32 v54, -v39, v88, v54
	v_fma_f32 v69, -v41, v89, v69
	v_fma_f32 v70, -v42, v90, v70
	v_fma_f32 v71, -v44, v91, v71
	ds_read_b128 v[88:91], v78 offset:11232
	s_waitcnt lgkmcnt(6)
	v_fma_f32 v54, -v48, v92, v54
	v_fma_f32 v69, -v49, v93, v69
	v_fma_f32 v70, -v51, v94, v70
	v_mov_b32_e32 v75, v95
	ds_read_b128 v[92:95], v78 offset:11248
	s_waitcnt lgkmcnt(6)
	v_fma_f32 v56, -v2, v96, v56
	v_fma_f32 v72, -v3, v97, 0
	v_fma_f32 v73, -v5, v98, 0
	v_fma_f32 v71, -v53, v75, v71
	v_fma_f32 v74, -v6, v99, 0
	ds_read_b128 v[96:99], v78 offset:11264
	s_waitcnt lgkmcnt(6)
	v_fma_f32 v56, -v7, v100, v56
	v_fma_f32 v72, -v8, v101, v72
	v_add_f32_e32 v69, v54, v69
	v_fma_f32 v73, -v9, v102, v73
	v_fma_f32 v74, -v10, v103, v74
	ds_read_b128 v[100:103], v78 offset:11280
	s_waitcnt lgkmcnt(6)
	v_fma_f32 v56, -v11, v104, v56
	v_add_f32_e32 v70, v70, v71
	v_fma_f32 v72, -v12, v105, v72
	v_fma_f32 v73, -v13, v106, v73
	v_fma_f32 v74, -v14, v107, v74
	v_add_f32_e32 v54, v69, v70
	ds_read_b128 v[104:107], v78 offset:11296
	s_waitcnt lgkmcnt(6)
; DI void gdn_prep(const Params& p, int item, unsigned char* smem) {
;     ...
;         for (int i = 1; i < 64; ++i) {
;             float a = X[i];
;             int dep; asm volatile("v_and_b32 %0, 0, %1" : "=v"(dep) : "v"(X[i - 1]));
;             const float* Lr = sL + i * 68 + dep;
;             float b0 = 0.f, b1 = 0.f, b2 = 0.f;
; #pragma unroll
;             for (int j4 = 0; j4 < (i + 3) / 4; ++j4) {
;                 const f32x4 l = *(const f32x4*)(Lr + 4 * j4);
;                 if (4 * j4 + 0 < i) a -= l.x * X[4 * j4 + 0];
;                 if (4 * j4 + 1 < i) b0 -= l.y * X[4 * j4 + 1];
;                 if (4 * j4 + 2 < i) b1 -= l.z * X[4 * j4 + 2];
;                 if (4 * j4 + 3 < i) b2 -= l.w * X[4 * j4 + 3];
;             }
;             X[i] = (a + b0) + (b1 + b2);
	v_fma_f32 v56, -v15, v108, v56
	v_fma_f32 v72, -v16, v109, v72
	v_fma_f32 v73, -v66, v110, v73
	v_fma_f32 v74, -v17, v111, v74
	ds_read_b128 v[108:111], v78 offset:11312
	s_waitcnt lgkmcnt(6)
	v_fma_f32 v56, -v18, v84, v56
	v_fma_f32 v72, -v19, v85, v72
	v_fma_f32 v73, -v20, v86, v73
	v_fma_f32 v74, -v21, v87, v74
	ds_read_b128 v[84:87], v78 offset:11424
	s_waitcnt lgkmcnt(6)
	v_fma_f32 v56, -v22, v88, v56
	v_fma_f32 v72, -v23, v89, v72
	v_fma_f32 v73, -v24, v90, v73
	v_fma_f32 v74, -v25, v91, v74
	ds_read_b128 v[88:91], v78 offset:11440
	s_waitcnt lgkmcnt(6)
	v_fma_f32 v56, -v26, v92, v56
	v_fma_f32 v72, -v27, v93, v72
	v_fma_f32 v73, -v29, v94, v73
	v_fma_f32 v74, -v30, v95, v74
	ds_read_b128 v[92:95], v78 offset:11456
	s_waitcnt lgkmcnt(6)
	v_fma_f32 v56, -v33, v96, v56
	v_fma_f32 v72, -v34, v97, v72
	v_fma_f32 v73, -v36, v98, v73
	v_fma_f32 v74, -v37, v99, v74
	ds_read_b128 v[96:99], v78 offset:11472
	s_waitcnt lgkmcnt(6)
	v_fma_f32 v56, -v39, v100, v56
	v_fma_f32 v72, -v41, v101, v72
	v_fma_f32 v73, -v42, v102, v73
	v_fma_f32 v74, -v44, v103, v74
	ds_read_b128 v[100:103], v78 offset:11488
	s_waitcnt lgkmcnt(6)
	v_fma_f32 v56, -v48, v104, v56
	v_fma_f32 v72, -v49, v105, v72
	v_fma_f32 v73, -v51, v106, v73
	v_fma_f32 v74, -v53, v107, v74
	ds_read_b128 v[104:107], v78 offset:11504
	s_waitcnt lgkmcnt(6)
	v_mov_b32_e32 v76, v108
	ds_read_b128 v[108:111], v78 offset:11520
	s_waitcnt lgkmcnt(6)
	v_fma_f32 v58, -v2, v84, v58
	v_fma_f32 v69, -v3, v85, 0
	v_fma_f32 v70, -v5, v86, 0
	v_fma_f32 v56, -v54, v76, v56
	v_fma_f32 v71, -v6, v87, 0
	ds_read_b128 v[84:87], v78 offset:11536
	s_waitcnt lgkmcnt(6)
	v_fma_f32 v58, -v7, v88, v58
	v_fma_f32 v69, -v8, v89, v69
	v_add_f32_e32 v72, v56, v72
	v_fma_f32 v70, -v9, v90, v70
	v_fma_f32 v71, -v10, v91, v71
	ds_read_b128 v[88:91], v78 offset:11552
	s_waitcnt lgkmcnt(6)
	v_fma_f32 v58, -v11, v92, v58
	v_add_f32_e32 v73, v73, v74
	v_fma_f32 v69, -v12, v93, v69
	v_fma_f32 v70, -v13, v94, v70
	v_fma_f32 v71, -v14, v95, v71
	v_add_f32_e32 v56, v72, v73
	ds_read_b128 v[92:95], v78 offset:11568
	s_waitcnt lgkmcnt(6)
	v_fma_f32 v58, -v15, v96, v58
	v_fma_f32 v69, -v16, v97, v69
	v_fma_f32 v70, -v66, v98, v70
	v_fma_f32 v71, -v17, v99, v71
	ds_read_b128 v[96:99], v78 offset:11584
	s_waitcnt lgkmcnt(6)
	v_fma_f32 v58, -v18, v100, v58
	v_fma_f32 v69, -v19, v101, v69
	v_fma_f32 v70, -v20, v102, v70
	v_fma_f32 v71, -v21, v103, v71
	ds_read_b128 v[100:103], v78 offset:11696
	s_waitcnt lgkmcnt(6)
	v_fma_f32 v58, -v22, v104, v58
	v_fma_f32 v69, -v23, v105, v69
	v_fma_f32 v70, -v24, v106, v70
	v_fma_f32 v71, -v25, v107, v71
	ds_read_b128 v[104:107], v78 offset:11712
	s_waitcnt lgkmcnt(6)
	v_fma_f32 v58, -v26, v108, v58
	v_fma_f32 v69, -v27, v109, v69
	v_fma_f32 v70, -v29, v110, v70
	v_fma_f32 v71, -v30, v111, v71
	ds_read_b128 v[108:111], v78 offset:11728
	s_waitcnt lgkmcnt(6)
	v_fma_f32 v58, -v33, v84, v58
	v_fma_f32 v69, -v34, v85, v69
	v_fma_f32 v70, -v36, v86, v70
	v_fma_f32 v71, -v37, v87, v71
	ds_read_b128 v[84:87], v78 offset:11744
	s_waitcnt lgkmcnt(6)
	v_fma_f32 v58, -v39, v88, v58
	v_fma_f32 v69, -v41, v89, v69
	v_fma_f32 v70, -v42, v90, v70
	v_fma_f32 v71, -v44, v91, v71
	ds_read_b128 v[88:91], v78 offset:11760
	s_waitcnt lgkmcnt(6)
	v_fma_f32 v58, -v48, v92, v58
	v_fma_f32 v69, -v49, v93, v69
	v_fma_f32 v70, -v51, v94, v70
	v_fma_f32 v71, -v53, v95, v71
	ds_read_b128 v[92:95], v78 offset:11776
	s_waitcnt lgkmcnt(6)
	v_fma_f32 v58, -v54, v96, v58
	v_mov_b32_e32 v75, v97
	ds_read_b128 v[96:99], v78 offset:11792
	s_waitcnt lgkmcnt(6)
	v_fma_f32 v61, -v2, v100, v61
	v_fma_f32 v72, -v3, v101, 0
	v_fma_f32 v73, -v5, v102, 0
	v_fma_f32 v69, -v56, v75, v69
	v_fma_f32 v74, -v6, v103, 0
	ds_read_b128 v[100:103], v78 offset:11808
	s_waitcnt lgkmcnt(6)
	v_fma_f32 v61, -v7, v104, v61
	v_fma_f32 v72, -v8, v105, v72
	v_add_f32_e32 v69, v58, v69
	v_fma_f32 v73, -v9, v106, v73
	v_fma_f32 v74, -v10, v107, v74
	ds_read_b128 v[104:107], v78 offset:11824
	s_waitcnt lgkmcnt(6)
	v_fma_f32 v61, -v11, v108, v61
	v_add_f32_e32 v70, v70, v71
	v_fma_f32 v72, -v12, v109, v72
	v_fma_f32 v73, -v13, v110, v73
	v_fma_f32 v74, -v14, v111, v74
	v_add_f32_e32 v58, v69, v70
	ds_read_b128 v[108:111], v78 offset:11840
	s_waitcnt lgkmcnt(6)
	v_fma_f32 v61, -v15, v84, v61
	v_fma_f32 v72, -v16, v85, v72
	v_fma_f32 v73, -v66, v86, v73
	v_fma_f32 v74, -v17, v87, v74
	ds_read_b128 v[84:87], v78 offset:11856
	s_waitcnt lgkmcnt(6)
	v_fma_f32 v61, -v18, v88, v61
	v_fma_f32 v72, -v19, v89, v72
	v_fma_f32 v73, -v20, v90, v73
	v_fma_f32 v74, -v21, v91, v74
	ds_read_b128 v[88:91], v78 offset:11968
	s_waitcnt lgkmcnt(6)
	v_fma_f32 v61, -v22, v92, v61
	v_fma_f32 v72, -v23, v93, v72
	v_fma_f32 v73, -v24, v94, v73
	v_fma_f32 v74, -v25, v95, v74
	ds_read_b128 v[92:95], v78 offset:11984
	s_waitcnt lgkmcnt(6)
	v_fma_f32 v61, -v26, v96, v61
	v_fma_f32 v72, -v27, v97, v72
	v_fma_f32 v73, -v29, v98, v73
	v_fma_f32 v74, -v30, v99, v74
	ds_read_b128 v[96:99], v78 offset:12000
	s_waitcnt lgkmcnt(6)
	v_fma_f32 v61, -v33, v100, v61
	v_fma_f32 v72, -v34, v101, v72
	v_fma_f32 v73, -v36, v102, v73
	v_fma_f32 v74, -v37, v103, v74
	ds_read_b128 v[100:103], v78 offset:12016
	s_waitcnt lgkmcnt(6)
	v_fma_f32 v61, -v39, v104, v61
	v_fma_f32 v72, -v41, v105, v72
	v_fma_f32 v73, -v42, v106, v73
	v_fma_f32 v74, -v44, v107, v74
	ds_read_b128 v[104:107], v78 offset:12032
	s_waitcnt lgkmcnt(6)
	v_fma_f32 v61, -v48, v108, v61
	v_fma_f32 v72, -v49, v109, v72
	v_fma_f32 v73, -v51, v110, v73
	v_fma_f32 v74, -v53, v111, v74
	ds_read_b128 v[108:111], v78 offset:12048
	s_waitcnt lgkmcnt(6)
	v_fma_f32 v61, -v54, v84, v61
	v_fma_f32 v72, -v56, v85, v72
	v_mov_b32_e32 v76, v86
	ds_read_b128 v[84:87], v78 offset:12064
	s_waitcnt lgkmcnt(6)
; DI void gdn_prep(const Params& p, int item, unsigned char* smem) {
;     ...
;         for (int i = 1; i < 64; ++i) {
;             float a = X[i];
;             int dep; asm volatile("v_and_b32 %0, 0, %1" : "=v"(dep) : "v"(X[i - 1]));
;             const float* Lr = sL + i * 68 + dep;
;             float b0 = 0.f, b1 = 0.f, b2 = 0.f;
; #pragma unroll
;             for (int j4 = 0; j4 < (i + 3) / 4; ++j4) {
;                 const f32x4 l = *(const f32x4*)(Lr + 4 * j4);
;                 if (4 * j4 + 0 < i) a -= l.x * X[4 * j4 + 0];
;                 if (4 * j4 + 1 < i) b0 -= l.y * X[4 * j4 + 1];
;                 if (4 * j4 + 2 < i) b1 -= l.z * X[4 * j4 + 2];
;                 if (4 * j4 + 3 < i) b2 -= l.w * X[4 * j4 + 3];
;             }
;             X[i] = (a + b0) + (b1 + b2);
	v_fma_f32 v63, -v2, v88, v63
	v_fma_f32 v69, -v3, v89, 0
	v_fma_f32 v70, -v5, v90, 0
	v_fma_f32 v73, -v58, v76, v73
	v_fma_f32 v71, -v6, v91, 0
	ds_read_b128 v[88:91], v78 offset:12080
	s_waitcnt lgkmcnt(6)
	v_fma_f32 v63, -v7, v92, v63
	v_fma_f32 v69, -v8, v93, v69
	v_add_f32_e32 v72, v61, v72
	v_fma_f32 v70, -v9, v94, v70
	v_fma_f32 v71, -v10, v95, v71
	ds_read_b128 v[92:95], v78 offset:12096
	s_waitcnt lgkmcnt(6)
	v_fma_f32 v63, -v11, v96, v63
	v_add_f32_e32 v73, v73, v74
	v_fma_f32 v69, -v12, v97, v69
	v_fma_f32 v70, -v13, v98, v70
	v_fma_f32 v71, -v14, v99, v71
	v_add_f32_e32 v61, v72, v73
	ds_read_b128 v[96:99], v78 offset:12112
	s_waitcnt lgkmcnt(6)
	v_fma_f32 v63, -v15, v100, v63
	v_fma_f32 v69, -v16, v101, v69
	v_fma_f32 v70, -v66, v102, v70
	v_fma_f32 v71, -v17, v103, v71
	ds_read_b128 v[100:103], v78 offset:12128
	s_waitcnt lgkmcnt(6)
	v_fma_f32 v63, -v18, v104, v63
	v_fma_f32 v69, -v19, v105, v69
	v_fma_f32 v70, -v20, v106, v70
	v_fma_f32 v71, -v21, v107, v71
	ds_read_b128 v[104:107], v78 offset:12240
	s_waitcnt lgkmcnt(6)
	v_fma_f32 v63, -v22, v108, v63
	v_fma_f32 v69, -v23, v109, v69
	v_fma_f32 v70, -v24, v110, v70
	v_fma_f32 v71, -v25, v111, v71
	ds_read_b128 v[108:111], v78 offset:12256
	s_waitcnt lgkmcnt(6)
	v_fma_f32 v63, -v26, v84, v63
	v_fma_f32 v69, -v27, v85, v69
	v_fma_f32 v70, -v29, v86, v70
	v_fma_f32 v71, -v30, v87, v71
	ds_read_b128 v[84:87], v78 offset:12272
	s_waitcnt lgkmcnt(6)
	v_fma_f32 v63, -v33, v88, v63
	v_fma_f32 v69, -v34, v89, v69
	v_fma_f32 v70, -v36, v90, v70
	v_fma_f32 v71, -v37, v91, v71
	ds_read_b128 v[88:91], v78 offset:12288
	s_waitcnt lgkmcnt(6)
	v_fma_f32 v63, -v39, v92, v63
	v_fma_f32 v69, -v41, v93, v69
	v_fma_f32 v70, -v42, v94, v70
	v_fma_f32 v71, -v44, v95, v71
	ds_read_b128 v[92:95], v78 offset:12304
	s_waitcnt lgkmcnt(6)
	v_fma_f32 v63, -v48, v96, v63
	v_fma_f32 v69, -v49, v97, v69
	v_fma_f32 v70, -v51, v98, v70
	v_fma_f32 v71, -v53, v99, v71
	ds_read_b128 v[96:99], v78 offset:12320
	s_waitcnt lgkmcnt(6)
	v_fma_f32 v63, -v54, v100, v63
	v_fma_f32 v69, -v56, v101, v69
	v_fma_f32 v70, -v58, v102, v70
	v_mov_b32_e32 v75, v103
	ds_read_b128 v[100:103], v78 offset:12336
	s_waitcnt lgkmcnt(6)
	v_fma_f32 v65, -v2, v104, v65
	v_fma_f32 v72, -v3, v105, 0
	v_fma_f32 v73, -v5, v106, 0
	v_fma_f32 v71, -v61, v75, v71
	v_fma_f32 v74, -v6, v107, 0
	ds_read_b128 v[104:107], v78 offset:12352
	s_waitcnt lgkmcnt(6)
	v_fma_f32 v65, -v7, v108, v65
	v_fma_f32 v72, -v8, v109, v72
	v_add_f32_e32 v69, v63, v69
	v_fma_f32 v73, -v9, v110, v73
	v_fma_f32 v74, -v10, v111, v74
	ds_read_b128 v[108:111], v78 offset:12368
	s_waitcnt lgkmcnt(6)
	v_fma_f32 v65, -v11, v84, v65
	v_add_f32_e32 v70, v70, v71
	v_fma_f32 v72, -v12, v85, v72
	v_fma_f32 v73, -v13, v86, v73
	v_fma_f32 v74, -v14, v87, v74
	v_add_f32_e32 v63, v69, v70
	ds_read_b128 v[84:87], v78 offset:12384
	s_waitcnt lgkmcnt(6)
	v_fma_f32 v65, -v15, v88, v65
	v_fma_f32 v72, -v16, v89, v72
	v_fma_f32 v73, -v66, v90, v73
	v_fma_f32 v74, -v17, v91, v74
	ds_read_b128 v[88:91], v78 offset:12400
	s_waitcnt lgkmcnt(6)
	v_fma_f32 v65, -v18, v92, v65
	v_fma_f32 v72, -v19, v93, v72
	v_fma_f32 v73, -v20, v94, v73
	v_fma_f32 v74, -v21, v95, v74
	ds_read_b128 v[92:95], v78 offset:12416
	s_waitcnt lgkmcnt(6)
	v_fma_f32 v65, -v22, v96, v65
	v_fma_f32 v72, -v23, v97, v72
	v_fma_f32 v73, -v24, v98, v73
	v_fma_f32 v74, -v25, v99, v74
	ds_read_b128 v[96:99], v78 offset:12512
	s_waitcnt lgkmcnt(6)
	v_fma_f32 v65, -v26, v100, v65
	v_fma_f32 v72, -v27, v101, v72
	v_fma_f32 v73, -v29, v102, v73
	v_fma_f32 v74, -v30, v103, v74
	ds_read_b128 v[100:103], v78 offset:12528
	s_waitcnt lgkmcnt(6)
	v_fma_f32 v65, -v33, v104, v65
	v_fma_f32 v72, -v34, v105, v72
	v_fma_f32 v73, -v36, v106, v73
	v_fma_f32 v74, -v37, v107, v74
	ds_read_b128 v[104:107], v78 offset:12544
	s_waitcnt lgkmcnt(6)
	v_fma_f32 v65, -v39, v108, v65
	v_fma_f32 v72, -v41, v109, v72
	v_fma_f32 v73, -v42, v110, v73
	v_fma_f32 v74, -v44, v111, v74
	ds_read_b128 v[108:111], v78 offset:12560
	s_waitcnt lgkmcnt(6)
	v_fma_f32 v65, -v48, v84, v65
	v_fma_f32 v72, -v49, v85, v72
	v_fma_f32 v73, -v51, v86, v73
	v_fma_f32 v74, -v53, v87, v74
	ds_read_b128 v[84:87], v78 offset:12576
	s_waitcnt lgkmcnt(6)
	v_fma_f32 v65, -v54, v88, v65
	v_fma_f32 v72, -v56, v89, v72
	v_fma_f32 v73, -v58, v90, v73
	v_fma_f32 v74, -v61, v91, v74
	ds_read_b128 v[88:91], v78 offset:12592
	s_waitcnt lgkmcnt(6)
	v_mov_b32_e32 v76, v92
	ds_read_b128 v[92:95], v78 offset:12608
	s_waitcnt lgkmcnt(6)
	v_fma_f32 v64, -v2, v96, v64
	v_fma_f32 v69, -v3, v97, 0
	v_fma_f32 v70, -v5, v98, 0
	v_fma_f32 v65, -v63, v76, v65
	v_fma_f32 v71, -v6, v99, 0
	ds_read_b128 v[96:99], v78 offset:12624
	s_waitcnt lgkmcnt(6)
	v_fma_f32 v64, -v7, v100, v64
	v_fma_f32 v69, -v8, v101, v69
	v_add_f32_e32 v72, v65, v72
	v_fma_f32 v70, -v9, v102, v70
	v_fma_f32 v71, -v10, v103, v71
	ds_read_b128 v[100:103], v78 offset:12640
	s_waitcnt lgkmcnt(6)
	v_fma_f32 v64, -v11, v104, v64
	v_add_f32_e32 v73, v73, v74
	v_fma_f32 v69, -v12, v105, v69
	v_fma_f32 v70, -v13, v106, v70
	v_fma_f32 v71, -v14, v107, v71
	v_add_f32_e32 v65, v72, v73
	ds_read_b128 v[104:107], v78 offset:12656
	s_waitcnt lgkmcnt(6)
	v_fma_f32 v64, -v15, v108, v64
	v_fma_f32 v69, -v16, v109, v69
	v_fma_f32 v70, -v66, v110, v70
	v_fma_f32 v71, -v17, v111, v71
	ds_read_b128 v[108:111], v78 offset:12672
	s_waitcnt lgkmcnt(6)
	v_fma_f32 v64, -v18, v84, v64
	v_fma_f32 v69, -v19, v85, v69
	v_fma_f32 v70, -v20, v86, v70
	v_fma_f32 v71, -v21, v87, v71
	ds_read_b128 v[84:87], v78 offset:12688
	s_waitcnt lgkmcnt(6)
	v_fma_f32 v64, -v22, v88, v64
	v_fma_f32 v69, -v23, v89, v69
	v_fma_f32 v70, -v24, v90, v70
	v_fma_f32 v71, -v25, v91, v71
	ds_read_b128 v[88:91], v78 offset:12784
	s_waitcnt lgkmcnt(6)
; DI void gdn_prep(const Params& p, int item, unsigned char* smem) {
;     ...
;         for (int i = 1; i < 64; ++i) {
;             float a = X[i];
;             int dep; asm volatile("v_and_b32 %0, 0, %1" : "=v"(dep) : "v"(X[i - 1]));
;             const float* Lr = sL + i * 68 + dep;
;             float b0 = 0.f, b1 = 0.f, b2 = 0.f;
; #pragma unroll
;             for (int j4 = 0; j4 < (i + 3) / 4; ++j4) {
;                 const f32x4 l = *(const f32x4*)(Lr + 4 * j4);
;                 if (4 * j4 + 0 < i) a -= l.x * X[4 * j4 + 0];
;                 if (4 * j4 + 1 < i) b0 -= l.y * X[4 * j4 + 1];
;                 if (4 * j4 + 2 < i) b1 -= l.z * X[4 * j4 + 2];
;                 if (4 * j4 + 3 < i) b2 -= l.w * X[4 * j4 + 3];
;             }
;             X[i] = (a + b0) + (b1 + b2);
	v_fma_f32 v64, -v26, v92, v64
	v_fma_f32 v69, -v27, v93, v69
	v_fma_f32 v70, -v29, v94, v70
	v_fma_f32 v71, -v30, v95, v71
	ds_read_b128 v[92:95], v78 offset:12800
	s_waitcnt lgkmcnt(6)
	v_fma_f32 v64, -v33, v96, v64
	v_fma_f32 v69, -v34, v97, v69
	v_fma_f32 v70, -v36, v98, v70
	v_fma_f32 v71, -v37, v99, v71
	ds_read_b128 v[96:99], v78 offset:12816
	s_waitcnt lgkmcnt(6)
	v_fma_f32 v64, -v39, v100, v64
	v_fma_f32 v69, -v41, v101, v69
	v_fma_f32 v70, -v42, v102, v70
	v_fma_f32 v71, -v44, v103, v71
	ds_read_b128 v[100:103], v78 offset:12832
	s_waitcnt lgkmcnt(6)
	v_fma_f32 v64, -v48, v104, v64
	v_fma_f32 v69, -v49, v105, v69
	v_fma_f32 v70, -v51, v106, v70
	v_fma_f32 v71, -v53, v107, v71
	ds_read_b128 v[104:107], v78 offset:12848
	s_waitcnt lgkmcnt(6)
	v_fma_f32 v64, -v54, v108, v64
	v_fma_f32 v69, -v56, v109, v69
	v_fma_f32 v70, -v58, v110, v70
	v_fma_f32 v71, -v61, v111, v71
	ds_read_b128 v[108:111], v78 offset:12864
	s_waitcnt lgkmcnt(6)
	v_fma_f32 v64, -v63, v84, v64
	v_mov_b32_e32 v75, v85
	ds_read_b128 v[84:87], v78 offset:12880
	s_waitcnt lgkmcnt(6)
	v_fma_f32 v62, -v2, v88, v62
	v_fma_f32 v72, -v3, v89, 0
	v_fma_f32 v73, -v5, v90, 0
	v_fma_f32 v69, -v65, v75, v69
	v_fma_f32 v74, -v6, v91, 0
	ds_read_b128 v[88:91], v78 offset:12896
	s_waitcnt lgkmcnt(6)
	v_fma_f32 v62, -v7, v92, v62
	v_fma_f32 v72, -v8, v93, v72
	v_add_f32_e32 v69, v64, v69
	v_fma_f32 v73, -v9, v94, v73
	v_fma_f32 v74, -v10, v95, v74
	ds_read_b128 v[92:95], v78 offset:12912
	s_waitcnt lgkmcnt(6)
	v_fma_f32 v62, -v11, v96, v62
	v_add_f32_e32 v70, v70, v71
	v_fma_f32 v72, -v12, v97, v72
	v_fma_f32 v73, -v13, v98, v73
	v_fma_f32 v74, -v14, v99, v74
	v_add_f32_e32 v64, v69, v70
	ds_read_b128 v[96:99], v78 offset:12928
	s_waitcnt lgkmcnt(6)
	v_fma_f32 v62, -v15, v100, v62
	v_fma_f32 v72, -v16, v101, v72
	v_fma_f32 v73, -v66, v102, v73
	v_fma_f32 v74, -v17, v103, v74
	ds_read_b128 v[100:103], v78 offset:12944
	s_waitcnt lgkmcnt(6)
	v_fma_f32 v62, -v18, v104, v62
	v_fma_f32 v72, -v19, v105, v72
	v_fma_f32 v73, -v20, v106, v73
	v_fma_f32 v74, -v21, v107, v74
	ds_read_b128 v[104:107], v78 offset:12960
	s_waitcnt lgkmcnt(6)
	v_fma_f32 v62, -v22, v108, v62
	v_fma_f32 v72, -v23, v109, v72
	v_fma_f32 v73, -v24, v110, v73
	v_fma_f32 v74, -v25, v111, v74
	ds_read_b128 v[108:111], v78 offset:13056
	s_waitcnt lgkmcnt(6)
	v_fma_f32 v62, -v26, v84, v62
	v_fma_f32 v72, -v27, v85, v72
	v_fma_f32 v73, -v29, v86, v73
	v_fma_f32 v74, -v30, v87, v74
	ds_read_b128 v[84:87], v78 offset:13072
	s_waitcnt lgkmcnt(6)
	v_fma_f32 v62, -v33, v88, v62
	v_fma_f32 v72, -v34, v89, v72
	v_fma_f32 v73, -v36, v90, v73
	v_fma_f32 v74, -v37, v91, v74
	ds_read_b128 v[88:91], v78 offset:13088
	s_waitcnt lgkmcnt(6)
	v_fma_f32 v62, -v39, v92, v62
	v_fma_f32 v72, -v41, v93, v72
	v_fma_f32 v73, -v42, v94, v73
	v_fma_f32 v74, -v44, v95, v74
	ds_read_b128 v[92:95], v78 offset:13104
	s_waitcnt lgkmcnt(6)
	v_fma_f32 v62, -v48, v96, v62
	v_fma_f32 v72, -v49, v97, v72
	v_fma_f32 v73, -v51, v98, v73
	v_fma_f32 v74, -v53, v99, v74
	ds_read_b128 v[96:99], v78 offset:13120
	s_waitcnt lgkmcnt(6)
	v_fma_f32 v62, -v54, v100, v62
	v_fma_f32 v72, -v56, v101, v72
	v_fma_f32 v73, -v58, v102, v73
	v_fma_f32 v74, -v61, v103, v74
	ds_read_b128 v[100:103], v78 offset:13136
	s_waitcnt lgkmcnt(6)
	v_fma_f32 v62, -v63, v104, v62
	v_fma_f32 v72, -v65, v105, v72
	v_mov_b32_e32 v76, v106
	ds_read_b128 v[104:107], v78 offset:13152
	s_waitcnt lgkmcnt(6)
	v_fma_f32 v60, -v2, v108, v60
	v_fma_f32 v69, -v3, v109, 0
	v_fma_f32 v70, -v5, v110, 0
	v_fma_f32 v73, -v64, v76, v73
	v_fma_f32 v71, -v6, v111, 0
	ds_read_b128 v[108:111], v78 offset:13168
	s_waitcnt lgkmcnt(6)
	v_fma_f32 v60, -v7, v84, v60
	v_fma_f32 v69, -v8, v85, v69
	v_add_f32_e32 v72, v62, v72
	v_fma_f32 v70, -v9, v86, v70
	v_fma_f32 v71, -v10, v87, v71
	ds_read_b128 v[84:87], v78 offset:13184
	s_waitcnt lgkmcnt(6)
	v_fma_f32 v60, -v11, v88, v60
	v_add_f32_e32 v73, v73, v74
	v_fma_f32 v69, -v12, v89, v69
	v_fma_f32 v70, -v13, v90, v70
	v_fma_f32 v71, -v14, v91, v71
	v_add_f32_e32 v62, v72, v73
	ds_read_b128 v[88:91], v78 offset:13200
	s_waitcnt lgkmcnt(6)
	v_fma_f32 v60, -v15, v92, v60
	v_fma_f32 v69, -v16, v93, v69
	v_fma_f32 v70, -v66, v94, v70
	v_fma_f32 v71, -v17, v95, v71
	ds_read_b128 v[92:95], v78 offset:13216
	s_waitcnt lgkmcnt(6)
	v_fma_f32 v60, -v18, v96, v60
	v_fma_f32 v69, -v19, v97, v69
	v_fma_f32 v70, -v20, v98, v70
	v_fma_f32 v71, -v21, v99, v71
	ds_read_b128 v[96:99], v78 offset:13232
	s_waitcnt lgkmcnt(6)
	v_fma_f32 v60, -v22, v100, v60
	v_fma_f32 v69, -v23, v101, v69
	v_fma_f32 v70, -v24, v102, v70
	v_fma_f32 v71, -v25, v103, v71
	ds_read_b128 v[100:103], v78 offset:13328
	s_waitcnt lgkmcnt(6)
	v_fma_f32 v60, -v26, v104, v60
	v_fma_f32 v69, -v27, v105, v69
	v_fma_f32 v70, -v29, v106, v70
	v_fma_f32 v71, -v30, v107, v71
	ds_read_b128 v[104:107], v78 offset:13344
	s_waitcnt lgkmcnt(6)
	v_fma_f32 v60, -v33, v108, v60
	v_fma_f32 v69, -v34, v109, v69
	v_fma_f32 v70, -v36, v110, v70
	v_fma_f32 v71, -v37, v111, v71
	ds_read_b128 v[108:111], v78 offset:13360
	s_waitcnt lgkmcnt(6)
	v_fma_f32 v60, -v39, v84, v60
	v_fma_f32 v69, -v41, v85, v69
	v_fma_f32 v70, -v42, v86, v70
	v_fma_f32 v71, -v44, v87, v71
	ds_read_b128 v[84:87], v78 offset:13376
	s_waitcnt lgkmcnt(6)
	v_fma_f32 v60, -v48, v88, v60
	v_fma_f32 v69, -v49, v89, v69
	v_fma_f32 v70, -v51, v90, v70
	v_fma_f32 v71, -v53, v91, v71
	ds_read_b128 v[88:91], v78 offset:13392
	s_waitcnt lgkmcnt(6)
	v_fma_f32 v60, -v54, v92, v60
	v_fma_f32 v69, -v56, v93, v69
	v_fma_f32 v70, -v58, v94, v70
	v_fma_f32 v71, -v61, v95, v71
	ds_read_b128 v[92:95], v78 offset:13408
	s_waitcnt lgkmcnt(6)
; DI void gdn_prep(const Params& p, int item, unsigned char* smem) {
;     ...
;         for (int i = 1; i < 64; ++i) {
;             float a = X[i];
;             int dep; asm volatile("v_and_b32 %0, 0, %1" : "=v"(dep) : "v"(X[i - 1]));
;             const float* Lr = sL + i * 68 + dep;
;             float b0 = 0.f, b1 = 0.f, b2 = 0.f;
; #pragma unroll
;             for (int j4 = 0; j4 < (i + 3) / 4; ++j4) {
;                 const f32x4 l = *(const f32x4*)(Lr + 4 * j4);
;                 if (4 * j4 + 0 < i) a -= l.x * X[4 * j4 + 0];
;                 if (4 * j4 + 1 < i) b0 -= l.y * X[4 * j4 + 1];
;                 if (4 * j4 + 2 < i) b1 -= l.z * X[4 * j4 + 2];
;                 if (4 * j4 + 3 < i) b2 -= l.w * X[4 * j4 + 3];
;             }
;             X[i] = (a + b0) + (b1 + b2);
	v_fma_f32 v60, -v63, v96, v60
	v_fma_f32 v69, -v65, v97, v69
	v_fma_f32 v70, -v64, v98, v70
	v_mov_b32_e32 v75, v99
	ds_read_b128 v[96:99], v78 offset:13424
	s_waitcnt lgkmcnt(6)
	v_fma_f32 v59, -v2, v100, v59
	v_fma_f32 v72, -v3, v101, 0
	v_fma_f32 v73, -v5, v102, 0
	v_fma_f32 v71, -v62, v75, v71
	v_fma_f32 v74, -v6, v103, 0
	ds_read_b128 v[100:103], v78 offset:13440
	s_waitcnt lgkmcnt(6)
	v_fma_f32 v59, -v7, v104, v59
	v_fma_f32 v72, -v8, v105, v72
	v_add_f32_e32 v69, v60, v69
	v_fma_f32 v73, -v9, v106, v73
	v_fma_f32 v74, -v10, v107, v74
	ds_read_b128 v[104:107], v78 offset:13456
	s_waitcnt lgkmcnt(6)
	v_fma_f32 v59, -v11, v108, v59
	v_add_f32_e32 v70, v70, v71
	v_fma_f32 v72, -v12, v109, v72
	v_fma_f32 v73, -v13, v110, v73
	v_fma_f32 v74, -v14, v111, v74
	v_add_f32_e32 v60, v69, v70
	ds_read_b128 v[108:111], v78 offset:13472
	s_waitcnt lgkmcnt(6)
	v_fma_f32 v59, -v15, v84, v59
	v_fma_f32 v72, -v16, v85, v72
	v_fma_f32 v73, -v66, v86, v73
	v_fma_f32 v74, -v17, v87, v74
	ds_read_b128 v[84:87], v78 offset:13488
	s_waitcnt lgkmcnt(6)
	v_fma_f32 v59, -v18, v88, v59
	v_fma_f32 v72, -v19, v89, v72
	v_fma_f32 v73, -v20, v90, v73
	v_fma_f32 v74, -v21, v91, v74
	ds_read_b128 v[88:91], v78 offset:13504
	s_waitcnt lgkmcnt(6)
	v_fma_f32 v59, -v22, v92, v59
	v_fma_f32 v72, -v23, v93, v72
	v_fma_f32 v73, -v24, v94, v73
	v_fma_f32 v74, -v25, v95, v74
	ds_read_b128 v[92:95], v78 offset:13520
	s_waitcnt lgkmcnt(6)
	v_fma_f32 v59, -v26, v96, v59
	v_fma_f32 v72, -v27, v97, v72
	v_fma_f32 v73, -v29, v98, v73
	v_fma_f32 v74, -v30, v99, v74
	ds_read_b128 v[96:99], v78 offset:13600
	s_waitcnt lgkmcnt(6)
	v_fma_f32 v59, -v33, v100, v59
	v_fma_f32 v72, -v34, v101, v72
	v_fma_f32 v73, -v36, v102, v73
	v_fma_f32 v74, -v37, v103, v74
	ds_read_b128 v[100:103], v78 offset:13616
	s_waitcnt lgkmcnt(6)
	v_fma_f32 v59, -v39, v104, v59
	v_fma_f32 v72, -v41, v105, v72
	v_fma_f32 v73, -v42, v106, v73
	v_fma_f32 v74, -v44, v107, v74
	ds_read_b128 v[104:107], v78 offset:13632
	s_waitcnt lgkmcnt(6)
	v_fma_f32 v59, -v48, v108, v59
	v_fma_f32 v72, -v49, v109, v72
	v_fma_f32 v73, -v51, v110, v73
	v_fma_f32 v74, -v53, v111, v74
	ds_read_b128 v[108:111], v78 offset:13648
	s_waitcnt lgkmcnt(6)
	v_fma_f32 v59, -v54, v84, v59
	v_fma_f32 v72, -v56, v85, v72
	v_fma_f32 v73, -v58, v86, v73
	v_fma_f32 v74, -v61, v87, v74
	ds_read_b128 v[84:87], v78 offset:13664
	s_waitcnt lgkmcnt(6)
	v_fma_f32 v59, -v63, v88, v59
	v_fma_f32 v72, -v65, v89, v72
	v_fma_f32 v73, -v64, v90, v73
	v_fma_f32 v74, -v62, v91, v74
	ds_read_b128 v[88:91], v78 offset:13680
	s_waitcnt lgkmcnt(6)
	v_mov_b32_e32 v76, v92
	ds_read_b128 v[92:95], v78 offset:13696
	s_waitcnt lgkmcnt(6)
	v_fma_f32 v57, -v2, v96, v57
	v_fma_f32 v69, -v3, v97, 0
	v_fma_f32 v70, -v5, v98, 0
	v_fma_f32 v59, -v60, v76, v59
	v_fma_f32 v71, -v6, v99, 0
	ds_read_b128 v[96:99], v78 offset:13712
	s_waitcnt lgkmcnt(6)
	v_fma_f32 v57, -v7, v100, v57
	v_fma_f32 v69, -v8, v101, v69
	v_add_f32_e32 v72, v59, v72
	v_fma_f32 v70, -v9, v102, v70
	v_fma_f32 v71, -v10, v103, v71
	ds_read_b128 v[100:103], v78 offset:13728
	s_waitcnt lgkmcnt(6)
	v_fma_f32 v57, -v11, v104, v57
	v_add_f32_e32 v73, v73, v74
	v_fma_f32 v69, -v12, v105, v69
	v_fma_f32 v70, -v13, v106, v70
	v_fma_f32 v71, -v14, v107, v71
	v_add_f32_e32 v59, v72, v73
	ds_read_b128 v[104:107], v78 offset:13744
	s_waitcnt lgkmcnt(6)
	v_fma_f32 v57, -v15, v108, v57
	v_fma_f32 v69, -v16, v109, v69
	v_fma_f32 v70, -v66, v110, v70
	v_fma_f32 v71, -v17, v111, v71
	ds_read_b128 v[108:111], v78 offset:13760
	s_waitcnt lgkmcnt(6)
	v_fma_f32 v57, -v18, v84, v57
	v_fma_f32 v69, -v19, v85, v69
	v_fma_f32 v70, -v20, v86, v70
	v_fma_f32 v71, -v21, v87, v71
	ds_read_b128 v[84:87], v78 offset:13776
	s_waitcnt lgkmcnt(6)
	v_fma_f32 v57, -v22, v88, v57
	v_fma_f32 v69, -v23, v89, v69
	v_fma_f32 v70, -v24, v90, v70
	v_fma_f32 v71, -v25, v91, v71
	ds_read_b128 v[88:91], v78 offset:13792
	s_waitcnt lgkmcnt(6)
	v_fma_f32 v57, -v26, v92, v57
	v_fma_f32 v69, -v27, v93, v69
	v_fma_f32 v70, -v29, v94, v70
	v_fma_f32 v71, -v30, v95, v71
	ds_read_b128 v[92:95], v78 offset:13872
	s_waitcnt lgkmcnt(6)
	v_fma_f32 v57, -v33, v96, v57
	v_fma_f32 v69, -v34, v97, v69
	v_fma_f32 v70, -v36, v98, v70
	v_fma_f32 v71, -v37, v99, v71
	ds_read_b128 v[96:99], v78 offset:13888
	s_waitcnt lgkmcnt(6)
	v_fma_f32 v57, -v39, v100, v57
	v_fma_f32 v69, -v41, v101, v69
	v_fma_f32 v70, -v42, v102, v70
	v_fma_f32 v71, -v44, v103, v71
	ds_read_b128 v[100:103], v78 offset:13904
	s_waitcnt lgkmcnt(6)
	v_fma_f32 v57, -v48, v104, v57
	v_fma_f32 v69, -v49, v105, v69
	v_fma_f32 v70, -v51, v106, v70
	v_fma_f32 v71, -v53, v107, v71
	ds_read_b128 v[104:107], v78 offset:13920
	s_waitcnt lgkmcnt(6)
	v_fma_f32 v57, -v54, v108, v57
	v_fma_f32 v69, -v56, v109, v69
	v_fma_f32 v70, -v58, v110, v70
	v_fma_f32 v71, -v61, v111, v71
	ds_read_b128 v[108:111], v78 offset:13936
	s_waitcnt lgkmcnt(6)
	v_fma_f32 v57, -v63, v84, v57
	v_fma_f32 v69, -v65, v85, v69
	v_fma_f32 v70, -v64, v86, v70
	v_fma_f32 v71, -v62, v87, v71
	ds_read_b128 v[84:87], v78 offset:13952
	s_waitcnt lgkmcnt(6)
	v_fma_f32 v57, -v60, v88, v57
	v_mov_b32_e32 v75, v89
	ds_read_b128 v[88:91], v78 offset:13968
	s_waitcnt lgkmcnt(6)
	v_fma_f32 v55, -v2, v92, v55
	v_fma_f32 v72, -v3, v93, 0
	v_fma_f32 v73, -v5, v94, 0
	v_fma_f32 v69, -v59, v75, v69
	v_fma_f32 v74, -v6, v95, 0
	ds_read_b128 v[92:95], v78 offset:13984
	s_waitcnt lgkmcnt(6)
	v_fma_f32 v55, -v7, v96, v55
	v_fma_f32 v72, -v8, v97, v72
	v_add_f32_e32 v69, v57, v69
	v_fma_f32 v73, -v9, v98, v73
	v_fma_f32 v74, -v10, v99, v74
	ds_read_b128 v[96:99], v78 offset:14000
	s_waitcnt lgkmcnt(6)
; DI void gdn_prep(const Params& p, int item, unsigned char* smem) {
;     ...
;         for (int i = 1; i < 64; ++i) {
;             float a = X[i];
;             int dep; asm volatile("v_and_b32 %0, 0, %1" : "=v"(dep) : "v"(X[i - 1]));
;             const float* Lr = sL + i * 68 + dep;
;             float b0 = 0.f, b1 = 0.f, b2 = 0.f;
; #pragma unroll
;             for (int j4 = 0; j4 < (i + 3) / 4; ++j4) {
;                 const f32x4 l = *(const f32x4*)(Lr + 4 * j4);
;                 if (4 * j4 + 0 < i) a -= l.x * X[4 * j4 + 0];
;                 if (4 * j4 + 1 < i) b0 -= l.y * X[4 * j4 + 1];
;                 if (4 * j4 + 2 < i) b1 -= l.z * X[4 * j4 + 2];
;                 if (4 * j4 + 3 < i) b2 -= l.w * X[4 * j4 + 3];
;             }
;             X[i] = (a + b0) + (b1 + b2);
	v_fma_f32 v55, -v11, v100, v55
	v_add_f32_e32 v70, v70, v71
	v_fma_f32 v72, -v12, v101, v72
	v_fma_f32 v73, -v13, v102, v73
	v_fma_f32 v74, -v14, v103, v74
	v_add_f32_e32 v57, v69, v70
	ds_read_b128 v[100:103], v78 offset:14016
	s_waitcnt lgkmcnt(6)
	v_fma_f32 v55, -v15, v104, v55
	v_fma_f32 v72, -v16, v105, v72
	v_fma_f32 v73, -v66, v106, v73
	v_fma_f32 v74, -v17, v107, v74
	ds_read_b128 v[104:107], v78 offset:14032
	s_waitcnt lgkmcnt(6)
	v_fma_f32 v55, -v18, v108, v55
	v_fma_f32 v72, -v19, v109, v72
	v_fma_f32 v73, -v20, v110, v73
	v_fma_f32 v74, -v21, v111, v74
	ds_read_b128 v[108:111], v78 offset:14048
	s_waitcnt lgkmcnt(6)
	v_fma_f32 v55, -v22, v84, v55
	v_fma_f32 v72, -v23, v85, v72
	v_fma_f32 v73, -v24, v86, v73
	v_fma_f32 v74, -v25, v87, v74
	ds_read_b128 v[84:87], v78 offset:14064
	s_waitcnt lgkmcnt(6)
	v_fma_f32 v55, -v26, v88, v55
	v_fma_f32 v72, -v27, v89, v72
	v_fma_f32 v73, -v29, v90, v73
	v_fma_f32 v74, -v30, v91, v74
	ds_read_b128 v[88:91], v78 offset:14144
	s_waitcnt lgkmcnt(6)
	v_fma_f32 v55, -v33, v92, v55
	v_fma_f32 v72, -v34, v93, v72
	v_fma_f32 v73, -v36, v94, v73
	v_fma_f32 v74, -v37, v95, v74
	ds_read_b128 v[92:95], v78 offset:14160
	s_waitcnt lgkmcnt(6)
	v_fma_f32 v55, -v39, v96, v55
	v_fma_f32 v72, -v41, v97, v72
	v_fma_f32 v73, -v42, v98, v73
	v_fma_f32 v74, -v44, v99, v74
	ds_read_b128 v[96:99], v78 offset:14176
	s_waitcnt lgkmcnt(6)
	v_fma_f32 v55, -v48, v100, v55
	v_fma_f32 v72, -v49, v101, v72
	v_fma_f32 v73, -v51, v102, v73
	v_fma_f32 v74, -v53, v103, v74
	ds_read_b128 v[100:103], v78 offset:14192
	s_waitcnt lgkmcnt(6)
	v_fma_f32 v55, -v54, v104, v55
	v_fma_f32 v72, -v56, v105, v72
	v_fma_f32 v73, -v58, v106, v73
	v_fma_f32 v74, -v61, v107, v74
	ds_read_b128 v[104:107], v78 offset:14208
	s_waitcnt lgkmcnt(6)
	v_fma_f32 v55, -v63, v108, v55
	v_fma_f32 v72, -v65, v109, v72
	v_fma_f32 v73, -v64, v110, v73
	v_fma_f32 v74, -v62, v111, v74
	ds_read_b128 v[108:111], v78 offset:14224
	s_waitcnt lgkmcnt(6)
	v_fma_f32 v55, -v60, v84, v55
	v_fma_f32 v72, -v59, v85, v72
	v_mov_b32_e32 v76, v86
	ds_read_b128 v[84:87], v78 offset:14240
	s_waitcnt lgkmcnt(6)
	v_fma_f32 v52, -v2, v88, v52
	v_fma_f32 v69, -v3, v89, 0
	v_fma_f32 v70, -v5, v90, 0
	v_fma_f32 v73, -v57, v76, v73
	v_fma_f32 v71, -v6, v91, 0
	ds_read_b128 v[88:91], v78 offset:14256
	s_waitcnt lgkmcnt(6)
	v_fma_f32 v52, -v7, v92, v52
	v_fma_f32 v69, -v8, v93, v69
	v_add_f32_e32 v72, v55, v72
	v_fma_f32 v70, -v9, v94, v70
	v_fma_f32 v71, -v10, v95, v71
	ds_read_b128 v[92:95], v78 offset:14272
	s_waitcnt lgkmcnt(6)
	v_fma_f32 v52, -v11, v96, v52
	v_add_f32_e32 v73, v73, v74
	v_fma_f32 v69, -v12, v97, v69
	v_fma_f32 v70, -v13, v98, v70
	v_fma_f32 v71, -v14, v99, v71
	v_add_f32_e32 v55, v72, v73
	ds_read_b128 v[96:99], v78 offset:14288
	s_waitcnt lgkmcnt(6)
	v_fma_f32 v52, -v15, v100, v52
	v_fma_f32 v69, -v16, v101, v69
	v_fma_f32 v70, -v66, v102, v70
	v_fma_f32 v71, -v17, v103, v71
	ds_read_b128 v[100:103], v78 offset:14304
	s_waitcnt lgkmcnt(6)
	v_fma_f32 v52, -v18, v104, v52
	v_fma_f32 v69, -v19, v105, v69
	v_fma_f32 v70, -v20, v106, v70
	v_fma_f32 v71, -v21, v107, v71
	ds_read_b128 v[104:107], v78 offset:14320
	s_waitcnt lgkmcnt(6)
	v_fma_f32 v52, -v22, v108, v52
	v_fma_f32 v69, -v23, v109, v69
	v_fma_f32 v70, -v24, v110, v70
	v_fma_f32 v71, -v25, v111, v71
	ds_read_b128 v[108:111], v78 offset:14336
	s_waitcnt lgkmcnt(6)
	v_fma_f32 v52, -v26, v84, v52
	v_fma_f32 v69, -v27, v85, v69
	v_fma_f32 v70, -v29, v86, v70
	v_fma_f32 v71, -v30, v87, v71
	ds_read_b128 v[84:87], v78 offset:14416
	s_waitcnt lgkmcnt(6)
	v_fma_f32 v52, -v33, v88, v52
	v_fma_f32 v69, -v34, v89, v69
	v_fma_f32 v70, -v36, v90, v70
	v_fma_f32 v71, -v37, v91, v71
	ds_read_b128 v[88:91], v78 offset:14432
	s_waitcnt lgkmcnt(6)
	v_fma_f32 v52, -v39, v92, v52
	v_fma_f32 v69, -v41, v93, v69
	v_fma_f32 v70, -v42, v94, v70
	v_fma_f32 v71, -v44, v95, v71
	ds_read_b128 v[92:95], v78 offset:14448
	s_waitcnt lgkmcnt(6)
	v_fma_f32 v52, -v48, v96, v52
	v_fma_f32 v69, -v49, v97, v69
	v_fma_f32 v70, -v51, v98, v70
	v_fma_f32 v71, -v53, v99, v71
	ds_read_b128 v[96:99], v78 offset:14464
	s_waitcnt lgkmcnt(6)
	v_fma_f32 v52, -v54, v100, v52
	v_fma_f32 v69, -v56, v101, v69
	v_fma_f32 v70, -v58, v102, v70
	v_fma_f32 v71, -v61, v103, v71
	ds_read_b128 v[100:103], v78 offset:14480
	s_waitcnt lgkmcnt(6)
	v_fma_f32 v52, -v63, v104, v52
	v_fma_f32 v69, -v65, v105, v69
	v_fma_f32 v70, -v64, v106, v70
	v_fma_f32 v71, -v62, v107, v71
	ds_read_b128 v[104:107], v78 offset:14496
	s_waitcnt lgkmcnt(6)
	v_fma_f32 v52, -v60, v108, v52
	v_fma_f32 v69, -v59, v109, v69
	v_fma_f32 v70, -v57, v110, v70
	v_mov_b32_e32 v75, v111
	ds_read_b128 v[108:111], v78 offset:14512
	s_waitcnt lgkmcnt(6)
	v_fma_f32 v50, -v2, v84, v50
	v_fma_f32 v72, -v3, v85, 0
	v_fma_f32 v73, -v5, v86, 0
	v_fma_f32 v71, -v55, v75, v71
	v_fma_f32 v74, -v6, v87, 0
	ds_read_b128 v[84:87], v78 offset:14528
	s_waitcnt lgkmcnt(6)
	v_fma_f32 v50, -v7, v88, v50
	v_fma_f32 v72, -v8, v89, v72
	v_add_f32_e32 v69, v52, v69
	v_fma_f32 v73, -v9, v90, v73
	v_fma_f32 v74, -v10, v91, v74
	ds_read_b128 v[88:91], v78 offset:14544
	s_waitcnt lgkmcnt(6)
	v_fma_f32 v50, -v11, v92, v50
	v_add_f32_e32 v70, v70, v71
	v_fma_f32 v72, -v12, v93, v72
	v_fma_f32 v73, -v13, v94, v73
	v_fma_f32 v74, -v14, v95, v74
	v_add_f32_e32 v52, v69, v70
	ds_read_b128 v[92:95], v78 offset:14560
	s_waitcnt lgkmcnt(6)
	v_fma_f32 v50, -v15, v96, v50
	v_fma_f32 v72, -v16, v97, v72
	v_fma_f32 v73, -v66, v98, v73
	v_fma_f32 v74, -v17, v99, v74
	ds_read_b128 v[96:99], v78 offset:14576
	s_waitcnt lgkmcnt(6)
	v_fma_f32 v50, -v18, v100, v50
	v_fma_f32 v72, -v19, v101, v72
	v_fma_f32 v73, -v20, v102, v73
	v_fma_f32 v74, -v21, v103, v74
	ds_read_b128 v[100:103], v78 offset:14592
	s_waitcnt lgkmcnt(6)
; DI void gdn_prep(const Params& p, int item, unsigned char* smem) {
;     ...
;         for (int i = 1; i < 64; ++i) {
;             float a = X[i];
;             int dep; asm volatile("v_and_b32 %0, 0, %1" : "=v"(dep) : "v"(X[i - 1]));
;             const float* Lr = sL + i * 68 + dep;
;             float b0 = 0.f, b1 = 0.f, b2 = 0.f;
; #pragma unroll
;             for (int j4 = 0; j4 < (i + 3) / 4; ++j4) {
;                 const f32x4 l = *(const f32x4*)(Lr + 4 * j4);
;                 if (4 * j4 + 0 < i) a -= l.x * X[4 * j4 + 0];
;                 if (4 * j4 + 1 < i) b0 -= l.y * X[4 * j4 + 1];
;                 if (4 * j4 + 2 < i) b1 -= l.z * X[4 * j4 + 2];
;                 if (4 * j4 + 3 < i) b2 -= l.w * X[4 * j4 + 3];
;             }
;             X[i] = (a + b0) + (b1 + b2);
	v_fma_f32 v50, -v22, v104, v50
	v_fma_f32 v72, -v23, v105, v72
	v_fma_f32 v73, -v24, v106, v73
	v_fma_f32 v74, -v25, v107, v74
	ds_read_b128 v[104:107], v78 offset:14608
	s_waitcnt lgkmcnt(6)
	v_fma_f32 v50, -v26, v108, v50
	v_fma_f32 v72, -v27, v109, v72
	v_fma_f32 v73, -v29, v110, v73
	v_fma_f32 v74, -v30, v111, v74
	ds_read_b128 v[108:111], v78 offset:14624
	s_waitcnt lgkmcnt(6)
	v_fma_f32 v50, -v33, v84, v50
	v_fma_f32 v72, -v34, v85, v72
	v_fma_f32 v73, -v36, v86, v73
	v_fma_f32 v74, -v37, v87, v74
	ds_read_b128 v[84:87], v78 offset:14688
	s_waitcnt lgkmcnt(6)
	v_fma_f32 v50, -v39, v88, v50
	v_fma_f32 v72, -v41, v89, v72
	v_fma_f32 v73, -v42, v90, v73
	v_fma_f32 v74, -v44, v91, v74
	ds_read_b128 v[88:91], v78 offset:14704
	s_waitcnt lgkmcnt(6)
	v_fma_f32 v50, -v48, v92, v50
	v_fma_f32 v72, -v49, v93, v72
	v_fma_f32 v73, -v51, v94, v73
	v_fma_f32 v74, -v53, v95, v74
	ds_read_b128 v[92:95], v78 offset:14720
	s_waitcnt lgkmcnt(6)
	v_fma_f32 v50, -v54, v96, v50
	v_fma_f32 v72, -v56, v97, v72
	v_fma_f32 v73, -v58, v98, v73
	v_fma_f32 v74, -v61, v99, v74
	ds_read_b128 v[96:99], v78 offset:14736
	s_waitcnt lgkmcnt(6)
	v_fma_f32 v50, -v63, v100, v50
	v_fma_f32 v72, -v65, v101, v72
	v_fma_f32 v73, -v64, v102, v73
	v_fma_f32 v74, -v62, v103, v74
	ds_read_b128 v[100:103], v78 offset:14752
	s_waitcnt lgkmcnt(6)
	v_fma_f32 v50, -v60, v104, v50
	v_fma_f32 v72, -v59, v105, v72
	v_fma_f32 v73, -v57, v106, v73
	v_fma_f32 v74, -v55, v107, v74
	ds_read_b128 v[104:107], v78 offset:14768
	s_waitcnt lgkmcnt(6)
	v_mov_b32_e32 v76, v108
	ds_read_b128 v[108:111], v78 offset:14784
	s_waitcnt lgkmcnt(6)
	v_fma_f32 v47, -v2, v84, v47
	v_fma_f32 v69, -v3, v85, 0
	v_fma_f32 v70, -v5, v86, 0
	v_fma_f32 v50, -v52, v76, v50
	v_fma_f32 v71, -v6, v87, 0
	ds_read_b128 v[84:87], v78 offset:14800
	s_waitcnt lgkmcnt(6)
	v_fma_f32 v47, -v7, v88, v47
	v_fma_f32 v69, -v8, v89, v69
	v_add_f32_e32 v72, v50, v72
	v_fma_f32 v70, -v9, v90, v70
	v_fma_f32 v71, -v10, v91, v71
	ds_read_b128 v[88:91], v78 offset:14816
	s_waitcnt lgkmcnt(6)
	v_fma_f32 v47, -v11, v92, v47
	v_add_f32_e32 v73, v73, v74
	v_fma_f32 v69, -v12, v93, v69
	v_fma_f32 v70, -v13, v94, v70
	v_fma_f32 v71, -v14, v95, v71
	v_add_f32_e32 v50, v72, v73
	ds_read_b128 v[92:95], v78 offset:14832
	s_waitcnt lgkmcnt(6)
	v_fma_f32 v47, -v15, v96, v47
	v_fma_f32 v69, -v16, v97, v69
	v_fma_f32 v70, -v66, v98, v70
	v_fma_f32 v71, -v17, v99, v71
	ds_read_b128 v[96:99], v78 offset:14848
	s_waitcnt lgkmcnt(6)
	v_fma_f32 v47, -v18, v100, v47
	v_fma_f32 v69, -v19, v101, v69
	v_fma_f32 v70, -v20, v102, v70
	v_fma_f32 v71, -v21, v103, v71
	ds_read_b128 v[100:103], v78 offset:14864
	s_waitcnt lgkmcnt(6)
	v_fma_f32 v47, -v22, v104, v47
	v_fma_f32 v69, -v23, v105, v69
	v_fma_f32 v70, -v24, v106, v70
	v_fma_f32 v71, -v25, v107, v71
	ds_read_b128 v[104:107], v78 offset:14880
	s_waitcnt lgkmcnt(6)
	v_fma_f32 v47, -v26, v108, v47
	v_fma_f32 v69, -v27, v109, v69
	v_fma_f32 v70, -v29, v110, v70
	v_fma_f32 v71, -v30, v111, v71
	ds_read_b128 v[108:111], v78 offset:14896
	s_waitcnt lgkmcnt(6)
	v_fma_f32 v47, -v33, v84, v47
	v_fma_f32 v69, -v34, v85, v69
	v_fma_f32 v70, -v36, v86, v70
	v_fma_f32 v71, -v37, v87, v71
	ds_read_b128 v[84:87], v78 offset:14960
	s_waitcnt lgkmcnt(6)
	v_fma_f32 v47, -v39, v88, v47
	v_fma_f32 v69, -v41, v89, v69
	v_fma_f32 v70, -v42, v90, v70
	v_fma_f32 v71, -v44, v91, v71
	ds_read_b128 v[88:91], v78 offset:14976
	s_waitcnt lgkmcnt(6)
	v_fma_f32 v47, -v48, v92, v47
	v_fma_f32 v69, -v49, v93, v69
	v_fma_f32 v70, -v51, v94, v70
	v_fma_f32 v71, -v53, v95, v71
	ds_read_b128 v[92:95], v78 offset:14992
	s_waitcnt lgkmcnt(6)
	v_fma_f32 v47, -v54, v96, v47
	v_fma_f32 v69, -v56, v97, v69
	v_fma_f32 v70, -v58, v98, v70
	v_fma_f32 v71, -v61, v99, v71
	ds_read_b128 v[96:99], v78 offset:15008
	s_waitcnt lgkmcnt(6)
	v_fma_f32 v47, -v63, v100, v47
	v_fma_f32 v69, -v65, v101, v69
	v_fma_f32 v70, -v64, v102, v70
	v_fma_f32 v71, -v62, v103, v71
	ds_read_b128 v[100:103], v78 offset:15024
	s_waitcnt lgkmcnt(6)
	v_fma_f32 v47, -v60, v104, v47
	v_fma_f32 v69, -v59, v105, v69
	v_fma_f32 v70, -v57, v106, v70
	v_fma_f32 v71, -v55, v107, v71
	ds_read_b128 v[104:107], v78 offset:15040
	s_waitcnt lgkmcnt(6)
	v_fma_f32 v47, -v52, v108, v47
	v_mov_b32_e32 v75, v109
	ds_read_b128 v[108:111], v78 offset:15056
	s_waitcnt lgkmcnt(6)
	v_fma_f32 v45, -v2, v84, v45
	v_fma_f32 v72, -v3, v85, 0
	v_fma_f32 v73, -v5, v86, 0
	v_fma_f32 v69, -v50, v75, v69
	v_fma_f32 v74, -v6, v87, 0
	ds_read_b128 v[84:87], v78 offset:15072
	s_waitcnt lgkmcnt(6)
	v_fma_f32 v45, -v7, v88, v45
	v_fma_f32 v72, -v8, v89, v72
	v_add_f32_e32 v69, v47, v69
	v_fma_f32 v73, -v9, v90, v73
	v_fma_f32 v74, -v10, v91, v74
	ds_read_b128 v[88:91], v78 offset:15088
	s_waitcnt lgkmcnt(6)
	v_fma_f32 v45, -v11, v92, v45
	v_add_f32_e32 v70, v70, v71
	v_fma_f32 v72, -v12, v93, v72
	v_fma_f32 v73, -v13, v94, v73
	v_fma_f32 v74, -v14, v95, v74
	v_add_f32_e32 v47, v69, v70
	ds_read_b128 v[92:95], v78 offset:15104
	s_waitcnt lgkmcnt(6)
	v_fma_f32 v45, -v15, v96, v45
	v_fma_f32 v72, -v16, v97, v72
	v_fma_f32 v73, -v66, v98, v73
	v_fma_f32 v74, -v17, v99, v74
	ds_read_b128 v[96:99], v78 offset:15120
	s_waitcnt lgkmcnt(6)
	v_fma_f32 v45, -v18, v100, v45
	v_fma_f32 v72, -v19, v101, v72
	v_fma_f32 v73, -v20, v102, v73
	v_fma_f32 v74, -v21, v103, v74
	ds_read_b128 v[100:103], v78 offset:15136
	s_waitcnt lgkmcnt(6)
	v_fma_f32 v45, -v22, v104, v45
	v_fma_f32 v72, -v23, v105, v72
	v_fma_f32 v73, -v24, v106, v73
	v_fma_f32 v74, -v25, v107, v74
	ds_read_b128 v[104:107], v78 offset:15152
	s_waitcnt lgkmcnt(6)
	v_fma_f32 v45, -v26, v108, v45
	v_fma_f32 v72, -v27, v109, v72
	v_fma_f32 v73, -v29, v110, v73
	v_fma_f32 v74, -v30, v111, v74
	ds_read_b128 v[108:111], v78 offset:15168
	s_waitcnt lgkmcnt(6)
; DI void gdn_prep(const Params& p, int item, unsigned char* smem) {
;     ...
;         for (int i = 1; i < 64; ++i) {
;             float a = X[i];
;             int dep; asm volatile("v_and_b32 %0, 0, %1" : "=v"(dep) : "v"(X[i - 1]));
;             const float* Lr = sL + i * 68 + dep;
;             float b0 = 0.f, b1 = 0.f, b2 = 0.f;
; #pragma unroll
;             for (int j4 = 0; j4 < (i + 3) / 4; ++j4) {
;                 const f32x4 l = *(const f32x4*)(Lr + 4 * j4);
;                 if (4 * j4 + 0 < i) a -= l.x * X[4 * j4 + 0];
;                 if (4 * j4 + 1 < i) b0 -= l.y * X[4 * j4 + 1];
;                 if (4 * j4 + 2 < i) b1 -= l.z * X[4 * j4 + 2];
;                 if (4 * j4 + 3 < i) b2 -= l.w * X[4 * j4 + 3];
;             }
;             X[i] = (a + b0) + (b1 + b2);
	v_fma_f32 v45, -v33, v84, v45
	v_fma_f32 v72, -v34, v85, v72
	v_fma_f32 v73, -v36, v86, v73
	v_fma_f32 v74, -v37, v87, v74
	ds_read_b128 v[84:87], v78 offset:15232
	s_waitcnt lgkmcnt(6)
	v_fma_f32 v45, -v39, v88, v45
	v_fma_f32 v72, -v41, v89, v72
	v_fma_f32 v73, -v42, v90, v73
	v_fma_f32 v74, -v44, v91, v74
	ds_read_b128 v[88:91], v78 offset:15248
	s_waitcnt lgkmcnt(6)
	v_fma_f32 v45, -v48, v92, v45
	v_fma_f32 v72, -v49, v93, v72
	v_fma_f32 v73, -v51, v94, v73
	v_fma_f32 v74, -v53, v95, v74
	ds_read_b128 v[92:95], v78 offset:15264
	s_waitcnt lgkmcnt(6)
	v_fma_f32 v45, -v54, v96, v45
	v_fma_f32 v72, -v56, v97, v72
	v_fma_f32 v73, -v58, v98, v73
	v_fma_f32 v74, -v61, v99, v74
	ds_read_b128 v[96:99], v78 offset:15280
	s_waitcnt lgkmcnt(6)
	v_fma_f32 v45, -v63, v100, v45
	v_fma_f32 v72, -v65, v101, v72
	v_fma_f32 v73, -v64, v102, v73
	v_fma_f32 v74, -v62, v103, v74
	ds_read_b128 v[100:103], v78 offset:15296
	s_waitcnt lgkmcnt(6)
	v_fma_f32 v45, -v60, v104, v45
	v_fma_f32 v72, -v59, v105, v72
	v_fma_f32 v73, -v57, v106, v73
	v_fma_f32 v74, -v55, v107, v74
	ds_read_b128 v[104:107], v78 offset:15312
	s_waitcnt lgkmcnt(6)
	v_fma_f32 v45, -v52, v108, v45
	v_fma_f32 v72, -v50, v109, v72
	v_mov_b32_e32 v76, v110
	ds_read_b128 v[108:111], v78 offset:15328
	s_waitcnt lgkmcnt(6)
	v_fma_f32 v43, -v2, v84, v43
	v_fma_f32 v69, -v3, v85, 0
	v_fma_f32 v70, -v5, v86, 0
	v_fma_f32 v73, -v47, v76, v73
	v_fma_f32 v71, -v6, v87, 0
	ds_read_b128 v[84:87], v78 offset:15344
	s_waitcnt lgkmcnt(6)
	v_fma_f32 v43, -v7, v88, v43
	v_fma_f32 v69, -v8, v89, v69
	v_add_f32_e32 v72, v45, v72
	v_fma_f32 v70, -v9, v90, v70
	v_fma_f32 v71, -v10, v91, v71
	ds_read_b128 v[88:91], v78 offset:15360
	s_waitcnt lgkmcnt(6)
	v_fma_f32 v43, -v11, v92, v43
	v_add_f32_e32 v73, v73, v74
	v_fma_f32 v69, -v12, v93, v69
	v_fma_f32 v70, -v13, v94, v70
	v_fma_f32 v71, -v14, v95, v71
	v_add_f32_e32 v45, v72, v73
	ds_read_b128 v[92:95], v78 offset:15376
	s_waitcnt lgkmcnt(6)
	v_fma_f32 v43, -v15, v96, v43
	v_fma_f32 v69, -v16, v97, v69
	v_fma_f32 v70, -v66, v98, v70
	v_fma_f32 v71, -v17, v99, v71
	ds_read_b128 v[96:99], v78 offset:15392
	s_waitcnt lgkmcnt(6)
	v_fma_f32 v43, -v18, v100, v43
	v_fma_f32 v69, -v19, v101, v69
	v_fma_f32 v70, -v20, v102, v70
	v_fma_f32 v71, -v21, v103, v71
	ds_read_b128 v[100:103], v78 offset:15408
	s_waitcnt lgkmcnt(6)
	v_fma_f32 v43, -v22, v104, v43
	v_fma_f32 v69, -v23, v105, v69
	v_fma_f32 v70, -v24, v106, v70
	v_fma_f32 v71, -v25, v107, v71
	ds_read_b128 v[104:107], v78 offset:15424
	s_waitcnt lgkmcnt(6)
	v_fma_f32 v43, -v26, v108, v43
	v_fma_f32 v69, -v27, v109, v69
	v_fma_f32 v70, -v29, v110, v70
	v_fma_f32 v71, -v30, v111, v71
	ds_read_b128 v[108:111], v78 offset:15440
	s_waitcnt lgkmcnt(6)
	v_fma_f32 v43, -v33, v84, v43
	v_fma_f32 v69, -v34, v85, v69
	v_fma_f32 v70, -v36, v86, v70
	v_fma_f32 v71, -v37, v87, v71
	ds_read_b128 v[84:87], v78 offset:15504
	s_waitcnt lgkmcnt(6)
	v_fma_f32 v43, -v39, v88, v43
	v_fma_f32 v69, -v41, v89, v69
	v_fma_f32 v70, -v42, v90, v70
	v_fma_f32 v71, -v44, v91, v71
	ds_read_b128 v[88:91], v78 offset:15520
	s_waitcnt lgkmcnt(6)
	v_fma_f32 v43, -v48, v92, v43
	v_fma_f32 v69, -v49, v93, v69
	v_fma_f32 v70, -v51, v94, v70
	v_fma_f32 v71, -v53, v95, v71
	ds_read_b128 v[92:95], v78 offset:15536
	s_waitcnt lgkmcnt(6)
	v_fma_f32 v43, -v54, v96, v43
	v_fma_f32 v69, -v56, v97, v69
	v_fma_f32 v70, -v58, v98, v70
	v_fma_f32 v71, -v61, v99, v71
	ds_read_b128 v[96:99], v78 offset:15552
	s_waitcnt lgkmcnt(6)
	v_fma_f32 v43, -v63, v100, v43
	v_fma_f32 v69, -v65, v101, v69
	v_fma_f32 v70, -v64, v102, v70
	v_fma_f32 v71, -v62, v103, v71
	ds_read_b128 v[100:103], v78 offset:15568
	s_waitcnt lgkmcnt(6)
	v_fma_f32 v43, -v60, v104, v43
	v_fma_f32 v69, -v59, v105, v69
	v_fma_f32 v70, -v57, v106, v70
	v_fma_f32 v71, -v55, v107, v71
	ds_read_b128 v[104:107], v78 offset:15584
	s_waitcnt lgkmcnt(6)
	v_fma_f32 v43, -v52, v108, v43
	v_fma_f32 v69, -v50, v109, v69
	v_fma_f32 v70, -v47, v110, v70
	v_mov_b32_e32 v75, v111
	ds_read_b128 v[108:111], v78 offset:15600
	s_waitcnt lgkmcnt(6)
	v_fma_f32 v40, -v2, v84, v40
	v_fma_f32 v72, -v3, v85, 0
	v_fma_f32 v73, -v5, v86, 0
	v_fma_f32 v71, -v45, v75, v71
	v_fma_f32 v74, -v6, v87, 0
	ds_read_b128 v[84:87], v78 offset:15616
	s_waitcnt lgkmcnt(6)
	v_fma_f32 v40, -v7, v88, v40
	v_fma_f32 v72, -v8, v89, v72
	v_add_f32_e32 v69, v43, v69
	v_fma_f32 v73, -v9, v90, v73
	v_fma_f32 v74, -v10, v91, v74
	ds_read_b128 v[88:91], v78 offset:15632
	s_waitcnt lgkmcnt(6)
	v_fma_f32 v40, -v11, v92, v40
	v_add_f32_e32 v70, v70, v71
	v_fma_f32 v72, -v12, v93, v72
	v_fma_f32 v73, -v13, v94, v73
	v_fma_f32 v74, -v14, v95, v74
	v_add_f32_e32 v43, v69, v70
	ds_read_b128 v[92:95], v78 offset:15648
	s_waitcnt lgkmcnt(6)
	v_fma_f32 v40, -v15, v96, v40
	v_fma_f32 v72, -v16, v97, v72
	v_fma_f32 v73, -v66, v98, v73
	v_fma_f32 v74, -v17, v99, v74
	ds_read_b128 v[96:99], v78 offset:15664
	s_waitcnt lgkmcnt(6)
	v_fma_f32 v40, -v18, v100, v40
	v_fma_f32 v72, -v19, v101, v72
	v_fma_f32 v73, -v20, v102, v73
	v_fma_f32 v74, -v21, v103, v74
	ds_read_b128 v[100:103], v78 offset:15680
	s_waitcnt lgkmcnt(6)
	v_fma_f32 v40, -v22, v104, v40
	v_fma_f32 v72, -v23, v105, v72
	v_fma_f32 v73, -v24, v106, v73
	v_fma_f32 v74, -v25, v107, v74
	ds_read_b128 v[104:107], v78 offset:15696
	s_waitcnt lgkmcnt(6)
	v_fma_f32 v40, -v26, v108, v40
	v_fma_f32 v72, -v27, v109, v72
	v_fma_f32 v73, -v29, v110, v73
	v_fma_f32 v74, -v30, v111, v74
	ds_read_b128 v[108:111], v78 offset:15712
	s_waitcnt lgkmcnt(6)
	v_fma_f32 v40, -v33, v84, v40
	v_fma_f32 v72, -v34, v85, v72
	v_fma_f32 v73, -v36, v86, v73
	v_fma_f32 v74, -v37, v87, v74
	ds_read_b128 v[84:87], v78 offset:15728
	s_waitcnt lgkmcnt(6)
; DI void gdn_prep(const Params& p, int item, unsigned char* smem) {
;     ...
;         for (int i = 1; i < 64; ++i) {
;             float a = X[i];
;             int dep; asm volatile("v_and_b32 %0, 0, %1" : "=v"(dep) : "v"(X[i - 1]));
;             const float* Lr = sL + i * 68 + dep;
;             float b0 = 0.f, b1 = 0.f, b2 = 0.f;
; #pragma unroll
;             for (int j4 = 0; j4 < (i + 3) / 4; ++j4) {
;                 const f32x4 l = *(const f32x4*)(Lr + 4 * j4);
;                 if (4 * j4 + 0 < i) a -= l.x * X[4 * j4 + 0];
;                 if (4 * j4 + 1 < i) b0 -= l.y * X[4 * j4 + 1];
;                 if (4 * j4 + 2 < i) b1 -= l.z * X[4 * j4 + 2];
;                 if (4 * j4 + 3 < i) b2 -= l.w * X[4 * j4 + 3];
;             }
;             X[i] = (a + b0) + (b1 + b2);
	v_fma_f32 v40, -v39, v88, v40
	v_fma_f32 v72, -v41, v89, v72
	v_fma_f32 v73, -v42, v90, v73
	v_fma_f32 v74, -v44, v91, v74
	ds_read_b128 v[88:91], v78 offset:15776
	s_waitcnt lgkmcnt(6)
	v_fma_f32 v40, -v48, v92, v40
	v_fma_f32 v72, -v49, v93, v72
	v_fma_f32 v73, -v51, v94, v73
	v_fma_f32 v74, -v53, v95, v74
	ds_read_b128 v[92:95], v78 offset:15792
	s_waitcnt lgkmcnt(6)
	v_fma_f32 v40, -v54, v96, v40
	v_fma_f32 v72, -v56, v97, v72
	v_fma_f32 v73, -v58, v98, v73
	v_fma_f32 v74, -v61, v99, v74
	ds_read_b128 v[96:99], v78 offset:15808
	s_waitcnt lgkmcnt(6)
	v_fma_f32 v40, -v63, v100, v40
	v_fma_f32 v72, -v65, v101, v72
	v_fma_f32 v73, -v64, v102, v73
	v_fma_f32 v74, -v62, v103, v74
	ds_read_b128 v[100:103], v78 offset:15824
	s_waitcnt lgkmcnt(6)
	v_fma_f32 v40, -v60, v104, v40
	v_fma_f32 v72, -v59, v105, v72
	v_fma_f32 v73, -v57, v106, v73
	v_fma_f32 v74, -v55, v107, v74
	ds_read_b128 v[104:107], v78 offset:15840
	s_waitcnt lgkmcnt(6)
	v_fma_f32 v40, -v52, v108, v40
	v_fma_f32 v72, -v50, v109, v72
	v_fma_f32 v73, -v47, v110, v73
	v_fma_f32 v74, -v45, v111, v74
	ds_read_b128 v[108:111], v78 offset:15856
	s_waitcnt lgkmcnt(6)
	v_mov_b32_e32 v76, v84
	ds_read_b128 v[84:87], v78 offset:15872
	s_waitcnt lgkmcnt(6)
	v_fma_f32 v38, -v2, v88, v38
	v_fma_f32 v69, -v3, v89, 0
	v_fma_f32 v70, -v5, v90, 0
	v_fma_f32 v40, -v43, v76, v40
	v_fma_f32 v71, -v6, v91, 0
	ds_read_b128 v[88:91], v78 offset:15888
	s_waitcnt lgkmcnt(6)
	v_fma_f32 v38, -v7, v92, v38
	v_fma_f32 v69, -v8, v93, v69
	v_add_f32_e32 v72, v40, v72
	v_fma_f32 v70, -v9, v94, v70
	v_fma_f32 v71, -v10, v95, v71
	ds_read_b128 v[92:95], v78 offset:15904
	s_waitcnt lgkmcnt(6)
	v_fma_f32 v38, -v11, v96, v38
	v_add_f32_e32 v73, v73, v74
	v_fma_f32 v69, -v12, v97, v69
	v_fma_f32 v70, -v13, v98, v70
	v_fma_f32 v71, -v14, v99, v71
	v_add_f32_e32 v40, v72, v73
	ds_read_b128 v[96:99], v78 offset:15920
	s_waitcnt lgkmcnt(6)
	v_fma_f32 v38, -v15, v100, v38
	v_fma_f32 v69, -v16, v101, v69
	v_fma_f32 v70, -v66, v102, v70
	v_fma_f32 v71, -v17, v103, v71
	ds_read_b128 v[100:103], v78 offset:15936
	s_waitcnt lgkmcnt(6)
	v_fma_f32 v38, -v18, v104, v38
	v_fma_f32 v69, -v19, v105, v69
	v_fma_f32 v70, -v20, v106, v70
	v_fma_f32 v71, -v21, v107, v71
	ds_read_b128 v[104:107], v78 offset:15952
	s_waitcnt lgkmcnt(6)
	v_fma_f32 v38, -v22, v108, v38
	v_fma_f32 v69, -v23, v109, v69
	v_fma_f32 v70, -v24, v110, v70
	v_fma_f32 v71, -v25, v111, v71
	ds_read_b128 v[108:111], v78 offset:15968
	s_waitcnt lgkmcnt(6)
	v_fma_f32 v38, -v26, v84, v38
	v_fma_f32 v69, -v27, v85, v69
	v_fma_f32 v70, -v29, v86, v70
	v_fma_f32 v71, -v30, v87, v71
	ds_read_b128 v[84:87], v78 offset:15984
	s_waitcnt lgkmcnt(6)
	v_fma_f32 v38, -v33, v88, v38
	v_fma_f32 v69, -v34, v89, v69
	v_fma_f32 v70, -v36, v90, v70
	v_fma_f32 v71, -v37, v91, v71
	ds_read_b128 v[88:91], v78 offset:16000
	s_waitcnt lgkmcnt(6)
	v_fma_f32 v38, -v39, v92, v38
	v_fma_f32 v69, -v41, v93, v69
	v_fma_f32 v70, -v42, v94, v70
	v_fma_f32 v71, -v44, v95, v71
	ds_read_b128 v[92:95], v78 offset:16048
	s_waitcnt lgkmcnt(6)
	v_fma_f32 v38, -v48, v96, v38
	v_fma_f32 v69, -v49, v97, v69
	v_fma_f32 v70, -v51, v98, v70
	v_fma_f32 v71, -v53, v99, v71
	ds_read_b128 v[96:99], v78 offset:16064
	s_waitcnt lgkmcnt(6)
	v_fma_f32 v38, -v54, v100, v38
	v_fma_f32 v69, -v56, v101, v69
	v_fma_f32 v70, -v58, v102, v70
	v_fma_f32 v71, -v61, v103, v71
	ds_read_b128 v[100:103], v78 offset:16080
	s_waitcnt lgkmcnt(6)
	v_fma_f32 v38, -v63, v104, v38
	v_fma_f32 v69, -v65, v105, v69
	v_fma_f32 v70, -v64, v106, v70
	v_fma_f32 v71, -v62, v107, v71
	ds_read_b128 v[104:107], v78 offset:16096
	s_waitcnt lgkmcnt(6)
	v_fma_f32 v38, -v60, v108, v38
	v_fma_f32 v69, -v59, v109, v69
	v_fma_f32 v70, -v57, v110, v70
	v_fma_f32 v71, -v55, v111, v71
	ds_read_b128 v[108:111], v78 offset:16112
	s_waitcnt lgkmcnt(6)
	v_fma_f32 v38, -v52, v84, v38
	v_fma_f32 v69, -v50, v85, v69
	v_fma_f32 v70, -v47, v86, v70
	v_fma_f32 v71, -v45, v87, v71
	ds_read_b128 v[84:87], v78 offset:16128
	s_waitcnt lgkmcnt(6)
	v_fma_f32 v38, -v43, v88, v38
	v_mov_b32_e32 v75, v89
	ds_read_b128 v[88:91], v78 offset:16144
	s_waitcnt lgkmcnt(6)
	v_fma_f32 v35, -v2, v92, v35
	v_fma_f32 v72, -v3, v93, 0
	v_fma_f32 v73, -v5, v94, 0
	v_fma_f32 v69, -v40, v75, v69
	v_fma_f32 v74, -v6, v95, 0
	ds_read_b128 v[92:95], v78 offset:16160
	s_waitcnt lgkmcnt(6)
	v_fma_f32 v35, -v7, v96, v35
	v_fma_f32 v72, -v8, v97, v72
	v_add_f32_e32 v69, v38, v69
	v_fma_f32 v73, -v9, v98, v73
	v_fma_f32 v74, -v10, v99, v74
	ds_read_b128 v[96:99], v78 offset:16176
	s_waitcnt lgkmcnt(6)
	v_fma_f32 v35, -v11, v100, v35
	v_add_f32_e32 v70, v70, v71
	v_fma_f32 v72, -v12, v101, v72
	v_fma_f32 v73, -v13, v102, v73
	v_fma_f32 v74, -v14, v103, v74
	v_add_f32_e32 v38, v69, v70
	ds_read_b128 v[100:103], v78 offset:16192
	s_waitcnt lgkmcnt(6)
	v_fma_f32 v35, -v15, v104, v35
	v_fma_f32 v72, -v16, v105, v72
	v_fma_f32 v73, -v66, v106, v73
	v_fma_f32 v74, -v17, v107, v74
	ds_read_b128 v[104:107], v78 offset:16208
	s_waitcnt lgkmcnt(6)
	v_fma_f32 v35, -v18, v108, v35
	v_fma_f32 v72, -v19, v109, v72
	v_fma_f32 v73, -v20, v110, v73
	v_fma_f32 v74, -v21, v111, v74
	ds_read_b128 v[108:111], v78 offset:16224
	s_waitcnt lgkmcnt(6)
	v_fma_f32 v35, -v22, v84, v35
	v_fma_f32 v72, -v23, v85, v72
	v_fma_f32 v73, -v24, v86, v73
	v_fma_f32 v74, -v25, v87, v74
	ds_read_b128 v[84:87], v78 offset:16240
	s_waitcnt lgkmcnt(6)
	v_fma_f32 v35, -v26, v88, v35
	v_fma_f32 v72, -v27, v89, v72
	v_fma_f32 v73, -v29, v90, v73
	v_fma_f32 v74, -v30, v91, v74
	ds_read_b128 v[88:91], v78 offset:16256
	s_waitcnt lgkmcnt(6)
	v_fma_f32 v35, -v33, v92, v35
	v_fma_f32 v72, -v34, v93, v72
	v_fma_f32 v73, -v36, v94, v73
	v_fma_f32 v74, -v37, v95, v74
	ds_read_b128 v[92:95], v78 offset:16272
	s_waitcnt lgkmcnt(6)
; DI void gdn_prep(const Params& p, int item, unsigned char* smem) {
;     ...
;         for (int i = 1; i < 64; ++i) {
;             float a = X[i];
;             int dep; asm volatile("v_and_b32 %0, 0, %1" : "=v"(dep) : "v"(X[i - 1]));
;             const float* Lr = sL + i * 68 + dep;
;             float b0 = 0.f, b1 = 0.f, b2 = 0.f;
; #pragma unroll
;             for (int j4 = 0; j4 < (i + 3) / 4; ++j4) {
;                 const f32x4 l = *(const f32x4*)(Lr + 4 * j4);
;                 if (4 * j4 + 0 < i) a -= l.x * X[4 * j4 + 0];
;                 if (4 * j4 + 1 < i) b0 -= l.y * X[4 * j4 + 1];
;                 if (4 * j4 + 2 < i) b1 -= l.z * X[4 * j4 + 2];
;                 if (4 * j4 + 3 < i) b2 -= l.w * X[4 * j4 + 3];
;             }
;             X[i] = (a + b0) + (b1 + b2);
	v_fma_f32 v35, -v39, v96, v35
	v_fma_f32 v72, -v41, v97, v72
	v_fma_f32 v73, -v42, v98, v73
	v_fma_f32 v74, -v44, v99, v74
	ds_read_b128 v[96:99], v78 offset:16320
	s_waitcnt lgkmcnt(6)
	v_fma_f32 v35, -v48, v100, v35
	v_fma_f32 v72, -v49, v101, v72
	v_fma_f32 v73, -v51, v102, v73
	v_fma_f32 v74, -v53, v103, v74
	ds_read_b128 v[100:103], v78 offset:16336
	s_waitcnt lgkmcnt(6)
	v_fma_f32 v35, -v54, v104, v35
	v_fma_f32 v72, -v56, v105, v72
	v_fma_f32 v73, -v58, v106, v73
	v_fma_f32 v74, -v61, v107, v74
	ds_read_b128 v[104:107], v78 offset:16352
	s_waitcnt lgkmcnt(6)
	v_fma_f32 v35, -v63, v108, v35
	v_fma_f32 v72, -v65, v109, v72
	v_fma_f32 v73, -v64, v110, v73
	v_fma_f32 v74, -v62, v111, v74
	ds_read_b128 v[108:111], v78 offset:16368
	s_waitcnt lgkmcnt(6)
	v_fma_f32 v35, -v60, v84, v35
	v_fma_f32 v72, -v59, v85, v72
	v_fma_f32 v73, -v57, v86, v73
	v_fma_f32 v74, -v55, v87, v74
	ds_read_b128 v[84:87], v78 offset:16384
	s_waitcnt lgkmcnt(6)
	v_fma_f32 v35, -v52, v88, v35
	v_fma_f32 v72, -v50, v89, v72
	v_fma_f32 v73, -v47, v90, v73
	v_fma_f32 v74, -v45, v91, v74
	ds_read_b128 v[88:91], v78 offset:16400
	s_waitcnt lgkmcnt(6)
	v_fma_f32 v35, -v43, v92, v35
	v_fma_f32 v72, -v40, v93, v72
	v_mov_b32_e32 v76, v94
	ds_read_b128 v[92:95], v78 offset:16416
	s_waitcnt lgkmcnt(6)
	v_fma_f32 v31, -v2, v96, v31
	v_fma_f32 v69, -v3, v97, 0
	v_fma_f32 v70, -v5, v98, 0
	v_fma_f32 v73, -v38, v76, v73
	v_fma_f32 v71, -v6, v99, 0
	ds_read_b128 v[96:99], v78 offset:16432
	s_waitcnt lgkmcnt(6)
	v_fma_f32 v31, -v7, v100, v31
	v_fma_f32 v69, -v8, v101, v69
	v_add_f32_e32 v72, v35, v72
	v_fma_f32 v70, -v9, v102, v70
	v_fma_f32 v71, -v10, v103, v71
	ds_read_b128 v[100:103], v78 offset:16448
	s_waitcnt lgkmcnt(6)
	v_fma_f32 v31, -v11, v104, v31
	v_add_f32_e32 v73, v73, v74
	v_fma_f32 v69, -v12, v105, v69
	v_fma_f32 v70, -v13, v106, v70
	v_fma_f32 v71, -v14, v107, v71
	v_add_f32_e32 v35, v72, v73
	ds_read_b128 v[104:107], v78 offset:16464
	s_waitcnt lgkmcnt(6)
	v_fma_f32 v31, -v15, v108, v31
	v_fma_f32 v69, -v16, v109, v69
	v_fma_f32 v70, -v66, v110, v70
	v_fma_f32 v71, -v17, v111, v71
	ds_read_b128 v[108:111], v78 offset:16480
	s_waitcnt lgkmcnt(6)
	v_fma_f32 v31, -v18, v84, v31
	v_fma_f32 v69, -v19, v85, v69
	v_fma_f32 v70, -v20, v86, v70
	v_fma_f32 v71, -v21, v87, v71
	ds_read_b128 v[84:87], v78 offset:16496
	s_waitcnt lgkmcnt(6)
	v_fma_f32 v31, -v22, v88, v31
	v_fma_f32 v69, -v23, v89, v69
	v_fma_f32 v70, -v24, v90, v70
	v_fma_f32 v71, -v25, v91, v71
	ds_read_b128 v[88:91], v78 offset:16512
	s_waitcnt lgkmcnt(6)
	v_fma_f32 v31, -v26, v92, v31
	v_fma_f32 v69, -v27, v93, v69
	v_fma_f32 v70, -v29, v94, v70
	v_fma_f32 v71, -v30, v95, v71
	ds_read_b128 v[92:95], v78 offset:16528
	s_waitcnt lgkmcnt(6)
	v_fma_f32 v31, -v33, v96, v31
	v_fma_f32 v69, -v34, v97, v69
	v_fma_f32 v70, -v36, v98, v70
	v_fma_f32 v71, -v37, v99, v71
	ds_read_b128 v[96:99], v78 offset:16544
	s_waitcnt lgkmcnt(6)
	v_fma_f32 v31, -v39, v100, v31
	v_fma_f32 v69, -v41, v101, v69
	v_fma_f32 v70, -v42, v102, v70
	v_fma_f32 v71, -v44, v103, v71
	ds_read_b128 v[100:103], v78 offset:16592
	s_waitcnt lgkmcnt(6)
	v_fma_f32 v31, -v48, v104, v31
	v_fma_f32 v69, -v49, v105, v69
	v_fma_f32 v70, -v51, v106, v70
	v_fma_f32 v71, -v53, v107, v71
	ds_read_b128 v[104:107], v78 offset:16608
	s_waitcnt lgkmcnt(6)
	v_fma_f32 v31, -v54, v108, v31
	v_fma_f32 v69, -v56, v109, v69
	v_fma_f32 v70, -v58, v110, v70
	v_fma_f32 v71, -v61, v111, v71
	ds_read_b128 v[108:111], v78 offset:16624
	s_waitcnt lgkmcnt(6)
	v_fma_f32 v31, -v63, v84, v31
	v_fma_f32 v69, -v65, v85, v69
	v_fma_f32 v70, -v64, v86, v70
	v_fma_f32 v71, -v62, v87, v71
	ds_read_b128 v[84:87], v78 offset:16640
	s_waitcnt lgkmcnt(6)
	v_fma_f32 v31, -v60, v88, v31
	v_fma_f32 v69, -v59, v89, v69
	v_fma_f32 v70, -v57, v90, v70
	v_fma_f32 v71, -v55, v91, v71
	ds_read_b128 v[88:91], v78 offset:16656
	s_waitcnt lgkmcnt(6)
	v_fma_f32 v31, -v52, v92, v31
	v_fma_f32 v69, -v50, v93, v69
	v_fma_f32 v70, -v47, v94, v70
	v_fma_f32 v71, -v45, v95, v71
	ds_read_b128 v[92:95], v78 offset:16672
	s_waitcnt lgkmcnt(6)
	v_fma_f32 v31, -v43, v96, v31
	v_fma_f32 v69, -v40, v97, v69
	v_fma_f32 v70, -v38, v98, v70
	v_mov_b32_e32 v75, v99
	ds_read_b128 v[96:99], v78 offset:16688
	s_waitcnt lgkmcnt(6)
	v_fma_f32 v28, -v2, v100, v28
	v_fma_f32 v72, -v3, v101, 0
	v_fma_f32 v73, -v5, v102, 0
	v_fma_f32 v71, -v35, v75, v71
	v_fma_f32 v74, -v6, v103, 0
	ds_read_b128 v[100:103], v78 offset:16704
	s_waitcnt lgkmcnt(6)
	v_fma_f32 v28, -v7, v104, v28
	v_fma_f32 v72, -v8, v105, v72
	v_add_f32_e32 v69, v31, v69
	v_fma_f32 v73, -v9, v106, v73
	v_fma_f32 v74, -v10, v107, v74
	ds_read_b128 v[104:107], v78 offset:16720
	s_waitcnt lgkmcnt(6)
	v_fma_f32 v28, -v11, v108, v28
	v_add_f32_e32 v70, v70, v71
	v_fma_f32 v72, -v12, v109, v72
	v_fma_f32 v73, -v13, v110, v73
	v_fma_f32 v74, -v14, v111, v74
	v_add_f32_e32 v31, v69, v70
	ds_read_b128 v[108:111], v78 offset:16736
	s_waitcnt lgkmcnt(6)
	v_fma_f32 v28, -v15, v84, v28
	v_fma_f32 v72, -v16, v85, v72
	v_fma_f32 v73, -v66, v86, v73
	v_fma_f32 v74, -v17, v87, v74
	ds_read_b128 v[84:87], v78 offset:16752
	s_waitcnt lgkmcnt(6)
	v_fma_f32 v28, -v18, v88, v28
	v_fma_f32 v72, -v19, v89, v72
	v_fma_f32 v73, -v20, v90, v73
	v_fma_f32 v74, -v21, v91, v74
	ds_read_b128 v[88:91], v78 offset:16768
	s_waitcnt lgkmcnt(6)
	v_fma_f32 v28, -v22, v92, v28
	v_fma_f32 v72, -v23, v93, v72
	v_fma_f32 v73, -v24, v94, v73
	v_fma_f32 v74, -v25, v95, v74
	ds_read_b128 v[92:95], v78 offset:16784
	s_waitcnt lgkmcnt(6)
	v_fma_f32 v28, -v26, v96, v28
	v_fma_f32 v72, -v27, v97, v72
	v_fma_f32 v73, -v29, v98, v73
	v_fma_f32 v74, -v30, v99, v74
	ds_read_b128 v[96:99], v78 offset:16800
	s_waitcnt lgkmcnt(6)
; DI void gdn_prep(const Params& p, int item, unsigned char* smem) {
;     ...
;         for (int i = 1; i < 64; ++i) {
;             float a = X[i];
;             int dep; asm volatile("v_and_b32 %0, 0, %1" : "=v"(dep) : "v"(X[i - 1]));
;             const float* Lr = sL + i * 68 + dep;
;             float b0 = 0.f, b1 = 0.f, b2 = 0.f;
; #pragma unroll
;             for (int j4 = 0; j4 < (i + 3) / 4; ++j4) {
;                 const f32x4 l = *(const f32x4*)(Lr + 4 * j4);
;                 if (4 * j4 + 0 < i) a -= l.x * X[4 * j4 + 0];
;                 if (4 * j4 + 1 < i) b0 -= l.y * X[4 * j4 + 1];
;                 if (4 * j4 + 2 < i) b1 -= l.z * X[4 * j4 + 2];
;                 if (4 * j4 + 3 < i) b2 -= l.w * X[4 * j4 + 3];
;             }
;             X[i] = (a + b0) + (b1 + b2);
	v_fma_f32 v28, -v33, v100, v28
	v_fma_f32 v72, -v34, v101, v72
	v_fma_f32 v73, -v36, v102, v73
	v_fma_f32 v74, -v37, v103, v74
	ds_read_b128 v[100:103], v78 offset:16816
	s_waitcnt lgkmcnt(6)
	v_fma_f32 v28, -v39, v104, v28
	v_fma_f32 v72, -v41, v105, v72
	v_fma_f32 v73, -v42, v106, v73
	v_fma_f32 v74, -v44, v107, v74
	ds_read_b128 v[104:107], v78 offset:16832
	s_waitcnt lgkmcnt(6)
	v_fma_f32 v28, -v48, v108, v28
	v_fma_f32 v72, -v49, v109, v72
	v_fma_f32 v73, -v51, v110, v73
	v_fma_f32 v74, -v53, v111, v74
	ds_read_b128 v[108:111], v78 offset:16864
	s_waitcnt lgkmcnt(6)
	v_fma_f32 v28, -v54, v84, v28
	v_fma_f32 v72, -v56, v85, v72
	v_fma_f32 v73, -v58, v86, v73
	v_fma_f32 v74, -v61, v87, v74
	ds_read_b128 v[84:87], v78 offset:16880
	s_waitcnt lgkmcnt(6)
	v_fma_f32 v28, -v63, v88, v28
	v_fma_f32 v72, -v65, v89, v72
	v_fma_f32 v73, -v64, v90, v73
	v_fma_f32 v74, -v62, v91, v74
	ds_read_b128 v[88:91], v78 offset:16896
	s_waitcnt lgkmcnt(6)
	v_fma_f32 v28, -v60, v92, v28
	v_fma_f32 v72, -v59, v93, v72
	v_fma_f32 v73, -v57, v94, v73
	v_fma_f32 v74, -v55, v95, v74
	ds_read_b128 v[92:95], v78 offset:16912
	s_waitcnt lgkmcnt(6)
	v_fma_f32 v28, -v52, v96, v28
	v_fma_f32 v72, -v50, v97, v72
	v_fma_f32 v73, -v47, v98, v73
	v_fma_f32 v74, -v45, v99, v74
	ds_read_b128 v[96:99], v78 offset:16928
	s_waitcnt lgkmcnt(6)
	v_fma_f32 v28, -v43, v100, v28
	v_fma_f32 v72, -v40, v101, v72
	v_fma_f32 v73, -v38, v102, v73
	v_fma_f32 v74, -v35, v103, v74
	ds_read_b128 v[100:103], v78 offset:16944
	s_waitcnt lgkmcnt(6)
	v_mov_b32_e32 v76, v104
	ds_read_b128 v[104:107], v78 offset:16960
	s_waitcnt lgkmcnt(6)
	v_fma_f32 v1, -v2, v108, v1
	v_fma_f32 v69, -v3, v109, 0
	v_fma_f32 v70, -v5, v110, 0
	v_fma_f32 v28, -v31, v76, v28
	v_fma_f32 v71, -v6, v111, 0
	ds_read_b128 v[108:111], v78 offset:16976
	s_waitcnt lgkmcnt(6)
	v_fma_f32 v1, -v7, v84, v1
	v_fma_f32 v69, -v8, v85, v69
	v_add_f32_e32 v72, v28, v72
	v_fma_f32 v70, -v9, v86, v70
	v_fma_f32 v71, -v10, v87, v71
	ds_read_b128 v[84:87], v78 offset:16992
	s_waitcnt lgkmcnt(6)
	v_fma_f32 v1, -v11, v88, v1
	v_add_f32_e32 v73, v73, v74
	v_fma_f32 v69, -v12, v89, v69
	v_fma_f32 v70, -v13, v90, v70
	v_fma_f32 v71, -v14, v91, v71
	v_add_f32_e32 v28, v72, v73
	ds_read_b128 v[88:91], v78 offset:17008
	s_waitcnt lgkmcnt(6)
	v_fma_f32 v1, -v15, v92, v1
	v_fma_f32 v69, -v16, v93, v69
	v_fma_f32 v70, -v66, v94, v70
	v_fma_f32 v71, -v17, v95, v71
	ds_read_b128 v[92:95], v78 offset:17024
	s_waitcnt lgkmcnt(6)
	v_fma_f32 v1, -v18, v96, v1
	v_fma_f32 v69, -v19, v97, v69
	v_fma_f32 v70, -v20, v98, v70
	v_fma_f32 v71, -v21, v99, v71
	ds_read_b128 v[96:99], v78 offset:17040
	s_waitcnt lgkmcnt(6)
	v_fma_f32 v1, -v22, v100, v1
	v_fma_f32 v69, -v23, v101, v69
	v_fma_f32 v70, -v24, v102, v70
	v_fma_f32 v71, -v25, v103, v71
	ds_read_b128 v[100:103], v78 offset:17056
	s_waitcnt lgkmcnt(6)
	v_fma_f32 v1, -v26, v104, v1
	v_fma_f32 v69, -v27, v105, v69
	v_fma_f32 v70, -v29, v106, v70
	v_fma_f32 v71, -v30, v107, v71
	ds_read_b128 v[104:107], v78 offset:17072
	s_waitcnt lgkmcnt(6)
	v_fma_f32 v1, -v33, v108, v1
	v_fma_f32 v69, -v34, v109, v69
	v_fma_f32 v70, -v36, v110, v70
	v_fma_f32 v71, -v37, v111, v71
	ds_read_b128 v[108:111], v78 offset:17088
	s_waitcnt lgkmcnt(6)
	v_fma_f32 v1, -v39, v84, v1
	v_fma_f32 v69, -v41, v85, v69
	v_fma_f32 v70, -v42, v86, v70
	v_fma_f32 v71, -v44, v87, v71
	ds_read_b128 v[84:87], v78 offset:17104
	s_waitcnt lgkmcnt(6)
	v_fma_f32 v1, -v48, v88, v1
	v_fma_f32 v69, -v49, v89, v69
	v_fma_f32 v70, -v51, v90, v70
	v_fma_f32 v71, -v53, v91, v71
	ds_read_b128 v[88:91], v78 offset:17136
	s_waitcnt lgkmcnt(6)
	v_fma_f32 v1, -v54, v92, v1
	v_fma_f32 v69, -v56, v93, v69
	v_fma_f32 v70, -v58, v94, v70
	v_fma_f32 v71, -v61, v95, v71
	ds_read_b128 v[92:95], v78 offset:17152
	s_waitcnt lgkmcnt(6)
	v_fma_f32 v1, -v63, v96, v1
	v_fma_f32 v69, -v65, v97, v69
	v_fma_f32 v70, -v64, v98, v70
	v_fma_f32 v71, -v62, v99, v71
	ds_read_b128 v[96:99], v78 offset:17168
	s_waitcnt lgkmcnt(6)
	v_fma_f32 v1, -v60, v100, v1
	v_fma_f32 v69, -v59, v101, v69
	v_fma_f32 v70, -v57, v102, v70
	v_fma_f32 v71, -v55, v103, v71
	ds_read_b128 v[100:103], v78 offset:17184
	s_waitcnt lgkmcnt(6)
	v_fma_f32 v1, -v52, v104, v1
	v_fma_f32 v69, -v50, v105, v69
	v_fma_f32 v70, -v47, v106, v70
	v_fma_f32 v71, -v45, v107, v71
	ds_read_b128 v[104:107], v78 offset:17200
	s_waitcnt lgkmcnt(6)
	v_fma_f32 v1, -v43, v108, v1
	v_fma_f32 v69, -v40, v109, v69
	v_fma_f32 v70, -v38, v110, v70
	v_fma_f32 v71, -v35, v111, v71
	ds_read_b128 v[108:111], v78 offset:17216
	s_waitcnt lgkmcnt(6)
	v_fma_f32 v1, -v31, v84, v1
	v_mov_b32_e32 v75, v85
	ds_read_b128 v[84:87], v78 offset:17232
	s_waitcnt lgkmcnt(6)
	v_fma_f32 v0, -v2, v88, v0
	v_fma_f32 v72, -v3, v89, 0
	v_fma_f32 v73, -v5, v90, 0
	v_fma_f32 v69, -v28, v75, v69
	v_fma_f32 v74, -v6, v91, 0
	ds_read_b128 v[88:91], v78 offset:17248
	s_waitcnt lgkmcnt(6)
	v_fma_f32 v0, -v7, v92, v0
	v_fma_f32 v72, -v8, v93, v72
	v_add_f32_e32 v69, v1, v69
	v_fma_f32 v73, -v9, v94, v73
	v_fma_f32 v74, -v10, v95, v74
	ds_read_b128 v[92:95], v78 offset:17264
	s_waitcnt lgkmcnt(6)
	v_fma_f32 v0, -v11, v96, v0
	v_add_f32_e32 v70, v70, v71
	v_fma_f32 v72, -v12, v97, v72
	v_fma_f32 v73, -v13, v98, v73
	v_fma_f32 v74, -v14, v99, v74
	v_add_f32_e32 v1, v69, v70
	ds_read_b128 v[96:99], v78 offset:17280
	s_waitcnt lgkmcnt(6)
	v_fma_f32 v0, -v15, v100, v0
	v_fma_f32 v72, -v16, v101, v72
	v_fma_f32 v73, -v66, v102, v73
	v_fma_f32 v74, -v17, v103, v74
	ds_read_b128 v[100:103], v78 offset:17296
	s_waitcnt lgkmcnt(6)
	v_fma_f32 v0, -v18, v104, v0
	v_fma_f32 v72, -v19, v105, v72
	v_fma_f32 v73, -v20, v106, v73
	v_fma_f32 v74, -v21, v107, v74
	ds_read_b128 v[104:107], v78 offset:17312
	s_waitcnt lgkmcnt(6)
; DI void gdn_prep(const Params& p, int item, unsigned char* smem) {
;     ...
;         for (int i = 1; i < 64; ++i) {
;             float a = X[i];
;             int dep; asm volatile("v_and_b32 %0, 0, %1" : "=v"(dep) : "v"(X[i - 1]));
;             const float* Lr = sL + i * 68 + dep;
;             float b0 = 0.f, b1 = 0.f, b2 = 0.f;
; #pragma unroll
;             for (int j4 = 0; j4 < (i + 3) / 4; ++j4) {
;                 const f32x4 l = *(const f32x4*)(Lr + 4 * j4);
;                 if (4 * j4 + 0 < i) a -= l.x * X[4 * j4 + 0];
;                 if (4 * j4 + 1 < i) b0 -= l.y * X[4 * j4 + 1];
;                 if (4 * j4 + 2 < i) b1 -= l.z * X[4 * j4 + 2];
;                 if (4 * j4 + 3 < i) b2 -= l.w * X[4 * j4 + 3];
;             }
;             X[i] = (a + b0) + (b1 + b2);
;         }
	v_fma_f32 v0, -v22, v108, v0
	v_fma_f32 v72, -v23, v109, v72
	v_fma_f32 v73, -v24, v110, v73
	v_fma_f32 v74, -v25, v111, v74
	ds_read_b128 v[108:111], v78 offset:17328
	s_waitcnt lgkmcnt(6)
	v_fma_f32 v0, -v26, v84, v0
	v_fma_f32 v72, -v27, v85, v72
	v_fma_f32 v73, -v29, v86, v73
	v_fma_f32 v74, -v30, v87, v74
	ds_read_b128 v[84:87], v78 offset:17344
	s_waitcnt lgkmcnt(6)
	v_fma_f32 v0, -v33, v88, v0
	v_fma_f32 v72, -v34, v89, v72
	v_fma_f32 v73, -v36, v90, v73
	v_fma_f32 v74, -v37, v91, v74
	ds_read_b128 v[88:91], v78 offset:17360
	s_waitcnt lgkmcnt(6)
	v_fma_f32 v0, -v39, v92, v0
	v_fma_f32 v72, -v41, v93, v72
	v_fma_f32 v73, -v42, v94, v73
	v_fma_f32 v74, -v44, v95, v74
	ds_read_b128 v[92:95], v78 offset:17376
	s_waitcnt lgkmcnt(6)
	v_fma_f32 v0, -v48, v96, v0
	v_fma_f32 v72, -v49, v97, v72
	v_fma_f32 v73, -v51, v98, v73
	v_fma_f32 v74, -v53, v99, v74
	s_waitcnt lgkmcnt(5)
	v_fma_f32 v0, -v54, v100, v0
	v_fma_f32 v72, -v56, v101, v72
	v_fma_f32 v73, -v58, v102, v73
	v_fma_f32 v74, -v61, v103, v74
	s_waitcnt lgkmcnt(4)
	v_fma_f32 v0, -v63, v104, v0
	v_fma_f32 v72, -v65, v105, v72
	v_fma_f32 v73, -v64, v106, v73
	v_fma_f32 v74, -v62, v107, v74
	s_waitcnt lgkmcnt(3)
	v_fma_f32 v0, -v60, v108, v0
	v_fma_f32 v72, -v59, v109, v72
	v_fma_f32 v73, -v57, v110, v73
	v_fma_f32 v74, -v55, v111, v74
	s_waitcnt lgkmcnt(2)
	v_fma_f32 v0, -v52, v84, v0
	v_fma_f32 v72, -v50, v85, v72
	v_fma_f32 v73, -v47, v86, v73
	v_fma_f32 v74, -v45, v87, v74
	s_waitcnt lgkmcnt(1)
	v_fma_f32 v0, -v43, v88, v0
	v_fma_f32 v72, -v40, v89, v72
	v_fma_f32 v73, -v38, v90, v73
	v_fma_f32 v74, -v35, v91, v74
	s_waitcnt lgkmcnt(0)
	v_fma_f32 v0, -v31, v92, v0
	v_fma_f32 v72, -v28, v93, v72
	v_mov_b32_e32 v76, v94
	v_fma_f32 v73, -v1, v76, v73
	v_add_f32_e32 v72, v0, v72
	v_add_f32_e32 v73, v73, v74
	v_add_f32_e32 v0, v72, v73
	v_mov_b32_e32 v4, v3
	v_mov_b32_e32 v3, v5
	v_mov_b32_e32 v5, v6
	v_mov_b32_e32 v6, v7
	v_mov_b32_e32 v7, v8
	v_mov_b32_e32 v8, v9
	v_mov_b32_e32 v9, v10
	v_mov_b32_e32 v10, v11
	v_mov_b32_e32 v11, v12
	v_mov_b32_e32 v12, v13
	v_mov_b32_e32 v13, v14
	v_mov_b32_e32 v14, v15
	v_mov_b32_e32 v15, v16
	v_mov_b32_e32 v16, v66
	v_mov_b32_e32 v66, v47
	v_mov_b32_e32 v67, v1
	v_mov_b32_e32 v68, v0
	s_and_saveexec_b64 s[4:5], vcc
	s_xor_b64 s[4:5], exec, s[4:5]
	s_cbranch_execz .LBB0_409
; DI bf16_t f2bf(float a) { return (bf16_t)(pk2(a, 0.f) & 0xffffu); }
; DI void gdn_prep(const Params& p, int item, unsigned char* smem) {
;     ...
;             bf16_t* wg = (bf16_t*)(p.ws + WS_W) + (size_t)item * 8192 + (tid - 128);
; #pragma unroll
;             for (int i = 0; i < 64; ++i) wg[i * 128] = f2bf(X[i]);
	s_add_u32 s74, s72, s30
	v_mov_b32_e32 v47, v117
	s_addc_u32 s75, s73, s31
	v_lshl_add_u64 v[0:1], v[46:47], 1, s[74:75]
	v_add_co_u32_e32 v70, vcc, 0x1ddc4000, v0
	v_cvt_pk_bf16_f32 v2, v2, s0
	s_nop 0
	v_addc_co_u32_e32 v71, vcc, 0, v1, vcc
	global_store_short v[70:71], v2, off offset:3840
	v_add_co_u32_e32 v70, vcc, 0x1ddc5000, v0
	v_cvt_pk_bf16_f32 v2, v4, s0
	s_nop 0
	v_addc_co_u32_e32 v71, vcc, 0, v1, vcc
	global_store_short v[70:71], v2, off
	v_cvt_pk_bf16_f32 v2, v3, s0
	global_store_short v[70:71], v2, off offset:256
	v_cvt_pk_bf16_f32 v2, v5, s0
	global_store_short v[70:71], v2, off offset:512
	v_cvt_pk_bf16_f32 v2, v6, s0
	global_store_short v[70:71], v2, off offset:768
	v_cvt_pk_bf16_f32 v2, v7, s0
	global_store_short v[70:71], v2, off offset:1024
	v_cvt_pk_bf16_f32 v2, v8, s0
	global_store_short v[70:71], v2, off offset:1280
	v_cvt_pk_bf16_f32 v2, v9, s0
	global_store_short v[70:71], v2, off offset:1536
	v_cvt_pk_bf16_f32 v2, v10, s0
	global_store_short v[70:71], v2, off offset:1792
	v_cvt_pk_bf16_f32 v2, v11, s0
	global_store_short v[70:71], v2, off offset:2048
	v_cvt_pk_bf16_f32 v2, v12, s0
	global_store_short v[70:71], v2, off offset:2304
	v_cvt_pk_bf16_f32 v2, v13, s0
	global_store_short v[70:71], v2, off offset:2560
	v_cvt_pk_bf16_f32 v2, v14, s0
	global_store_short v[70:71], v2, off offset:2816
	v_cvt_pk_bf16_f32 v2, v15, s0
	global_store_short v[70:71], v2, off offset:3072
	v_cvt_pk_bf16_f32 v2, v16, s0
	global_store_short v[70:71], v2, off offset:3328
	v_cvt_pk_bf16_f32 v2, v17, s0
	global_store_short v[70:71], v2, off offset:3584
	v_cvt_pk_bf16_f32 v2, v18, s0
	s_mov_b32 s15, 0x1ddc6000
	global_store_short v[70:71], v2, off offset:3840
	v_add_co_u32_e32 v2, vcc, s15, v0
	s_mov_b32 s15, 0x1ddc7000
	s_nop 0
	v_addc_co_u32_e32 v3, vcc, 0, v1, vcc
	v_add_co_u32_e32 v4, vcc, s15, v0
	v_cvt_pk_bf16_f32 v6, v19, s0
	s_nop 0
	v_addc_co_u32_e32 v5, vcc, 0, v1, vcc
	global_store_short v[4:5], v6, off offset:-4096
	v_cvt_pk_bf16_f32 v6, v20, s0
	global_store_short v[2:3], v6, off offset:256
	v_cvt_pk_bf16_f32 v6, v21, s0
	global_store_short v[2:3], v6, off offset:512
	v_cvt_pk_bf16_f32 v6, v22, s0
	global_store_short v[2:3], v6, off offset:768
	v_cvt_pk_bf16_f32 v6, v23, s0
	global_store_short v[2:3], v6, off offset:1024
	v_cvt_pk_bf16_f32 v6, v24, s0
	global_store_short v[2:3], v6, off offset:1280
	v_cvt_pk_bf16_f32 v6, v25, s0
	global_store_short v[2:3], v6, off offset:1536
	v_cvt_pk_bf16_f32 v6, v26, s0
	global_store_short v[2:3], v6, off offset:1792
	v_cvt_pk_bf16_f32 v6, v27, s0
	global_store_short v[2:3], v6, off offset:2048
	v_cvt_pk_bf16_f32 v6, v29, s0
	global_store_short v[2:3], v6, off offset:2304
	v_cvt_pk_bf16_f32 v6, v30, s0
	global_store_short v[2:3], v6, off offset:2560
	v_cvt_pk_bf16_f32 v6, v33, s0
	global_store_short v[2:3], v6, off offset:2816
	v_cvt_pk_bf16_f32 v6, v34, s0
	global_store_short v[2:3], v6, off offset:3072
	v_cvt_pk_bf16_f32 v6, v36, s0
	global_store_short v[2:3], v6, off offset:3328
	v_cvt_pk_bf16_f32 v6, v37, s0
	global_store_short v[2:3], v6, off offset:3584
	v_cvt_pk_bf16_f32 v6, v39, s0
	global_store_short v[2:3], v6, off offset:3840
	v_cvt_pk_bf16_f32 v2, v41, s0
	global_store_short v[4:5], v2, off
	v_cvt_pk_bf16_f32 v2, v42, s0
	global_store_short v[4:5], v2, off offset:256
	v_cvt_pk_bf16_f32 v2, v44, s0
	global_store_short v[4:5], v2, off offset:512
	v_cvt_pk_bf16_f32 v2, v48, s0
	global_store_short v[4:5], v2, off offset:768
	v_cvt_pk_bf16_f32 v2, v49, s0
	global_store_short v[4:5], v2, off offset:1024
	v_cvt_pk_bf16_f32 v2, v51, s0
	global_store_short v[4:5], v2, off offset:1280
	v_cvt_pk_bf16_f32 v2, v53, s0
	global_store_short v[4:5], v2, off offset:1536
	v_cvt_pk_bf16_f32 v2, v54, s0
	global_store_short v[4:5], v2, off offset:1792
	v_cvt_pk_bf16_f32 v2, v56, s0
	global_store_short v[4:5], v2, off offset:2048
	v_cvt_pk_bf16_f32 v2, v58, s0
	global_store_short v[4:5], v2, off offset:2304
	v_cvt_pk_bf16_f32 v2, v61, s0
	global_store_short v[4:5], v2, off offset:2560
	v_cvt_pk_bf16_f32 v2, v63, s0
	global_store_short v[4:5], v2, off offset:2816
	v_cvt_pk_bf16_f32 v2, v65, s0
	global_store_short v[4:5], v2, off offset:3072
	v_cvt_pk_bf16_f32 v2, v64, s0
	global_store_short v[4:5], v2, off offset:3328
	v_cvt_pk_bf16_f32 v2, v62, s0
	s_mov_b32 s15, 0x1ddc8000
	global_store_short v[4:5], v2, off offset:3584
	v_cvt_pk_bf16_f32 v2, v60, s0
	v_add_co_u32_e32 v0, vcc, s15, v0
	global_store_short v[4:5], v2, off offset:3840
	v_cvt_pk_bf16_f32 v2, v59, s0
	v_addc_co_u32_e32 v1, vcc, 0, v1, vcc
	global_store_short v[0:1], v2, off
	v_cvt_pk_bf16_f32 v2, v57, s0
	global_store_short v[0:1], v2, off offset:256
	v_cvt_pk_bf16_f32 v2, v55, s0
	global_store_short v[0:1], v2, off offset:512
	v_cvt_pk_bf16_f32 v2, v52, s0
	global_store_short v[0:1], v2, off offset:768
	v_cvt_pk_bf16_f32 v2, v50, s0
	global_store_short v[0:1], v2, off offset:1024
	v_cvt_pk_bf16_f32 v2, v66, s0
	global_store_short v[0:1], v2, off offset:1280
	v_cvt_pk_bf16_f32 v2, v45, s0
	global_store_short v[0:1], v2, off offset:1536
	v_cvt_pk_bf16_f32 v2, v43, s0
	global_store_short v[0:1], v2, off offset:1792
	v_cvt_pk_bf16_f32 v2, v40, s0
	global_store_short v[0:1], v2, off offset:2048
	v_cvt_pk_bf16_f32 v2, v38, s0
	global_store_short v[0:1], v2, off offset:2304
	v_cvt_pk_bf16_f32 v2, v35, s0
	global_store_short v[0:1], v2, off offset:2560
	v_cvt_pk_bf16_f32 v2, v31, s0
	global_store_short v[0:1], v2, off offset:2816
	v_cvt_pk_bf16_f32 v2, v28, s0
	global_store_short v[0:1], v2, off offset:3072
	v_cvt_pk_bf16_f32 v2, v67, s0
	global_store_short v[0:1], v2, off offset:3328
	v_cvt_pk_bf16_f32 v2, v68, s0
	global_store_short v[0:1], v2, off offset:3584

.LBB0_503:
	ds_read_b128 v[148:151], v139 offset:32768
	ds_read_b128 v[164:167], v140
	ds_read_b128 v[152:155], v139 offset:34816
	ds_read_b128 v[156:159], v139 offset:36864
	ds_read_b128 v[160:163], v139 offset:38912
	ds_read_b128 v[168:171], v140 offset:2048
	ds_read_b128 v[172:175], v140 offset:4096
	ds_read_b128 v[176:179], v140 offset:6144
	ds_read_b128 v[180:183], v140 offset:8192
	ds_read_b128 v[184:187], v140 offset:10240
	ds_read_b128 v[188:191], v140 offset:12288
	ds_read_b128 v[192:195], v140 offset:14336
	v_lshl_add_u64 v[196:197], v[134:135], 0, v[128:129]
	s_mov_b32 m0, s88
	s_waitcnt lgkmcnt(10)
	v_mfma_f32_16x16x32_bf16 v[124:127], v[148:151], v[164:167], v[124:127]
	s_add_i32 s50, s2, 1
	s_add_i32 s47, s2, 2
	s_cmp_lt_u32 s2, 30
	s_waitcnt lgkmcnt(9)
	v_mfma_f32_16x16x32_bf16 v[120:123], v[152:155], v[164:167], v[120:123]
	s_cselect_b64 s[48:49], -1, 0
	s_and_b64 vcc, s[48:49], exec
	s_cselect_b32 s2, s47, s50
	s_waitcnt lgkmcnt(8)
	v_mfma_f32_16x16x32_bf16 v[116:119], v[156:159], v[164:167], v[116:119]
	s_lshl_b32 s2, s2, 7
	v_lshl_add_u64 v[134:135], v[134:135], 0, s[26:27]
	s_waitcnt lgkmcnt(7)
	v_mfma_f32_16x16x32_bf16 v[112:115], v[160:163], v[164:167], v[112:115]
	v_lshl_add_u64 v[164:165], v[196:197], 0, s[10:11]
	global_load_lds_dwordx4 v[164:165], off
	v_lshl_add_u64 v[164:165], v[196:197], 0, s[12:13]
	s_mov_b32 m0, s92
	s_waitcnt lgkmcnt(6)
	v_mfma_f32_16x16x32_bf16 v[108:111], v[148:151], v[168:171], v[108:111]
	v_mfma_f32_16x16x32_bf16 v[104:107], v[152:155], v[168:171], v[104:107]
	v_mfma_f32_16x16x32_bf16 v[100:103], v[156:159], v[168:171], v[100:103]
	v_mfma_f32_16x16x32_bf16 v[96:99], v[160:163], v[168:171], v[96:99]
	global_load_lds_dwordx4 v[164:165], off
	v_lshl_add_u64 v[164:165], v[196:197], 0, s[14:15]
	s_mov_b32 m0, s93
	s_waitcnt lgkmcnt(5)
	v_mfma_f32_16x16x32_bf16 v[92:95], v[148:151], v[172:175], v[92:95]
	v_mfma_f32_16x16x32_bf16 v[88:91], v[152:155], v[172:175], v[88:91]
	v_mfma_f32_16x16x32_bf16 v[84:87], v[156:159], v[172:175], v[84:87]
	v_mfma_f32_16x16x32_bf16 v[80:83], v[160:163], v[172:175], v[80:83]
	global_load_lds_dwordx4 v[164:165], off
	v_lshl_add_u64 v[164:165], v[196:197], 0, s[16:17]
	s_mov_b32 m0, s94
	s_waitcnt lgkmcnt(4)
	v_mfma_f32_16x16x32_bf16 v[76:79], v[148:151], v[176:179], v[76:79]
	v_lshl_add_u64 v[196:197], v[136:137], 0, v[128:129]
	v_lshl_add_u64 v[198:199], v[196:197], 0, s[18:19]
	v_lshl_add_u64 v[136:137], v[136:137], 0, s[26:27]
	v_mfma_f32_16x16x32_bf16 v[72:75], v[152:155], v[176:179], v[72:75]
	v_mfma_f32_16x16x32_bf16 v[68:71], v[156:159], v[176:179], v[68:71]
	v_mfma_f32_16x16x32_bf16 v[64:67], v[160:163], v[176:179], v[64:67]
	global_load_lds_dwordx4 v[164:165], off
	s_mov_b32 m0, s89
	s_waitcnt lgkmcnt(3)
	v_mfma_f32_16x16x32_bf16 v[60:63], v[148:151], v[180:183], v[60:63]
	v_mfma_f32_16x16x32_bf16 v[56:59], v[152:155], v[180:183], v[56:59]
	v_mfma_f32_16x16x32_bf16 v[52:55], v[156:159], v[180:183], v[52:55]
	v_mfma_f32_16x16x32_bf16 v[48:51], v[160:163], v[180:183], v[48:51]
	s_waitcnt lgkmcnt(2)
	v_mfma_f32_16x16x32_bf16 v[44:47], v[148:151], v[184:187], v[44:47]
	v_mfma_f32_16x16x32_bf16 v[40:43], v[152:155], v[184:187], v[40:43]
	v_mfma_f32_16x16x32_bf16 v[36:39], v[156:159], v[184:187], v[36:39]
	v_mfma_f32_16x16x32_bf16 v[28:31], v[160:163], v[184:187], v[28:31]
	s_waitcnt lgkmcnt(1)
	v_mfma_f32_16x16x32_bf16 v[24:27], v[148:151], v[188:191], v[24:27]
	v_mfma_f32_16x16x32_bf16 v[20:23], v[152:155], v[188:191], v[20:23]
	v_mfma_f32_16x16x32_bf16 v[16:19], v[156:159], v[188:191], v[16:19]
	v_mfma_f32_16x16x32_bf16 v[12:15], v[160:163], v[188:191], v[12:15]
	s_waitcnt lgkmcnt(0)
	v_mfma_f32_16x16x32_bf16 v[8:11], v[148:151], v[192:195], v[8:11]
	v_mfma_f32_16x16x32_bf16 v[4:7], v[152:155], v[192:195], v[4:7]
	v_mfma_f32_16x16x32_bf16 v[0:3], v[156:159], v[192:195], v[0:3]
	v_mfma_f32_16x16x32_bf16 v[32:35], v[160:163], v[192:195], v[32:35]
	ds_read_b128 v[148:151], v141 offset:32768
	ds_read_b128 v[164:167], v142
	ds_read_b128 v[152:155], v141 offset:34816
	ds_read_b128 v[156:159], v141 offset:36864
	ds_read_b128 v[160:163], v141 offset:38912
	ds_read_b128 v[168:171], v142 offset:2048
	ds_read_b128 v[172:175], v142 offset:4096
	ds_read_b128 v[176:179], v142 offset:6144
	ds_read_b128 v[180:183], v142 offset:8192
	ds_read_b128 v[184:187], v142 offset:10240
	ds_read_b128 v[188:191], v142 offset:12288
	ds_read_b128 v[192:195], v142 offset:14336
	s_waitcnt lgkmcnt(10)
	v_mfma_f32_16x16x32_bf16 v[124:127], v[148:151], v[164:167], v[124:127]
	s_waitcnt lgkmcnt(9)
	v_mfma_f32_16x16x32_bf16 v[120:123], v[152:155], v[164:167], v[120:123]
	s_waitcnt lgkmcnt(8)
	v_mfma_f32_16x16x32_bf16 v[116:119], v[156:159], v[164:167], v[116:119]
	s_waitcnt lgkmcnt(7)
	v_mfma_f32_16x16x32_bf16 v[112:115], v[160:163], v[164:167], v[112:115]
	global_load_lds_dwordx4 v[198:199], off
	v_lshl_add_u64 v[164:165], v[196:197], 0, s[20:21]
	s_mov_b32 m0, s95
	s_waitcnt lgkmcnt(6)
	v_mfma_f32_16x16x32_bf16 v[108:111], v[148:151], v[168:171], v[108:111]
	v_mfma_f32_16x16x32_bf16 v[104:107], v[152:155], v[168:171], v[104:107]
	v_mfma_f32_16x16x32_bf16 v[100:103], v[156:159], v[168:171], v[100:103]
	v_mfma_f32_16x16x32_bf16 v[96:99], v[160:163], v[168:171], v[96:99]
	global_load_lds_dwordx4 v[164:165], off
	v_lshl_add_u64 v[164:165], v[196:197], 0, s[22:23]
	s_mov_b32 m0, s96
	s_waitcnt lgkmcnt(5)
	v_mfma_f32_16x16x32_bf16 v[92:95], v[148:151], v[172:175], v[92:95]
	v_mfma_f32_16x16x32_bf16 v[88:91], v[152:155], v[172:175], v[88:91]
	v_mfma_f32_16x16x32_bf16 v[84:87], v[156:159], v[172:175], v[84:87]
	v_mfma_f32_16x16x32_bf16 v[80:83], v[160:163], v[172:175], v[80:83]
	global_load_lds_dwordx4 v[164:165], off
	v_lshl_add_u64 v[164:165], v[196:197], 0, s[24:25]
	s_mov_b32 m0, s97
	s_waitcnt lgkmcnt(4)
	v_mfma_f32_16x16x32_bf16 v[76:79], v[148:151], v[176:179], v[76:79]
	v_lshl_add_u64 v[196:197], v[130:131], 0, s[2:3]
	v_mfma_f32_16x16x32_bf16 v[72:75], v[152:155], v[176:179], v[72:75]
	v_mfma_f32_16x16x32_bf16 v[68:71], v[156:159], v[176:179], v[68:71]
	v_mfma_f32_16x16x32_bf16 v[64:67], v[160:163], v[176:179], v[64:67]
	global_load_lds_dwordx4 v[164:165], off
	s_waitcnt vmcnt(0)
	s_waitcnt lgkmcnt(3)
	v_mfma_f32_16x16x32_bf16 v[60:63], v[148:151], v[180:183], v[60:63]
	s_barrier
	s_mov_b32 m0, s0
	v_mfma_f32_16x16x32_bf16 v[56:59], v[152:155], v[180:183], v[56:59]
	v_mfma_f32_16x16x32_bf16 v[52:55], v[156:159], v[180:183], v[52:55]
	v_mfma_f32_16x16x32_bf16 v[48:51], v[160:163], v[180:183], v[48:51]
	s_waitcnt lgkmcnt(2)
	v_mfma_f32_16x16x32_bf16 v[44:47], v[148:151], v[184:187], v[44:47]
	v_mfma_f32_16x16x32_bf16 v[40:43], v[152:155], v[184:187], v[40:43]
	v_mfma_f32_16x16x32_bf16 v[36:39], v[156:159], v[184:187], v[36:39]
	v_mfma_f32_16x16x32_bf16 v[28:31], v[160:163], v[184:187], v[28:31]
	s_waitcnt lgkmcnt(1)
	v_mfma_f32_16x16x32_bf16 v[24:27], v[148:151], v[188:191], v[24:27]
	v_mfma_f32_16x16x32_bf16 v[20:23], v[152:155], v[188:191], v[20:23]
	v_mfma_f32_16x16x32_bf16 v[16:19], v[156:159], v[188:191], v[16:19]
	v_mfma_f32_16x16x32_bf16 v[12:15], v[160:163], v[188:191], v[12:15]
	s_waitcnt lgkmcnt(0)
	v_mfma_f32_16x16x32_bf16 v[8:11], v[148:151], v[192:195], v[8:11]
	v_mfma_f32_16x16x32_bf16 v[4:7], v[152:155], v[192:195], v[4:7]
	v_mfma_f32_16x16x32_bf16 v[0:3], v[156:159], v[192:195], v[0:3]
	v_mfma_f32_16x16x32_bf16 v[32:35], v[160:163], v[192:195], v[32:35]
	ds_read_b128 v[148:151], v143
	ds_read_b128 v[164:167], v144
	ds_read_b128 v[152:155], v143 offset:2048
	ds_read_b128 v[156:159], v143 offset:4096
	ds_read_b128 v[160:163], v143 offset:6144
	ds_read_b128 v[168:171], v144 offset:2048
	ds_read_b128 v[172:175], v144 offset:4096
	ds_read_b128 v[176:179], v144 offset:6144
	ds_read_b128 v[180:183], v144 offset:8192
	ds_read_b128 v[184:187], v144 offset:10240
	ds_read_b128 v[188:191], v144 offset:12288
	ds_read_b128 v[192:195], v144 offset:14336
	s_waitcnt lgkmcnt(10)
	v_mfma_f32_16x16x32_bf16 v[124:127], v[148:151], v[164:167], v[124:127]
	s_waitcnt lgkmcnt(9)
	v_mfma_f32_16x16x32_bf16 v[120:123], v[152:155], v[164:167], v[120:123]
	s_waitcnt lgkmcnt(8)
	v_mfma_f32_16x16x32_bf16 v[116:119], v[156:159], v[164:167], v[116:119]
	s_waitcnt lgkmcnt(7)
	v_mfma_f32_16x16x32_bf16 v[112:115], v[160:163], v[164:167], v[112:115]
	global_load_lds_dwordx4 v[196:197], off
	v_lshl_add_u64 v[164:165], v[196:197], 0, s[4:5]
	s_mov_b32 m0, s55
	s_waitcnt lgkmcnt(6)
	v_mfma_f32_16x16x32_bf16 v[108:111], v[148:151], v[168:171], v[108:111]
	v_mfma_f32_16x16x32_bf16 v[104:107], v[152:155], v[168:171], v[104:107]
	v_mfma_f32_16x16x32_bf16 v[100:103], v[156:159], v[168:171], v[100:103]
	v_mfma_f32_16x16x32_bf16 v[96:99], v[160:163], v[168:171], v[96:99]
	global_load_lds_dwordx4 v[164:165], off
	v_lshl_add_u64 v[164:165], v[196:197], 0, s[6:7]
	s_mov_b32 m0, s87
	s_waitcnt lgkmcnt(5)
	v_mfma_f32_16x16x32_bf16 v[92:95], v[148:151], v[172:175], v[92:95]
	v_mfma_f32_16x16x32_bf16 v[88:91], v[152:155], v[172:175], v[88:91]
	v_mfma_f32_16x16x32_bf16 v[84:87], v[156:159], v[172:175], v[84:87]
	v_mfma_f32_16x16x32_bf16 v[80:83], v[160:163], v[172:175], v[80:83]
	global_load_lds_dwordx4 v[164:165], off
	v_lshl_add_u64 v[164:165], v[196:197], 0, s[8:9]
	s_mov_b32 m0, s69
	s_waitcnt lgkmcnt(4)
	v_mfma_f32_16x16x32_bf16 v[76:79], v[148:151], v[176:179], v[76:79]
	v_lshl_add_u64 v[196:197], v[132:133], 0, s[2:3]
	s_mov_b32 s2, s47
	v_mfma_f32_16x16x32_bf16 v[72:75], v[152:155], v[176:179], v[72:75]
	v_mfma_f32_16x16x32_bf16 v[68:71], v[156:159], v[176:179], v[68:71]
	v_mfma_f32_16x16x32_bf16 v[64:67], v[160:163], v[176:179], v[64:67]
	global_load_lds_dwordx4 v[164:165], off
	s_mov_b32 m0, s68
	s_waitcnt lgkmcnt(3)
	v_mfma_f32_16x16x32_bf16 v[60:63], v[148:151], v[180:183], v[60:63]
	v_mfma_f32_16x16x32_bf16 v[56:59], v[152:155], v[180:183], v[56:59]
	v_mfma_f32_16x16x32_bf16 v[52:55], v[156:159], v[180:183], v[52:55]
	v_mfma_f32_16x16x32_bf16 v[48:51], v[160:163], v[180:183], v[48:51]
	s_waitcnt lgkmcnt(2)
	v_mfma_f32_16x16x32_bf16 v[44:47], v[148:151], v[184:187], v[44:47]
	v_mfma_f32_16x16x32_bf16 v[40:43], v[152:155], v[184:187], v[40:43]
	v_mfma_f32_16x16x32_bf16 v[36:39], v[156:159], v[184:187], v[36:39]
	v_mfma_f32_16x16x32_bf16 v[28:31], v[160:163], v[184:187], v[28:31]
	s_waitcnt lgkmcnt(1)
	v_mfma_f32_16x16x32_bf16 v[24:27], v[148:151], v[188:191], v[24:27]
	v_mfma_f32_16x16x32_bf16 v[20:23], v[152:155], v[188:191], v[20:23]
	v_mfma_f32_16x16x32_bf16 v[16:19], v[156:159], v[188:191], v[16:19]
	v_mfma_f32_16x16x32_bf16 v[12:15], v[160:163], v[188:191], v[12:15]
	s_waitcnt lgkmcnt(0)
	v_mfma_f32_16x16x32_bf16 v[8:11], v[148:151], v[192:195], v[8:11]
	v_mfma_f32_16x16x32_bf16 v[4:7], v[152:155], v[192:195], v[4:7]
	v_mfma_f32_16x16x32_bf16 v[0:3], v[156:159], v[192:195], v[0:3]
	v_mfma_f32_16x16x32_bf16 v[32:35], v[160:163], v[192:195], v[32:35]
	ds_read_b128 v[148:151], v145
	ds_read_b128 v[164:167], v146
	ds_read_b128 v[152:155], v145 offset:2048
	ds_read_b128 v[156:159], v145 offset:4096
	ds_read_b128 v[160:163], v145 offset:6144
	ds_read_b128 v[168:171], v146 offset:2048
	ds_read_b128 v[172:175], v146 offset:4096
	ds_read_b128 v[176:179], v146 offset:6144
	ds_read_b128 v[180:183], v146 offset:8192
	ds_read_b128 v[184:187], v146 offset:10240
	ds_read_b128 v[188:191], v146 offset:12288
	ds_read_b128 v[192:195], v146 offset:14336
	s_waitcnt lgkmcnt(10)
	v_mfma_f32_16x16x32_bf16 v[124:127], v[148:151], v[164:167], v[124:127]
	s_waitcnt lgkmcnt(9)
	v_mfma_f32_16x16x32_bf16 v[120:123], v[152:155], v[164:167], v[120:123]
	s_waitcnt lgkmcnt(8)
	v_mfma_f32_16x16x32_bf16 v[116:119], v[156:159], v[164:167], v[116:119]
	s_waitcnt lgkmcnt(7)
	v_mfma_f32_16x16x32_bf16 v[112:115], v[160:163], v[164:167], v[112:115]
	global_load_lds_dwordx4 v[196:197], off
	v_lshl_add_u64 v[164:165], v[196:197], 0, s[4:5]
	s_mov_b32 m0, s39
	s_waitcnt lgkmcnt(6)
	v_mfma_f32_16x16x32_bf16 v[108:111], v[148:151], v[168:171], v[108:111]
	v_mfma_f32_16x16x32_bf16 v[104:107], v[152:155], v[168:171], v[104:107]
	v_mfma_f32_16x16x32_bf16 v[100:103], v[156:159], v[168:171], v[100:103]
	v_mfma_f32_16x16x32_bf16 v[96:99], v[160:163], v[168:171], v[96:99]
	global_load_lds_dwordx4 v[164:165], off
	v_lshl_add_u64 v[164:165], v[196:197], 0, s[6:7]
	s_mov_b32 m0, s38
	s_waitcnt lgkmcnt(5)
	v_mfma_f32_16x16x32_bf16 v[92:95], v[148:151], v[172:175], v[92:95]
	v_mfma_f32_16x16x32_bf16 v[88:91], v[152:155], v[172:175], v[88:91]
	v_mfma_f32_16x16x32_bf16 v[84:87], v[156:159], v[172:175], v[84:87]
	v_mfma_f32_16x16x32_bf16 v[80:83], v[160:163], v[172:175], v[80:83]
	global_load_lds_dwordx4 v[164:165], off
	v_lshl_add_u64 v[164:165], v[196:197], 0, s[8:9]
	s_mov_b32 m0, s1
	s_waitcnt lgkmcnt(4)
	v_mfma_f32_16x16x32_bf16 v[76:79], v[148:151], v[176:179], v[76:79]
	v_mfma_f32_16x16x32_bf16 v[72:75], v[152:155], v[176:179], v[72:75]
	v_mfma_f32_16x16x32_bf16 v[68:71], v[156:159], v[176:179], v[68:71]
	v_mfma_f32_16x16x32_bf16 v[64:67], v[160:163], v[176:179], v[64:67]
	global_load_lds_dwordx4 v[164:165], off
	s_waitcnt vmcnt(0)
	s_waitcnt lgkmcnt(3)
	v_mfma_f32_16x16x32_bf16 v[60:63], v[148:151], v[180:183], v[60:63]
	s_barrier
; DI void phase4(const Params& p, unsigned char* smem) {
;     ...
;         for (int i = 0; i < 8; ++i) {
;             const size_t m = (size_t)mt * 256 + wm * 128 + i * 16 + fr;
; #pragma unroll
;             for (int j = 0; j < 4; ++j) {
;                 const int c = nt * 256 + wn * 64 + j * 16 + fq * 4;
;                 const f32x4 xv = *(const f32x4*)(p.x + m * DM + c);
;                 *(f32x4*)(p.out + m * DM + c) = xv + acc[i][j];
;             }
	v_mfma_f32_16x16x32_bf16 v[56:59], v[152:155], v[180:183], v[56:59]
	v_mfma_f32_16x16x32_bf16 v[52:55], v[156:159], v[180:183], v[52:55]
	v_mfma_f32_16x16x32_bf16 v[48:51], v[160:163], v[180:183], v[48:51]
	s_waitcnt lgkmcnt(2)
	v_mfma_f32_16x16x32_bf16 v[44:47], v[148:151], v[184:187], v[44:47]
	v_mfma_f32_16x16x32_bf16 v[40:43], v[152:155], v[184:187], v[40:43]
	v_mfma_f32_16x16x32_bf16 v[36:39], v[156:159], v[184:187], v[36:39]
	v_mfma_f32_16x16x32_bf16 v[28:31], v[160:163], v[184:187], v[28:31]
	s_waitcnt lgkmcnt(1)
	v_mfma_f32_16x16x32_bf16 v[24:27], v[148:151], v[188:191], v[24:27]
	v_mfma_f32_16x16x32_bf16 v[20:23], v[152:155], v[188:191], v[20:23]
	v_mfma_f32_16x16x32_bf16 v[16:19], v[156:159], v[188:191], v[16:19]
	v_mfma_f32_16x16x32_bf16 v[12:15], v[160:163], v[188:191], v[12:15]
	s_waitcnt lgkmcnt(0)
	v_mfma_f32_16x16x32_bf16 v[8:11], v[148:151], v[192:195], v[8:11]
	v_mfma_f32_16x16x32_bf16 v[4:7], v[152:155], v[192:195], v[4:7]
	v_mfma_f32_16x16x32_bf16 v[0:3], v[156:159], v[192:195], v[0:3]
	v_mfma_f32_16x16x32_bf16 v[32:35], v[160:163], v[192:195], v[32:35]
	s_cbranch_vccnz .LBB0_503
	v_lshrrev_b32_e32 v130, 2, v138
	s_lshl_b32 s2, s46, 8
	v_and_b32_e32 v130, 12, v130
	s_add_i32 s2, s2, s54
	v_lshl_or_b32 v130, s45, 8, v130
	v_and_or_b32 v128, v138, 15, s2
	v_or_b32_e32 v132, s82, v130
	v_lshlrev_b64 v[130:131], 13, v[128:129]
	v_ashrrev_i32_e32 v133, 31, v132
	v_lshl_add_u64 v[134:135], s[40:41], 0, v[130:131]
	v_lshlrev_b64 v[132:133], 2, v[132:133]
	v_lshl_add_u64 v[138:139], v[134:135], 0, v[132:133]
	global_load_dwordx4 v[134:137], v[138:139], off
	v_lshl_add_u64 v[140:141], s[70:71], 0, v[130:131]
	v_lshl_add_u64 v[140:141], v[140:141], 0, v[132:133]
	s_lshr_b32 s2, s33, 3
	s_add_i32 s44, s44, s84
	s_add_i32 s37, s37, s2
	s_cmp_gt_i32 s44, 31
	s_waitcnt vmcnt(0)
	v_pk_add_f32 v[126:127], v[126:127], v[136:137]
	v_pk_add_f32 v[124:125], v[124:125], v[134:135]
	global_store_dwordx4 v[140:141], v[124:127], off
	global_load_dwordx4 v[124:127], v[138:139], off offset:64
	s_waitcnt vmcnt(0)
	v_pk_add_f32 v[122:123], v[122:123], v[126:127]
	v_pk_add_f32 v[120:121], v[120:121], v[124:125]
	global_store_dwordx4 v[140:141], v[120:123], off offset:64
	global_load_dwordx4 v[120:123], v[138:139], off offset:128
	s_waitcnt vmcnt(0)
	v_pk_add_f32 v[118:119], v[118:119], v[122:123]
	v_pk_add_f32 v[116:117], v[116:117], v[120:121]
	global_store_dwordx4 v[140:141], v[116:119], off offset:128
	global_load_dwordx4 v[116:119], v[138:139], off offset:192
	v_or_b32_e32 v120, 0x20000, v130
	v_mov_b32_e32 v121, v131
	v_lshl_add_u64 v[122:123], s[40:41], 0, v[120:121]
	v_lshl_add_u64 v[122:123], v[122:123], 0, v[132:133]
	s_waitcnt vmcnt(0)
	v_pk_add_f32 v[114:115], v[114:115], v[118:119]
	v_pk_add_f32 v[112:113], v[112:113], v[116:117]
	global_store_dwordx4 v[140:141], v[112:115], off offset:192
	global_load_dwordx4 v[112:115], v[122:123], off
	v_lshl_add_u64 v[116:117], s[70:71], 0, v[120:121]
	v_lshl_add_u64 v[116:117], v[116:117], 0, v[132:133]
	s_waitcnt vmcnt(0)
	v_pk_add_f32 v[110:111], v[110:111], v[114:115]
	v_pk_add_f32 v[108:109], v[108:109], v[112:113]
	global_store_dwordx4 v[116:117], v[108:111], off
	global_load_dwordx4 v[108:111], v[122:123], off offset:64
	s_waitcnt vmcnt(0)
	v_pk_add_f32 v[106:107], v[106:107], v[110:111]
	v_pk_add_f32 v[104:105], v[104:105], v[108:109]
	global_store_dwordx4 v[116:117], v[104:107], off offset:64
	global_load_dwordx4 v[104:107], v[122:123], off offset:128
	s_waitcnt vmcnt(0)
	v_pk_add_f32 v[102:103], v[102:103], v[106:107]
	v_pk_add_f32 v[100:101], v[100:101], v[104:105]
	global_store_dwordx4 v[116:117], v[100:103], off offset:128
	global_load_dwordx4 v[100:103], v[122:123], off offset:192
	v_or_b32_e32 v104, 0x40000, v130
	v_mov_b32_e32 v105, v131
	v_lshl_add_u64 v[106:107], s[40:41], 0, v[104:105]
	v_lshl_add_u64 v[106:107], v[106:107], 0, v[132:133]
	s_waitcnt vmcnt(0)
	v_pk_add_f32 v[98:99], v[98:99], v[102:103]
	v_pk_add_f32 v[96:97], v[96:97], v[100:101]
	global_store_dwordx4 v[116:117], v[96:99], off offset:192
	global_load_dwordx4 v[96:99], v[106:107], off
	v_lshl_add_u64 v[100:101], s[70:71], 0, v[104:105]
	v_lshl_add_u64 v[100:101], v[100:101], 0, v[132:133]
	s_waitcnt vmcnt(0)
	v_pk_add_f32 v[94:95], v[94:95], v[98:99]
	v_pk_add_f32 v[92:93], v[92:93], v[96:97]
	global_store_dwordx4 v[100:101], v[92:95], off
	global_load_dwordx4 v[92:95], v[106:107], off offset:64
	s_waitcnt vmcnt(0)
	v_pk_add_f32 v[90:91], v[90:91], v[94:95]
	v_pk_add_f32 v[88:89], v[88:89], v[92:93]
	global_store_dwordx4 v[100:101], v[88:91], off offset:64
	global_load_dwordx4 v[88:91], v[106:107], off offset:128
	s_waitcnt vmcnt(0)
	v_pk_add_f32 v[86:87], v[86:87], v[90:91]
	v_pk_add_f32 v[84:85], v[84:85], v[88:89]
	global_store_dwordx4 v[100:101], v[84:87], off offset:128
	global_load_dwordx4 v[84:87], v[106:107], off offset:192
	v_or_b32_e32 v88, 0x60000, v130
	v_mov_b32_e32 v89, v131
	v_lshl_add_u64 v[90:91], s[40:41], 0, v[88:89]
	v_lshl_add_u64 v[90:91], v[90:91], 0, v[132:133]
	s_waitcnt vmcnt(0)
	v_pk_add_f32 v[82:83], v[82:83], v[86:87]
	v_pk_add_f32 v[80:81], v[80:81], v[84:85]
	global_store_dwordx4 v[100:101], v[80:83], off offset:192
	global_load_dwordx4 v[80:83], v[90:91], off
	v_lshl_add_u64 v[84:85], s[70:71], 0, v[88:89]
	v_lshl_add_u64 v[84:85], v[84:85], 0, v[132:133]
	s_waitcnt vmcnt(0)
; DI void phase4(const Params& p, unsigned char* smem) {
;     ...
;         for (int i = 0; i < 8; ++i) {
;             const size_t m = (size_t)mt * 256 + wm * 128 + i * 16 + fr;
; #pragma unroll
;             for (int j = 0; j < 4; ++j) {
;                 const int c = nt * 256 + wn * 64 + j * 16 + fq * 4;
;                 const f32x4 xv = *(const f32x4*)(p.x + m * DM + c);
;                 *(f32x4*)(p.out + m * DM + c) = xv + acc[i][j];
;             }
	v_pk_add_f32 v[78:79], v[78:79], v[82:83]
	v_pk_add_f32 v[76:77], v[76:77], v[80:81]
	global_store_dwordx4 v[84:85], v[76:79], off
	global_load_dwordx4 v[76:79], v[90:91], off offset:64
	s_waitcnt vmcnt(0)
	v_pk_add_f32 v[74:75], v[74:75], v[78:79]
	v_pk_add_f32 v[72:73], v[72:73], v[76:77]
	global_store_dwordx4 v[84:85], v[72:75], off offset:64
	global_load_dwordx4 v[72:75], v[90:91], off offset:128
	s_waitcnt vmcnt(0)
	v_pk_add_f32 v[70:71], v[70:71], v[74:75]
	v_pk_add_f32 v[68:69], v[68:69], v[72:73]
	global_store_dwordx4 v[84:85], v[68:71], off offset:128
	global_load_dwordx4 v[68:71], v[90:91], off offset:192
	v_or_b32_e32 v72, 0x80000, v130
	v_mov_b32_e32 v73, v131
	v_lshl_add_u64 v[74:75], s[40:41], 0, v[72:73]
	v_lshl_add_u64 v[74:75], v[74:75], 0, v[132:133]
	s_waitcnt vmcnt(0)
	v_pk_add_f32 v[66:67], v[66:67], v[70:71]
	v_pk_add_f32 v[64:65], v[64:65], v[68:69]
	global_store_dwordx4 v[84:85], v[64:67], off offset:192
	global_load_dwordx4 v[64:67], v[74:75], off
	v_lshl_add_u64 v[68:69], s[70:71], 0, v[72:73]
	v_lshl_add_u64 v[68:69], v[68:69], 0, v[132:133]
	s_waitcnt vmcnt(0)
	v_pk_add_f32 v[62:63], v[62:63], v[66:67]
	v_pk_add_f32 v[60:61], v[60:61], v[64:65]
	global_store_dwordx4 v[68:69], v[60:63], off
	global_load_dwordx4 v[60:63], v[74:75], off offset:64
	s_waitcnt vmcnt(0)
	v_pk_add_f32 v[58:59], v[58:59], v[62:63]
	v_pk_add_f32 v[56:57], v[56:57], v[60:61]
	global_store_dwordx4 v[68:69], v[56:59], off offset:64
	global_load_dwordx4 v[56:59], v[74:75], off offset:128
	s_waitcnt vmcnt(0)
	v_pk_add_f32 v[54:55], v[54:55], v[58:59]
	v_pk_add_f32 v[52:53], v[52:53], v[56:57]
	global_store_dwordx4 v[68:69], v[52:55], off offset:128
	global_load_dwordx4 v[52:55], v[74:75], off offset:192
	v_or_b32_e32 v56, 0xa0000, v130
	v_mov_b32_e32 v57, v131
	v_lshl_add_u64 v[58:59], s[40:41], 0, v[56:57]
	v_lshl_add_u64 v[58:59], v[58:59], 0, v[132:133]
	s_waitcnt vmcnt(0)
	v_pk_add_f32 v[50:51], v[50:51], v[54:55]
	v_pk_add_f32 v[48:49], v[48:49], v[52:53]
	global_store_dwordx4 v[68:69], v[48:51], off offset:192
	global_load_dwordx4 v[48:51], v[58:59], off
	v_lshl_add_u64 v[52:53], s[70:71], 0, v[56:57]
	v_lshl_add_u64 v[52:53], v[52:53], 0, v[132:133]
	s_waitcnt vmcnt(0)
	v_pk_add_f32 v[46:47], v[46:47], v[50:51]
	v_pk_add_f32 v[44:45], v[44:45], v[48:49]
	global_store_dwordx4 v[52:53], v[44:47], off
	global_load_dwordx4 v[44:47], v[58:59], off offset:64
	s_waitcnt vmcnt(0)
	v_pk_add_f32 v[42:43], v[42:43], v[46:47]
	v_pk_add_f32 v[40:41], v[40:41], v[44:45]
	global_store_dwordx4 v[52:53], v[40:43], off offset:64
	global_load_dwordx4 v[40:43], v[58:59], off offset:128
	s_waitcnt vmcnt(0)
	v_pk_add_f32 v[38:39], v[38:39], v[42:43]
	v_pk_add_f32 v[36:37], v[36:37], v[40:41]
	global_store_dwordx4 v[52:53], v[36:39], off offset:128
	global_load_dwordx4 v[36:39], v[58:59], off offset:192
	v_or_b32_e32 v40, 0xc0000, v130
	v_mov_b32_e32 v41, v131
	v_lshl_add_u64 v[42:43], s[40:41], 0, v[40:41]
	v_lshl_add_u64 v[42:43], v[42:43], 0, v[132:133]
	v_or_b32_e32 v130, 0xe0000, v130
	s_waitcnt vmcnt(0)
	v_pk_add_f32 v[30:31], v[30:31], v[38:39]
	v_pk_add_f32 v[28:29], v[28:29], v[36:37]
	global_store_dwordx4 v[52:53], v[28:31], off offset:192
	global_load_dwordx4 v[28:31], v[42:43], off
	v_lshl_add_u64 v[36:37], s[70:71], 0, v[40:41]
	v_lshl_add_u64 v[36:37], v[36:37], 0, v[132:133]
	s_waitcnt vmcnt(0)
	v_pk_add_f32 v[26:27], v[26:27], v[30:31]
	v_pk_add_f32 v[24:25], v[24:25], v[28:29]
	global_store_dwordx4 v[36:37], v[24:27], off
	global_load_dwordx4 v[24:27], v[42:43], off offset:64
	s_waitcnt vmcnt(0)
	v_pk_add_f32 v[22:23], v[22:23], v[26:27]
	v_pk_add_f32 v[20:21], v[20:21], v[24:25]
	global_store_dwordx4 v[36:37], v[20:23], off offset:64
	global_load_dwordx4 v[20:23], v[42:43], off offset:128
	s_waitcnt vmcnt(0)
	v_pk_add_f32 v[18:19], v[18:19], v[22:23]
	v_pk_add_f32 v[16:17], v[16:17], v[20:21]
	global_store_dwordx4 v[36:37], v[16:19], off offset:128
	global_load_dwordx4 v[16:19], v[42:43], off offset:192
	v_lshl_add_u64 v[20:21], s[40:41], 0, v[130:131]
	v_lshl_add_u64 v[20:21], v[20:21], 0, v[132:133]
	s_waitcnt vmcnt(0)
	v_pk_add_f32 v[14:15], v[14:15], v[18:19]
	v_pk_add_f32 v[12:13], v[12:13], v[16:17]
	global_store_dwordx4 v[36:37], v[12:15], off offset:192
	global_load_dwordx4 v[12:15], v[20:21], off
	v_lshl_add_u64 v[16:17], s[70:71], 0, v[130:131]
	v_lshl_add_u64 v[16:17], v[16:17], 0, v[132:133]
	s_waitcnt vmcnt(0)
	v_pk_add_f32 v[10:11], v[10:11], v[14:15]
	v_pk_add_f32 v[8:9], v[8:9], v[12:13]
	global_store_dwordx4 v[16:17], v[8:11], off
	global_load_dwordx4 v[8:11], v[20:21], off offset:64
	s_waitcnt vmcnt(0)
	v_pk_add_f32 v[6:7], v[6:7], v[10:11]
	v_pk_add_f32 v[4:5], v[4:5], v[8:9]
	global_store_dwordx4 v[16:17], v[4:7], off offset:64
	global_load_dwordx4 v[4:7], v[20:21], off offset:128
	s_waitcnt vmcnt(0)
	v_pk_add_f32 v[2:3], v[2:3], v[6:7]
	v_pk_add_f32 v[0:1], v[0:1], v[4:5]
	global_store_dwordx4 v[16:17], v[0:3], off offset:128
	global_load_dwordx4 v[0:3], v[20:21], off offset:192
	s_waitcnt vmcnt(0)
	v_pk_add_f32 v[2:3], v[34:35], v[2:3]
	v_pk_add_f32 v[0:1], v[32:33], v[0:1]
	global_store_dwordx4 v[16:17], v[0:3], off offset:192
	s_cbranch_scc0 .LBB0_502
	s_branch .LBB0_499
